# static priority: one s_setprio 1 for waves 4-7 at kernel entry, every per-phase setprio flip removed
# baseline (speedup 1.0000x reference)
_Z8fwd_mega4Args:
	v_readfirstlane_b32 s3, v0
	s_nop 3
	s_and_b32 s3, s3, 0x3ff
	s_lshr_b32 s3, s3, 6
	s_cmp_ge_u32 s3, 4
	s_cbranch_scc0 .Lprio_done
	s_setprio 1
.Lprio_done:
	s_load_dwordx16 s[4:19], s[0:1], 0x80
	s_load_dwordx4 s[80:83], s[0:1], 0xc0
	s_load_dword s95, s[0:1], 0xd0
	v_and_b32_e32 v219, 0x3ff, v0
	v_cmp_gt_u32_e32 vcc, 4, v219
	v_readfirstlane_b32 s24, v219
	s_waitcnt lgkmcnt(0)
	v_writelane_b32 v249, s4, 0
	s_nop 1
	v_writelane_b32 v249, s5, 1
	v_writelane_b32 v249, s6, 2
	v_writelane_b32 v249, s7, 3
	v_writelane_b32 v249, s8, 4
	v_writelane_b32 v249, s9, 5
	v_writelane_b32 v249, s10, 6
	v_writelane_b32 v249, s11, 7
	v_writelane_b32 v249, s12, 8
	v_writelane_b32 v249, s13, 9
	v_writelane_b32 v249, s14, 10
	v_writelane_b32 v249, s15, 11
	v_writelane_b32 v249, s16, 12
	v_writelane_b32 v249, s17, 13
	v_writelane_b32 v249, s18, 14
	v_writelane_b32 v249, s19, 15
	s_add_u32 s6, s0, 0xc8
	s_addc_u32 s7, s1, 0
	s_and_saveexec_b64 s[4:5], vcc
	v_lshl_add_u32 v1, v219, 2, 0
	v_add_u32_e32 v1, 0x20400, v1
	v_mov_b32_e32 v2, 0
	ds_write_b32 v1, v2
	s_or_b64 exec, exec, s[4:5]
	s_load_dwordx16 s[8:23], s[0:1], 0x80
	s_waitcnt lgkmcnt(0)
	s_barrier
	s_getreg_b32 s3, hwreg(HW_REG_XCC_ID, 0, 4)
	s_add_u32 s70, s22, 0x180000
	s_addc_u32 s71, s23, 0
	s_and_b32 s94, s3, 15
	v_cmp_eq_u32_e64 s[96:97], 0, v219
	s_and_saveexec_b64 s[4:5], s[96:97]
	s_cbranch_execz .LBB0_5
	s_mov_b64 s[8:9], exec
	v_mbcnt_lo_u32_b32 v1, s8, 0
	v_mbcnt_hi_u32_b32 v1, s9, v1
	v_cmp_eq_u32_e32 vcc, 0, v1
	s_and_b64 s[10:11], exec, vcc
	s_mov_b64 exec, s[10:11]
	s_cbranch_execz .LBB0_5
	s_lshl_b32 s3, s94, 8
	s_bcnt1_i32_b64 s8, s[8:9]
	v_mov_b32_e32 v1, s3
	v_mov_b32_e32 v2, s8
	global_atomic_add v1, v2, s[70:71] offset:1024

.LBB0_141:
	s_lshl_b32 s34, s11, 8
	s_ashr_i32 s35, s34, 31
	s_lshl_b64 s[34:35], s[34:35], 11
	s_add_u32 s82, s49, s34
	s_addc_u32 s83, s53, s35
	s_and_b64 s[34:35], s[0:1], exec
	s_cselect_b32 s5, s83, s7
	s_cselect_b32 s22, s82, s6
	s_ashr_i32 s81, s80, 31
	s_lshl_b64 s[34:35], s[80:81], 19
	s_add_u32 s84, s55, s34
	s_addc_u32 s85, s57, s35
	s_and_b64 s[34:35], s[0:1], exec
	s_cselect_b32 s34, s85, s9
	s_cselect_b32 s35, s84, s8
	s_add_u32 s40, s8, 0x100
	s_addc_u32 s41, s9, 0
	s_mov_b32 s50, -2
	s_waitcnt vmcnt(0)
	s_waitcnt lgkmcnt(0)
	ds_read_b128 v[128:131], v175
	ds_read_b128 v[132:135], v175 offset:1024
	ds_read_b128 v[136:139], v175 offset:2048
	ds_read_b128 v[140:143], v175 offset:3072
	ds_read_b128 v[166:169], v176
	ds_read_b128 v[170:173], v176 offset:1024
	ds_read_b128 v[182:185], v176 offset:2048
	ds_read_b128 v[186:189], v176 offset:3072
	s_add_u32 s8, s6, 0x100
	s_addc_u32 s9, s7, 0
	s_cmp_eq_u32 s50, 12
	s_cselect_b32 s89, s5, s9
	s_cselect_b32 s88, s22, s8
	s_cselect_b32 s87, s34, s41
	s_cselect_b32 s86, s35, s40
	v_lshl_add_u64 v[220:221], s[6:7], 0, v[158:159]
	s_add_i32 m0, s61, 0xc000
	ds_read_b128 v[190:193], v177
	ds_read_b128 v[194:197], v177 offset:1024
	ds_read_b128 v[198:201], v177 offset:2048
	ds_read_b128 v[202:205], v177 offset:3072
	ds_read_b128 v[206:209], v177 offset:4096
	ds_read_b128 v[210:213], v177 offset:5120
	ds_read_b128 v[214:217], v177 offset:6144
	ds_read_b128 v[224:227], v177 offset:7168
	global_load_lds_dwordx4 v[220:221], off
	s_add_i32 m0, s61, 0xe000
	v_lshl_add_u64 v[220:221], s[6:7], 0, v[160:161]
	global_load_lds_dwordx4 v[220:221], off
	s_waitcnt vmcnt(8) lgkmcnt(0)
	s_barrier
	v_mfma_f32_16x16x32_bf16 v[124:127], v[128:131], v[190:193], 0
	v_mfma_f32_16x16x32_bf16 v[120:123], v[136:139], v[190:193], 0
	v_mfma_f32_16x16x32_bf16 v[108:111], v[128:131], v[198:201], 0
	v_mfma_f32_16x16x32_bf16 v[104:107], v[136:139], v[198:201], 0
	v_mfma_f32_16x16x32_bf16 v[92:95], v[128:131], v[206:209], 0
	v_mfma_f32_16x16x32_bf16 v[88:91], v[136:139], v[206:209], 0
	v_mfma_f32_16x16x32_bf16 v[76:79], v[128:131], v[214:217], 0
	v_mfma_f32_16x16x32_bf16 v[72:75], v[136:139], v[214:217], 0
	v_mfma_f32_16x16x32_bf16 v[124:127], v[132:135], v[194:197], v[124:127]
	v_mfma_f32_16x16x32_bf16 v[120:123], v[140:143], v[194:197], v[120:123]
	v_mfma_f32_16x16x32_bf16 v[108:111], v[132:135], v[202:205], v[108:111]
	v_mfma_f32_16x16x32_bf16 v[104:107], v[140:143], v[202:205], v[104:107]
	v_mfma_f32_16x16x32_bf16 v[92:95], v[132:135], v[210:213], v[92:95]
	v_mfma_f32_16x16x32_bf16 v[88:91], v[140:143], v[210:213], v[88:91]
	v_mfma_f32_16x16x32_bf16 v[76:79], v[132:135], v[224:227], v[76:79]
	v_mfma_f32_16x16x32_bf16 v[72:75], v[140:143], v[224:227], v[72:75]
	v_mfma_f32_16x16x32_bf16 v[116:119], v[166:169], v[190:193], 0
	v_mfma_f32_16x16x32_bf16 v[112:115], v[182:185], v[190:193], 0
	v_mfma_f32_16x16x32_bf16 v[100:103], v[166:169], v[198:201], 0
	v_mfma_f32_16x16x32_bf16 v[96:99], v[182:185], v[198:201], 0
	v_mfma_f32_16x16x32_bf16 v[84:87], v[166:169], v[206:209], 0
	v_mfma_f32_16x16x32_bf16 v[80:83], v[182:185], v[206:209], 0
	v_mfma_f32_16x16x32_bf16 v[68:71], v[166:169], v[214:217], 0
	v_mfma_f32_16x16x32_bf16 v[64:67], v[182:185], v[214:217], 0
	v_mfma_f32_16x16x32_bf16 v[116:119], v[170:173], v[194:197], v[116:119]
	v_mfma_f32_16x16x32_bf16 v[112:115], v[186:189], v[194:197], v[112:115]
	v_mfma_f32_16x16x32_bf16 v[100:103], v[170:173], v[202:205], v[100:103]
	v_mfma_f32_16x16x32_bf16 v[96:99], v[186:189], v[202:205], v[96:99]
	v_mfma_f32_16x16x32_bf16 v[84:87], v[170:173], v[210:213], v[84:87]
	v_mfma_f32_16x16x32_bf16 v[80:83], v[186:189], v[210:213], v[80:83]
	v_mfma_f32_16x16x32_bf16 v[68:71], v[170:173], v[224:227], v[68:71]
	v_mfma_f32_16x16x32_bf16 v[64:67], v[186:189], v[224:227], v[64:67]
	s_barrier
	s_add_i32 s6, s37, s59
	v_lshl_add_u64 v[220:221], s[86:87], 0, v[148:149]
	s_mov_b32 m0, s6
	ds_read_b128 v[190:193], v177 offset:16384
	ds_read_b128 v[194:197], v177 offset:17408
	ds_read_b128 v[198:201], v177 offset:18432
	ds_read_b128 v[202:205], v177 offset:19456
	ds_read_b128 v[206:209], v177 offset:20480
	ds_read_b128 v[210:213], v177 offset:21504
	ds_read_b128 v[214:217], v177 offset:22528
	ds_read_b128 v[224:227], v177 offset:23552
	global_load_lds_dwordx4 v[220:221], off
	s_add_i32 m0, s6, 0x2000
	s_add_u32 s6, s86, 0x40000
	v_lshl_add_u64 v[228:229], s[86:87], 0, v[152:153]
	s_addc_u32 s7, s87, 0
	s_add_i32 s51, s97, s59
	global_load_lds_dwordx4 v[228:229], off
	v_lshl_add_u64 v[230:231], s[6:7], 0, v[148:149]
	s_mov_b32 m0, s51
	v_lshl_add_u64 v[232:233], s[88:89], 0, v[150:151]
	global_load_lds_dwordx4 v[230:231], off
	v_lshl_add_u64 v[230:231], s[6:7], 0, v[152:153]
	s_add_i32 m0, s51, 0x2000
	v_lshl_add_u64 v[234:235], v[232:233], 0, s[68:69]
	global_load_lds_dwordx4 v[230:231], off
	s_mov_b32 m0, s61
	v_lshl_add_u64 v[230:231], s[88:89], 0, v[146:147]
	global_load_lds_dwordx4 v[230:231], off
	s_mov_b32 m0, s63
	s_nop 0
	global_load_lds_dwordx4 v[234:235], off
	s_waitcnt vmcnt(8) lgkmcnt(0)
	s_barrier
	v_mfma_f32_16x16x32_bf16 v[60:63], v[128:131], v[190:193], 0
	v_mfma_f32_16x16x32_bf16 v[56:59], v[136:139], v[190:193], 0
	v_mfma_f32_16x16x32_bf16 v[44:47], v[128:131], v[198:201], 0
	v_mfma_f32_16x16x32_bf16 v[40:43], v[136:139], v[198:201], 0
	v_mfma_f32_16x16x32_bf16 v[28:31], v[128:131], v[206:209], 0
	v_mfma_f32_16x16x32_bf16 v[24:27], v[136:139], v[206:209], 0
	v_mfma_f32_16x16x32_bf16 v[12:15], v[128:131], v[214:217], 0
	v_mfma_f32_16x16x32_bf16 v[8:11], v[136:139], v[214:217], 0
	v_mfma_f32_16x16x32_bf16 v[60:63], v[132:135], v[194:197], v[60:63]
	v_mfma_f32_16x16x32_bf16 v[56:59], v[140:143], v[194:197], v[56:59]
	v_mfma_f32_16x16x32_bf16 v[44:47], v[132:135], v[202:205], v[44:47]
	v_mfma_f32_16x16x32_bf16 v[40:43], v[140:143], v[202:205], v[40:43]
	v_mfma_f32_16x16x32_bf16 v[28:31], v[132:135], v[210:213], v[28:31]
	v_mfma_f32_16x16x32_bf16 v[24:27], v[140:143], v[210:213], v[24:27]
	v_mfma_f32_16x16x32_bf16 v[12:15], v[132:135], v[224:227], v[12:15]
	v_mfma_f32_16x16x32_bf16 v[8:11], v[140:143], v[224:227], v[8:11]
	v_mfma_f32_16x16x32_bf16 v[52:55], v[166:169], v[190:193], 0
	v_mfma_f32_16x16x32_bf16 v[48:51], v[182:185], v[190:193], 0
	v_mfma_f32_16x16x32_bf16 v[36:39], v[166:169], v[198:201], 0
	v_mfma_f32_16x16x32_bf16 v[32:35], v[182:185], v[198:201], 0
	v_mfma_f32_16x16x32_bf16 v[20:23], v[166:169], v[206:209], 0
	v_mfma_f32_16x16x32_bf16 v[16:19], v[182:185], v[206:209], 0
	v_mfma_f32_16x16x32_bf16 v[4:7], v[166:169], v[214:217], 0
	v_mfma_f32_16x16x32_bf16 v[0:3], v[182:185], v[214:217], 0
	v_mfma_f32_16x16x32_bf16 v[52:55], v[170:173], v[194:197], v[52:55]
	v_mfma_f32_16x16x32_bf16 v[48:51], v[186:189], v[194:197], v[48:51]
	v_mfma_f32_16x16x32_bf16 v[36:39], v[170:173], v[202:205], v[36:39]
	v_mfma_f32_16x16x32_bf16 v[32:35], v[186:189], v[202:205], v[32:35]
	v_mfma_f32_16x16x32_bf16 v[20:23], v[170:173], v[210:213], v[20:23]
	v_mfma_f32_16x16x32_bf16 v[16:19], v[186:189], v[210:213], v[16:19]
	v_mfma_f32_16x16x32_bf16 v[4:7], v[170:173], v[224:227], v[4:7]
	v_mfma_f32_16x16x32_bf16 v[0:3], v[186:189], v[224:227], v[0:3]
	s_barrier
	s_add_i32 s6, 0, 0x18000
	s_add_i32 s51, 0, 0x1c000
	v_add_u32_e32 v140, s6, v174
	v_add_u32_e32 v154, s51, v174
	ds_read_b128 v[128:131], v140
	ds_read_b128 v[132:135], v140 offset:1024
	ds_read_b128 v[136:139], v140 offset:2048
	ds_read_b128 v[140:143], v140 offset:3072
	ds_read_b128 v[166:169], v154
	ds_read_b128 v[170:173], v154 offset:1024
	ds_read_b128 v[182:185], v154 offset:2048
	ds_read_b128 v[186:189], v154 offset:3072
	s_mov_b32 m0, s65
	v_lshl_add_u64 v[234:235], v[230:231], 0, s[66:67]
	ds_read_b128 v[190:193], v177 offset:32768
	ds_read_b128 v[194:197], v177 offset:33792
	ds_read_b128 v[198:201], v177 offset:34816
	ds_read_b128 v[202:205], v177 offset:35840
	ds_read_b128 v[206:209], v177 offset:36864
	ds_read_b128 v[210:213], v177 offset:37888
	ds_read_b128 v[214:217], v177 offset:38912
	ds_read_b128 v[224:227], v177 offset:39936
	global_load_lds_dwordx4 v[234:235], off
	s_mov_b32 m0, s77
	v_lshl_add_u64 v[234:235], v[232:233], 0, s[46:47]
	global_load_lds_dwordx4 v[234:235], off
	s_waitcnt vmcnt(8) lgkmcnt(0)
	s_barrier
	v_mfma_f32_16x16x32_bf16 v[124:127], v[128:131], v[190:193], v[124:127]
	v_mfma_f32_16x16x32_bf16 v[120:123], v[136:139], v[190:193], v[120:123]
	v_mfma_f32_16x16x32_bf16 v[108:111], v[128:131], v[198:201], v[108:111]
	v_mfma_f32_16x16x32_bf16 v[104:107], v[136:139], v[198:201], v[104:107]
	v_mfma_f32_16x16x32_bf16 v[92:95], v[128:131], v[206:209], v[92:95]
	v_mfma_f32_16x16x32_bf16 v[88:91], v[136:139], v[206:209], v[88:91]
	v_mfma_f32_16x16x32_bf16 v[76:79], v[128:131], v[214:217], v[76:79]
	v_mfma_f32_16x16x32_bf16 v[72:75], v[136:139], v[214:217], v[72:75]
	v_mfma_f32_16x16x32_bf16 v[124:127], v[132:135], v[194:197], v[124:127]
	v_mfma_f32_16x16x32_bf16 v[120:123], v[140:143], v[194:197], v[120:123]
	v_mfma_f32_16x16x32_bf16 v[108:111], v[132:135], v[202:205], v[108:111]
	v_mfma_f32_16x16x32_bf16 v[104:107], v[140:143], v[202:205], v[104:107]
	v_mfma_f32_16x16x32_bf16 v[92:95], v[132:135], v[210:213], v[92:95]
	v_mfma_f32_16x16x32_bf16 v[88:91], v[140:143], v[210:213], v[88:91]
	v_mfma_f32_16x16x32_bf16 v[76:79], v[132:135], v[224:227], v[76:79]
	v_mfma_f32_16x16x32_bf16 v[72:75], v[140:143], v[224:227], v[72:75]
	v_mfma_f32_16x16x32_bf16 v[116:119], v[166:169], v[190:193], v[116:119]
	v_mfma_f32_16x16x32_bf16 v[112:115], v[182:185], v[190:193], v[112:115]
	v_mfma_f32_16x16x32_bf16 v[100:103], v[166:169], v[198:201], v[100:103]
	v_mfma_f32_16x16x32_bf16 v[96:99], v[182:185], v[198:201], v[96:99]
	v_mfma_f32_16x16x32_bf16 v[84:87], v[166:169], v[206:209], v[84:87]
	v_mfma_f32_16x16x32_bf16 v[80:83], v[182:185], v[206:209], v[80:83]
	v_mfma_f32_16x16x32_bf16 v[68:71], v[166:169], v[214:217], v[68:71]
	v_mfma_f32_16x16x32_bf16 v[64:67], v[182:185], v[214:217], v[64:67]
	v_mfma_f32_16x16x32_bf16 v[116:119], v[170:173], v[194:197], v[116:119]
	v_mfma_f32_16x16x32_bf16 v[112:115], v[186:189], v[194:197], v[112:115]
	v_mfma_f32_16x16x32_bf16 v[100:103], v[170:173], v[202:205], v[100:103]
	v_mfma_f32_16x16x32_bf16 v[96:99], v[186:189], v[202:205], v[96:99]
	v_mfma_f32_16x16x32_bf16 v[84:87], v[170:173], v[210:213], v[84:87]
	v_mfma_f32_16x16x32_bf16 v[80:83], v[186:189], v[210:213], v[80:83]
	v_mfma_f32_16x16x32_bf16 v[68:71], v[170:173], v[224:227], v[68:71]
	v_mfma_f32_16x16x32_bf16 v[64:67], v[186:189], v[224:227], v[64:67]
	s_barrier
	s_add_i32 s6, s6, s59
	v_lshl_add_u64 v[220:221], v[220:221], 0, s[42:43]
	s_mov_b32 m0, s6
	ds_read_b128 v[190:193], v177 offset:49152
	ds_read_b128 v[194:197], v177 offset:50176
	ds_read_b128 v[198:201], v177 offset:51200
	ds_read_b128 v[202:205], v177 offset:52224
	ds_read_b128 v[206:209], v177 offset:53248
	ds_read_b128 v[210:213], v177 offset:54272
	ds_read_b128 v[214:217], v177 offset:55296
	ds_read_b128 v[224:227], v177 offset:56320
	global_load_lds_dwordx4 v[220:221], off
	s_add_i32 m0, s6, 0x2000
	s_add_u32 s6, s86, 0x40080
	v_lshl_add_u64 v[220:221], v[228:229], 0, s[42:43]
	s_addc_u32 s7, s87, 0
	s_add_i32 s51, s51, s59
	global_load_lds_dwordx4 v[220:221], off
	s_mov_b32 m0, s51
	v_lshl_add_u64 v[220:221], s[6:7], 0, v[148:149]
	global_load_lds_dwordx4 v[220:221], off
	s_add_i32 m0, s51, 0x2000
	v_lshl_add_u64 v[220:221], s[6:7], 0, v[152:153]
	global_load_lds_dwordx4 v[220:221], off
	s_mov_b32 m0, s91
	v_lshl_add_u64 v[220:221], v[230:231], 0, s[42:43]
	global_load_lds_dwordx4 v[220:221], off
	s_mov_b32 m0, s92
	v_lshl_add_u64 v[220:221], v[232:233], 0, s[44:45]
	global_load_lds_dwordx4 v[220:221], off
	s_waitcnt vmcnt(8) lgkmcnt(0)
	s_barrier
	v_mfma_f32_16x16x32_bf16 v[60:63], v[128:131], v[190:193], v[60:63]
	v_mfma_f32_16x16x32_bf16 v[56:59], v[136:139], v[190:193], v[56:59]
	v_mfma_f32_16x16x32_bf16 v[44:47], v[128:131], v[198:201], v[44:47]
	v_mfma_f32_16x16x32_bf16 v[40:43], v[136:139], v[198:201], v[40:43]
	v_mfma_f32_16x16x32_bf16 v[28:31], v[128:131], v[206:209], v[28:31]
	v_mfma_f32_16x16x32_bf16 v[24:27], v[136:139], v[206:209], v[24:27]
	v_mfma_f32_16x16x32_bf16 v[12:15], v[128:131], v[214:217], v[12:15]
	v_mfma_f32_16x16x32_bf16 v[8:11], v[136:139], v[214:217], v[8:11]
	v_mfma_f32_16x16x32_bf16 v[60:63], v[132:135], v[194:197], v[60:63]
	v_mfma_f32_16x16x32_bf16 v[56:59], v[140:143], v[194:197], v[56:59]
	v_mfma_f32_16x16x32_bf16 v[44:47], v[132:135], v[202:205], v[44:47]
	v_mfma_f32_16x16x32_bf16 v[40:43], v[140:143], v[202:205], v[40:43]
	v_mfma_f32_16x16x32_bf16 v[28:31], v[132:135], v[210:213], v[28:31]
	v_mfma_f32_16x16x32_bf16 v[24:27], v[140:143], v[210:213], v[24:27]
	v_mfma_f32_16x16x32_bf16 v[12:15], v[132:135], v[224:227], v[12:15]
	v_mfma_f32_16x16x32_bf16 v[8:11], v[140:143], v[224:227], v[8:11]
	v_mfma_f32_16x16x32_bf16 v[52:55], v[166:169], v[190:193], v[52:55]
	v_mfma_f32_16x16x32_bf16 v[48:51], v[182:185], v[190:193], v[48:51]
	v_mfma_f32_16x16x32_bf16 v[36:39], v[166:169], v[198:201], v[36:39]
	v_mfma_f32_16x16x32_bf16 v[32:35], v[182:185], v[198:201], v[32:35]
	v_mfma_f32_16x16x32_bf16 v[20:23], v[166:169], v[206:209], v[20:23]
	v_mfma_f32_16x16x32_bf16 v[16:19], v[182:185], v[206:209], v[16:19]
	v_mfma_f32_16x16x32_bf16 v[4:7], v[166:169], v[214:217], v[4:7]
	v_mfma_f32_16x16x32_bf16 v[0:3], v[182:185], v[214:217], v[0:3]
	v_mfma_f32_16x16x32_bf16 v[52:55], v[170:173], v[194:197], v[52:55]
	v_mfma_f32_16x16x32_bf16 v[48:51], v[186:189], v[194:197], v[48:51]
	v_mfma_f32_16x16x32_bf16 v[36:39], v[170:173], v[202:205], v[36:39]
	v_mfma_f32_16x16x32_bf16 v[32:35], v[186:189], v[202:205], v[32:35]
	v_mfma_f32_16x16x32_bf16 v[20:23], v[170:173], v[210:213], v[20:23]
	v_mfma_f32_16x16x32_bf16 v[16:19], v[186:189], v[210:213], v[16:19]
	v_mfma_f32_16x16x32_bf16 v[4:7], v[170:173], v[224:227], v[4:7]
	v_mfma_f32_16x16x32_bf16 v[0:3], v[186:189], v[224:227], v[0:3]
	s_barrier
	s_add_i32 s50, s50, 2
	s_add_u32 s40, s40, 0x100
	s_addc_u32 s41, s41, 0
	s_cmp_gt_u32 s50, 13
	s_mov_b64 s[6:7], s[8:9]
.LBB0_142:
	ds_read_b128 v[128:131], v175
	ds_read_b128 v[132:135], v175 offset:1024
	ds_read_b128 v[136:139], v175 offset:2048
	ds_read_b128 v[140:143], v175 offset:3072
	ds_read_b128 v[166:169], v176
	ds_read_b128 v[170:173], v176 offset:1024
	ds_read_b128 v[182:185], v176 offset:2048
	ds_read_b128 v[186:189], v176 offset:3072
	s_add_u32 s8, s6, 0x100
	s_addc_u32 s9, s7, 0
	s_cmp_eq_u32 s50, 12
	s_cselect_b32 s89, s5, s9
	s_cselect_b32 s88, s22, s8
	s_cselect_b32 s87, s34, s41
	s_cselect_b32 s86, s35, s40
	v_lshl_add_u64 v[220:221], s[6:7], 0, v[158:159]
	s_add_i32 m0, s61, 0xc000
	ds_read_b128 v[190:193], v177
	ds_read_b128 v[194:197], v177 offset:1024
	ds_read_b128 v[198:201], v177 offset:2048
	ds_read_b128 v[202:205], v177 offset:3072
	ds_read_b128 v[206:209], v177 offset:4096
	ds_read_b128 v[210:213], v177 offset:5120
	ds_read_b128 v[214:217], v177 offset:6144
	ds_read_b128 v[224:227], v177 offset:7168
	global_load_lds_dwordx4 v[220:221], off
	s_add_i32 m0, s61, 0xe000
	v_lshl_add_u64 v[220:221], s[6:7], 0, v[160:161]
	global_load_lds_dwordx4 v[220:221], off
	s_waitcnt vmcnt(8) lgkmcnt(0)
	s_barrier
	v_mfma_f32_16x16x32_bf16 v[124:127], v[128:131], v[190:193], v[124:127]
	v_mfma_f32_16x16x32_bf16 v[120:123], v[136:139], v[190:193], v[120:123]
	v_mfma_f32_16x16x32_bf16 v[108:111], v[128:131], v[198:201], v[108:111]
	v_mfma_f32_16x16x32_bf16 v[104:107], v[136:139], v[198:201], v[104:107]
	v_mfma_f32_16x16x32_bf16 v[92:95], v[128:131], v[206:209], v[92:95]
	v_mfma_f32_16x16x32_bf16 v[88:91], v[136:139], v[206:209], v[88:91]
	v_mfma_f32_16x16x32_bf16 v[76:79], v[128:131], v[214:217], v[76:79]
	v_mfma_f32_16x16x32_bf16 v[72:75], v[136:139], v[214:217], v[72:75]
	v_mfma_f32_16x16x32_bf16 v[124:127], v[132:135], v[194:197], v[124:127]
	v_mfma_f32_16x16x32_bf16 v[120:123], v[140:143], v[194:197], v[120:123]
	v_mfma_f32_16x16x32_bf16 v[108:111], v[132:135], v[202:205], v[108:111]
	v_mfma_f32_16x16x32_bf16 v[104:107], v[140:143], v[202:205], v[104:107]
	v_mfma_f32_16x16x32_bf16 v[92:95], v[132:135], v[210:213], v[92:95]
	v_mfma_f32_16x16x32_bf16 v[88:91], v[140:143], v[210:213], v[88:91]
	v_mfma_f32_16x16x32_bf16 v[76:79], v[132:135], v[224:227], v[76:79]
	v_mfma_f32_16x16x32_bf16 v[72:75], v[140:143], v[224:227], v[72:75]
	v_mfma_f32_16x16x32_bf16 v[116:119], v[166:169], v[190:193], v[116:119]
	v_mfma_f32_16x16x32_bf16 v[112:115], v[182:185], v[190:193], v[112:115]
	v_mfma_f32_16x16x32_bf16 v[100:103], v[166:169], v[198:201], v[100:103]
	v_mfma_f32_16x16x32_bf16 v[96:99], v[182:185], v[198:201], v[96:99]
	v_mfma_f32_16x16x32_bf16 v[84:87], v[166:169], v[206:209], v[84:87]
	v_mfma_f32_16x16x32_bf16 v[80:83], v[182:185], v[206:209], v[80:83]
	v_mfma_f32_16x16x32_bf16 v[68:71], v[166:169], v[214:217], v[68:71]
	v_mfma_f32_16x16x32_bf16 v[64:67], v[182:185], v[214:217], v[64:67]
	v_mfma_f32_16x16x32_bf16 v[116:119], v[170:173], v[194:197], v[116:119]
	v_mfma_f32_16x16x32_bf16 v[112:115], v[186:189], v[194:197], v[112:115]
	v_mfma_f32_16x16x32_bf16 v[100:103], v[170:173], v[202:205], v[100:103]
	v_mfma_f32_16x16x32_bf16 v[96:99], v[186:189], v[202:205], v[96:99]
	v_mfma_f32_16x16x32_bf16 v[84:87], v[170:173], v[210:213], v[84:87]
	v_mfma_f32_16x16x32_bf16 v[80:83], v[186:189], v[210:213], v[80:83]
	v_mfma_f32_16x16x32_bf16 v[68:71], v[170:173], v[224:227], v[68:71]
	v_mfma_f32_16x16x32_bf16 v[64:67], v[186:189], v[224:227], v[64:67]
	s_barrier
	s_add_i32 s6, s37, s59
	v_lshl_add_u64 v[220:221], s[86:87], 0, v[148:149]
	s_mov_b32 m0, s6
	ds_read_b128 v[190:193], v177 offset:16384
	ds_read_b128 v[194:197], v177 offset:17408
	ds_read_b128 v[198:201], v177 offset:18432
	ds_read_b128 v[202:205], v177 offset:19456
	ds_read_b128 v[206:209], v177 offset:20480
	ds_read_b128 v[210:213], v177 offset:21504
	ds_read_b128 v[214:217], v177 offset:22528
	ds_read_b128 v[224:227], v177 offset:23552
	global_load_lds_dwordx4 v[220:221], off
	s_add_i32 m0, s6, 0x2000
	s_add_u32 s6, s86, 0x40000
	v_lshl_add_u64 v[228:229], s[86:87], 0, v[152:153]
	s_addc_u32 s7, s87, 0
	s_add_i32 s51, s97, s59
	global_load_lds_dwordx4 v[228:229], off
	v_lshl_add_u64 v[230:231], s[6:7], 0, v[148:149]
	s_mov_b32 m0, s51
	v_lshl_add_u64 v[232:233], s[88:89], 0, v[150:151]
	global_load_lds_dwordx4 v[230:231], off
	v_lshl_add_u64 v[230:231], s[6:7], 0, v[152:153]
	s_add_i32 m0, s51, 0x2000
	v_lshl_add_u64 v[234:235], v[232:233], 0, s[68:69]
	global_load_lds_dwordx4 v[230:231], off
	s_mov_b32 m0, s61
	v_lshl_add_u64 v[230:231], s[88:89], 0, v[146:147]
	global_load_lds_dwordx4 v[230:231], off
	s_mov_b32 m0, s63
	s_nop 0
	global_load_lds_dwordx4 v[234:235], off
	s_waitcnt vmcnt(8) lgkmcnt(0)
	s_barrier
	v_mfma_f32_16x16x32_bf16 v[60:63], v[128:131], v[190:193], v[60:63]
	v_mfma_f32_16x16x32_bf16 v[56:59], v[136:139], v[190:193], v[56:59]
	v_mfma_f32_16x16x32_bf16 v[44:47], v[128:131], v[198:201], v[44:47]
	v_mfma_f32_16x16x32_bf16 v[40:43], v[136:139], v[198:201], v[40:43]
	v_mfma_f32_16x16x32_bf16 v[28:31], v[128:131], v[206:209], v[28:31]
	v_mfma_f32_16x16x32_bf16 v[24:27], v[136:139], v[206:209], v[24:27]
	v_mfma_f32_16x16x32_bf16 v[12:15], v[128:131], v[214:217], v[12:15]
	v_mfma_f32_16x16x32_bf16 v[8:11], v[136:139], v[214:217], v[8:11]
	v_mfma_f32_16x16x32_bf16 v[60:63], v[132:135], v[194:197], v[60:63]
	v_mfma_f32_16x16x32_bf16 v[56:59], v[140:143], v[194:197], v[56:59]
	v_mfma_f32_16x16x32_bf16 v[44:47], v[132:135], v[202:205], v[44:47]
	v_mfma_f32_16x16x32_bf16 v[40:43], v[140:143], v[202:205], v[40:43]
	v_mfma_f32_16x16x32_bf16 v[28:31], v[132:135], v[210:213], v[28:31]
	v_mfma_f32_16x16x32_bf16 v[24:27], v[140:143], v[210:213], v[24:27]
	v_mfma_f32_16x16x32_bf16 v[12:15], v[132:135], v[224:227], v[12:15]
	v_mfma_f32_16x16x32_bf16 v[8:11], v[140:143], v[224:227], v[8:11]
	v_mfma_f32_16x16x32_bf16 v[52:55], v[166:169], v[190:193], v[52:55]
	v_mfma_f32_16x16x32_bf16 v[48:51], v[182:185], v[190:193], v[48:51]
	v_mfma_f32_16x16x32_bf16 v[36:39], v[166:169], v[198:201], v[36:39]
	v_mfma_f32_16x16x32_bf16 v[32:35], v[182:185], v[198:201], v[32:35]
	v_mfma_f32_16x16x32_bf16 v[20:23], v[166:169], v[206:209], v[20:23]
	v_mfma_f32_16x16x32_bf16 v[16:19], v[182:185], v[206:209], v[16:19]
	v_mfma_f32_16x16x32_bf16 v[4:7], v[166:169], v[214:217], v[4:7]
	v_mfma_f32_16x16x32_bf16 v[0:3], v[182:185], v[214:217], v[0:3]
	v_mfma_f32_16x16x32_bf16 v[52:55], v[170:173], v[194:197], v[52:55]
	v_mfma_f32_16x16x32_bf16 v[48:51], v[186:189], v[194:197], v[48:51]
	v_mfma_f32_16x16x32_bf16 v[36:39], v[170:173], v[202:205], v[36:39]
	v_mfma_f32_16x16x32_bf16 v[32:35], v[186:189], v[202:205], v[32:35]
	v_mfma_f32_16x16x32_bf16 v[20:23], v[170:173], v[210:213], v[20:23]
	v_mfma_f32_16x16x32_bf16 v[16:19], v[186:189], v[210:213], v[16:19]
	v_mfma_f32_16x16x32_bf16 v[4:7], v[170:173], v[224:227], v[4:7]
	v_mfma_f32_16x16x32_bf16 v[0:3], v[186:189], v[224:227], v[0:3]
	s_barrier
	s_add_i32 s6, 0, 0x18000
	s_add_i32 s51, 0, 0x1c000
	v_add_u32_e32 v140, s6, v174
	v_add_u32_e32 v154, s51, v174
	ds_read_b128 v[128:131], v140
	ds_read_b128 v[132:135], v140 offset:1024
	ds_read_b128 v[136:139], v140 offset:2048
	ds_read_b128 v[140:143], v140 offset:3072
	ds_read_b128 v[166:169], v154
	ds_read_b128 v[170:173], v154 offset:1024
	ds_read_b128 v[182:185], v154 offset:2048
	ds_read_b128 v[186:189], v154 offset:3072
	s_mov_b32 m0, s65
	v_lshl_add_u64 v[234:235], v[230:231], 0, s[66:67]
	ds_read_b128 v[190:193], v177 offset:32768
	ds_read_b128 v[194:197], v177 offset:33792
	ds_read_b128 v[198:201], v177 offset:34816
	ds_read_b128 v[202:205], v177 offset:35840
	ds_read_b128 v[206:209], v177 offset:36864
	ds_read_b128 v[210:213], v177 offset:37888
	ds_read_b128 v[214:217], v177 offset:38912
	ds_read_b128 v[224:227], v177 offset:39936
	global_load_lds_dwordx4 v[234:235], off
	s_mov_b32 m0, s77
	v_lshl_add_u64 v[234:235], v[232:233], 0, s[46:47]
	global_load_lds_dwordx4 v[234:235], off
	s_waitcnt vmcnt(8) lgkmcnt(0)
	s_barrier
	v_mfma_f32_16x16x32_bf16 v[124:127], v[128:131], v[190:193], v[124:127]
	v_mfma_f32_16x16x32_bf16 v[120:123], v[136:139], v[190:193], v[120:123]
	v_mfma_f32_16x16x32_bf16 v[108:111], v[128:131], v[198:201], v[108:111]
	v_mfma_f32_16x16x32_bf16 v[104:107], v[136:139], v[198:201], v[104:107]
	v_mfma_f32_16x16x32_bf16 v[92:95], v[128:131], v[206:209], v[92:95]
	v_mfma_f32_16x16x32_bf16 v[88:91], v[136:139], v[206:209], v[88:91]
	v_mfma_f32_16x16x32_bf16 v[76:79], v[128:131], v[214:217], v[76:79]
	v_mfma_f32_16x16x32_bf16 v[72:75], v[136:139], v[214:217], v[72:75]
	v_mfma_f32_16x16x32_bf16 v[124:127], v[132:135], v[194:197], v[124:127]
	v_mfma_f32_16x16x32_bf16 v[120:123], v[140:143], v[194:197], v[120:123]
	v_mfma_f32_16x16x32_bf16 v[108:111], v[132:135], v[202:205], v[108:111]
	v_mfma_f32_16x16x32_bf16 v[104:107], v[140:143], v[202:205], v[104:107]
	v_mfma_f32_16x16x32_bf16 v[92:95], v[132:135], v[210:213], v[92:95]
	v_mfma_f32_16x16x32_bf16 v[88:91], v[140:143], v[210:213], v[88:91]
	v_mfma_f32_16x16x32_bf16 v[76:79], v[132:135], v[224:227], v[76:79]
	v_mfma_f32_16x16x32_bf16 v[72:75], v[140:143], v[224:227], v[72:75]
	v_mfma_f32_16x16x32_bf16 v[116:119], v[166:169], v[190:193], v[116:119]
	v_mfma_f32_16x16x32_bf16 v[112:115], v[182:185], v[190:193], v[112:115]
	v_mfma_f32_16x16x32_bf16 v[100:103], v[166:169], v[198:201], v[100:103]
	v_mfma_f32_16x16x32_bf16 v[96:99], v[182:185], v[198:201], v[96:99]
	v_mfma_f32_16x16x32_bf16 v[84:87], v[166:169], v[206:209], v[84:87]
	v_mfma_f32_16x16x32_bf16 v[80:83], v[182:185], v[206:209], v[80:83]
	v_mfma_f32_16x16x32_bf16 v[68:71], v[166:169], v[214:217], v[68:71]
	v_mfma_f32_16x16x32_bf16 v[64:67], v[182:185], v[214:217], v[64:67]
	v_mfma_f32_16x16x32_bf16 v[116:119], v[170:173], v[194:197], v[116:119]
	v_mfma_f32_16x16x32_bf16 v[112:115], v[186:189], v[194:197], v[112:115]
	v_mfma_f32_16x16x32_bf16 v[100:103], v[170:173], v[202:205], v[100:103]
	v_mfma_f32_16x16x32_bf16 v[96:99], v[186:189], v[202:205], v[96:99]
	v_mfma_f32_16x16x32_bf16 v[84:87], v[170:173], v[210:213], v[84:87]
	v_mfma_f32_16x16x32_bf16 v[80:83], v[186:189], v[210:213], v[80:83]
	v_mfma_f32_16x16x32_bf16 v[68:71], v[170:173], v[224:227], v[68:71]
	v_mfma_f32_16x16x32_bf16 v[64:67], v[186:189], v[224:227], v[64:67]
	s_barrier
	s_add_i32 s6, s6, s59
	v_lshl_add_u64 v[220:221], v[220:221], 0, s[42:43]
	s_mov_b32 m0, s6
	ds_read_b128 v[190:193], v177 offset:49152
	ds_read_b128 v[194:197], v177 offset:50176
	ds_read_b128 v[198:201], v177 offset:51200
	ds_read_b128 v[202:205], v177 offset:52224
	ds_read_b128 v[206:209], v177 offset:53248
	ds_read_b128 v[210:213], v177 offset:54272
	ds_read_b128 v[214:217], v177 offset:55296
	ds_read_b128 v[224:227], v177 offset:56320
	global_load_lds_dwordx4 v[220:221], off
	s_add_i32 m0, s6, 0x2000
	s_add_u32 s6, s86, 0x40080
	v_lshl_add_u64 v[220:221], v[228:229], 0, s[42:43]
	s_addc_u32 s7, s87, 0
	s_add_i32 s51, s51, s59
	global_load_lds_dwordx4 v[220:221], off
	s_mov_b32 m0, s51
	v_lshl_add_u64 v[220:221], s[6:7], 0, v[148:149]
	global_load_lds_dwordx4 v[220:221], off
	s_add_i32 m0, s51, 0x2000
	v_lshl_add_u64 v[220:221], s[6:7], 0, v[152:153]
	global_load_lds_dwordx4 v[220:221], off
	s_mov_b32 m0, s91
	v_lshl_add_u64 v[220:221], v[230:231], 0, s[42:43]
	global_load_lds_dwordx4 v[220:221], off
	s_mov_b32 m0, s92
	v_lshl_add_u64 v[220:221], v[232:233], 0, s[44:45]
	global_load_lds_dwordx4 v[220:221], off
	s_waitcnt vmcnt(8) lgkmcnt(0)
	s_barrier
	v_mfma_f32_16x16x32_bf16 v[60:63], v[128:131], v[190:193], v[60:63]
	v_mfma_f32_16x16x32_bf16 v[56:59], v[136:139], v[190:193], v[56:59]
	v_mfma_f32_16x16x32_bf16 v[44:47], v[128:131], v[198:201], v[44:47]
	v_mfma_f32_16x16x32_bf16 v[40:43], v[136:139], v[198:201], v[40:43]
	v_mfma_f32_16x16x32_bf16 v[28:31], v[128:131], v[206:209], v[28:31]
	v_mfma_f32_16x16x32_bf16 v[24:27], v[136:139], v[206:209], v[24:27]
	v_mfma_f32_16x16x32_bf16 v[12:15], v[128:131], v[214:217], v[12:15]
	v_mfma_f32_16x16x32_bf16 v[8:11], v[136:139], v[214:217], v[8:11]
	v_mfma_f32_16x16x32_bf16 v[60:63], v[132:135], v[194:197], v[60:63]
	v_mfma_f32_16x16x32_bf16 v[56:59], v[140:143], v[194:197], v[56:59]
	v_mfma_f32_16x16x32_bf16 v[44:47], v[132:135], v[202:205], v[44:47]
	v_mfma_f32_16x16x32_bf16 v[40:43], v[140:143], v[202:205], v[40:43]
	v_mfma_f32_16x16x32_bf16 v[28:31], v[132:135], v[210:213], v[28:31]
	v_mfma_f32_16x16x32_bf16 v[24:27], v[140:143], v[210:213], v[24:27]
	v_mfma_f32_16x16x32_bf16 v[12:15], v[132:135], v[224:227], v[12:15]
	v_mfma_f32_16x16x32_bf16 v[8:11], v[140:143], v[224:227], v[8:11]
	v_mfma_f32_16x16x32_bf16 v[52:55], v[166:169], v[190:193], v[52:55]
	v_mfma_f32_16x16x32_bf16 v[48:51], v[182:185], v[190:193], v[48:51]
	v_mfma_f32_16x16x32_bf16 v[36:39], v[166:169], v[198:201], v[36:39]
	v_mfma_f32_16x16x32_bf16 v[32:35], v[182:185], v[198:201], v[32:35]
	v_mfma_f32_16x16x32_bf16 v[20:23], v[166:169], v[206:209], v[20:23]
	v_mfma_f32_16x16x32_bf16 v[16:19], v[182:185], v[206:209], v[16:19]
	v_mfma_f32_16x16x32_bf16 v[4:7], v[166:169], v[214:217], v[4:7]
	v_mfma_f32_16x16x32_bf16 v[0:3], v[182:185], v[214:217], v[0:3]
	v_mfma_f32_16x16x32_bf16 v[52:55], v[170:173], v[194:197], v[52:55]
	v_mfma_f32_16x16x32_bf16 v[48:51], v[186:189], v[194:197], v[48:51]
	v_mfma_f32_16x16x32_bf16 v[36:39], v[170:173], v[202:205], v[36:39]
	v_mfma_f32_16x16x32_bf16 v[32:35], v[186:189], v[202:205], v[32:35]
	v_mfma_f32_16x16x32_bf16 v[20:23], v[170:173], v[210:213], v[20:23]
	v_mfma_f32_16x16x32_bf16 v[16:19], v[186:189], v[210:213], v[16:19]
	v_mfma_f32_16x16x32_bf16 v[4:7], v[170:173], v[224:227], v[4:7]
	v_mfma_f32_16x16x32_bf16 v[0:3], v[186:189], v[224:227], v[0:3]
	s_barrier
	s_add_i32 s50, s50, 2
	s_add_u32 s40, s40, 0x100
	s_addc_u32 s41, s41, 0
	s_cmp_gt_u32 s50, 13
	s_mov_b64 s[6:7], s[8:9]
	s_cbranch_scc0 .LBB0_142
	v_readlane_b32 s6, v249, 60
	v_readlane_b32 s7, v249, 61
	s_and_b64 vcc, exec, s[6:7]
	s_cbranch_vccz .LBB0_145
	s_barrier

.LBB0_392:
	s_lshl_b32 s40, s65, 8
	v_readlane_b32 s72, v249, 0
	s_ashr_i32 s41, s40, 31
	v_readlane_b32 s84, v249, 12
	v_readlane_b32 s85, v249, 13
	s_lshl_b64 s[40:41], s[40:41], 10
	v_readlane_b32 s86, v249, 14
	v_readlane_b32 s87, v249, 15
	s_mov_b64 s[28:29], s[84:85]
	s_add_u32 s40, s28, s40
	s_addc_u32 s41, s29, s41
	s_and_b64 s[42:43], s[0:1], exec
	s_cselect_b32 s67, s41, s45
	s_cselect_b32 s72, s40, s44
	s_ashr_i32 s39, s38, 31
	s_lshl_b64 s[42:43], s[38:39], 18
	s_add_u32 s42, s10, s42
	s_addc_u32 s43, s11, s43
	s_and_b64 s[48:49], s[0:1], exec
	v_readlane_b32 s73, v249, 1
	v_readlane_b32 s74, v249, 2
	s_cselect_b32 s39, s43, s47
	s_cselect_b32 s50, s42, s46
	s_add_u32 s51, s46, 0x100
	s_addc_u32 s73, s47, 0
	s_mov_b32 s74, -2
	s_waitcnt vmcnt(0)
	s_waitcnt lgkmcnt(0)
	v_readlane_b32 s75, v249, 3
	v_readlane_b32 s76, v249, 4
	v_readlane_b32 s77, v249, 5
	v_readlane_b32 s78, v249, 6
	v_readlane_b32 s79, v249, 7
	v_readlane_b32 s80, v249, 8
	v_readlane_b32 s81, v249, 9
	v_readlane_b32 s82, v249, 10
	v_readlane_b32 s83, v249, 11
	s_mov_b64 s[30:31], s[86:87]
	ds_read_b128 v[144:147], v153
	ds_read_b128 v[156:159], v153 offset:1024
	ds_read_b128 v[160:163], v153 offset:2048
	ds_read_b128 v[164:167], v153 offset:3072
	ds_read_b128 v[168:171], v154
	ds_read_b128 v[172:175], v154 offset:1024
	ds_read_b128 v[176:179], v154 offset:2048
	ds_read_b128 v[180:183], v154 offset:3072
	s_add_u32 s46, s44, 0x100
	s_addc_u32 s47, s45, 0
	s_cmp_eq_u32 s74, 4
	s_cselect_b32 s77, s67, s47
	s_cselect_b32 s76, s72, s46
	s_cselect_b32 s49, s39, s73
	s_cselect_b32 s48, s50, s51
	v_lshl_add_u64 v[148:149], s[44:45], 0, v[136:137]
	s_add_i32 m0, s52, 0xc000
	ds_read_b128 v[184:187], v155
	ds_read_b128 v[188:191], v155 offset:1024
	ds_read_b128 v[192:195], v155 offset:2048
	ds_read_b128 v[196:199], v155 offset:3072
	ds_read_b128 v[200:203], v155 offset:4096
	ds_read_b128 v[204:207], v155 offset:5120
	ds_read_b128 v[208:211], v155 offset:6144
	ds_read_b128 v[212:215], v155 offset:7168
	global_load_lds_dwordx4 v[148:149], off
	s_add_i32 m0, s52, 0xe000
	v_lshl_add_u64 v[148:149], s[44:45], 0, v[138:139]
	global_load_lds_dwordx4 v[148:149], off
	s_waitcnt vmcnt(8) lgkmcnt(0)
	s_barrier
	v_mfma_f32_16x16x32_bf16 v[124:127], v[144:147], v[184:187], 0
	v_mfma_f32_16x16x32_bf16 v[120:123], v[160:163], v[184:187], 0
	v_mfma_f32_16x16x32_bf16 v[108:111], v[144:147], v[192:195], 0
	v_mfma_f32_16x16x32_bf16 v[104:107], v[160:163], v[192:195], 0
	v_mfma_f32_16x16x32_bf16 v[92:95], v[144:147], v[200:203], 0
	v_mfma_f32_16x16x32_bf16 v[88:91], v[160:163], v[200:203], 0
	v_mfma_f32_16x16x32_bf16 v[76:79], v[144:147], v[208:211], 0
	v_mfma_f32_16x16x32_bf16 v[72:75], v[160:163], v[208:211], 0
	v_mfma_f32_16x16x32_bf16 v[124:127], v[156:159], v[188:191], v[124:127]
	v_mfma_f32_16x16x32_bf16 v[120:123], v[164:167], v[188:191], v[120:123]
	v_mfma_f32_16x16x32_bf16 v[108:111], v[156:159], v[196:199], v[108:111]
	v_mfma_f32_16x16x32_bf16 v[104:107], v[164:167], v[196:199], v[104:107]
	v_mfma_f32_16x16x32_bf16 v[92:95], v[156:159], v[204:207], v[92:95]
	v_mfma_f32_16x16x32_bf16 v[88:91], v[164:167], v[204:207], v[88:91]
	v_mfma_f32_16x16x32_bf16 v[76:79], v[156:159], v[212:215], v[76:79]
	v_mfma_f32_16x16x32_bf16 v[72:75], v[164:167], v[212:215], v[72:75]
	v_mfma_f32_16x16x32_bf16 v[116:119], v[168:171], v[184:187], 0
	v_mfma_f32_16x16x32_bf16 v[112:115], v[176:179], v[184:187], 0
	v_mfma_f32_16x16x32_bf16 v[100:103], v[168:171], v[192:195], 0
	v_mfma_f32_16x16x32_bf16 v[96:99], v[176:179], v[192:195], 0
	v_mfma_f32_16x16x32_bf16 v[84:87], v[168:171], v[200:203], 0
	v_mfma_f32_16x16x32_bf16 v[80:83], v[176:179], v[200:203], 0
	v_mfma_f32_16x16x32_bf16 v[68:71], v[168:171], v[208:211], 0
	v_mfma_f32_16x16x32_bf16 v[64:67], v[176:179], v[208:211], 0
	v_mfma_f32_16x16x32_bf16 v[116:119], v[172:175], v[188:191], v[116:119]
	v_mfma_f32_16x16x32_bf16 v[112:115], v[180:183], v[188:191], v[112:115]
	v_mfma_f32_16x16x32_bf16 v[100:103], v[172:175], v[196:199], v[100:103]
	v_mfma_f32_16x16x32_bf16 v[96:99], v[180:183], v[196:199], v[96:99]
	v_mfma_f32_16x16x32_bf16 v[84:87], v[172:175], v[204:207], v[84:87]
	v_mfma_f32_16x16x32_bf16 v[80:83], v[180:183], v[204:207], v[80:83]
	v_mfma_f32_16x16x32_bf16 v[68:71], v[172:175], v[212:215], v[68:71]
	v_mfma_f32_16x16x32_bf16 v[64:67], v[180:183], v[212:215], v[64:67]
	s_barrier
	s_add_i32 s44, s61, s33
	v_lshl_add_u64 v[148:149], s[48:49], 0, v[132:133]
	s_mov_b32 m0, s44
	ds_read_b128 v[184:187], v155 offset:16384
	ds_read_b128 v[188:191], v155 offset:17408
	ds_read_b128 v[192:195], v155 offset:18432
	ds_read_b128 v[196:199], v155 offset:19456
	ds_read_b128 v[200:203], v155 offset:20480
	ds_read_b128 v[204:207], v155 offset:21504
	ds_read_b128 v[208:211], v155 offset:22528
	ds_read_b128 v[212:215], v155 offset:23552
	global_load_lds_dwordx4 v[148:149], off
	s_add_i32 m0, s44, 0x2000
	s_add_u32 s44, s48, 0x20000
	v_lshl_add_u64 v[216:217], s[48:49], 0, v[128:129]
	s_addc_u32 s45, s49, 0
	s_add_i32 s68, s62, s33
	global_load_lds_dwordx4 v[216:217], off
	v_lshl_add_u64 v[220:221], s[44:45], 0, v[132:133]
	s_mov_b32 m0, s68
	v_lshl_add_u64 v[224:225], s[76:77], 0, v[130:131]
	global_load_lds_dwordx4 v[220:221], off
	v_lshl_add_u64 v[220:221], s[44:45], 0, v[128:129]
	s_add_i32 m0, s68, 0x2000
	v_lshl_add_u64 v[226:227], v[224:225], 0, s[8:9]
	global_load_lds_dwordx4 v[220:221], off
	s_mov_b32 m0, s52
	v_lshl_add_u64 v[220:221], s[76:77], 0, v[134:135]
	global_load_lds_dwordx4 v[220:221], off
	s_mov_b32 m0, s53
	s_nop 0
	global_load_lds_dwordx4 v[226:227], off
	s_waitcnt vmcnt(8) lgkmcnt(0)
	s_barrier
	v_mfma_f32_16x16x32_bf16 v[60:63], v[144:147], v[184:187], 0
	v_mfma_f32_16x16x32_bf16 v[56:59], v[160:163], v[184:187], 0
	v_mfma_f32_16x16x32_bf16 v[44:47], v[144:147], v[192:195], 0
	v_mfma_f32_16x16x32_bf16 v[40:43], v[160:163], v[192:195], 0
	v_mfma_f32_16x16x32_bf16 v[28:31], v[144:147], v[200:203], 0
	v_mfma_f32_16x16x32_bf16 v[24:27], v[160:163], v[200:203], 0
	v_mfma_f32_16x16x32_bf16 v[12:15], v[144:147], v[208:211], 0
	v_mfma_f32_16x16x32_bf16 v[8:11], v[160:163], v[208:211], 0
	v_mfma_f32_16x16x32_bf16 v[60:63], v[156:159], v[188:191], v[60:63]
	v_mfma_f32_16x16x32_bf16 v[56:59], v[164:167], v[188:191], v[56:59]
	v_mfma_f32_16x16x32_bf16 v[44:47], v[156:159], v[196:199], v[44:47]
	v_mfma_f32_16x16x32_bf16 v[40:43], v[164:167], v[196:199], v[40:43]
	v_mfma_f32_16x16x32_bf16 v[28:31], v[156:159], v[204:207], v[28:31]
	v_mfma_f32_16x16x32_bf16 v[24:27], v[164:167], v[204:207], v[24:27]
	v_mfma_f32_16x16x32_bf16 v[12:15], v[156:159], v[212:215], v[12:15]
	v_mfma_f32_16x16x32_bf16 v[8:11], v[164:167], v[212:215], v[8:11]
	v_mfma_f32_16x16x32_bf16 v[52:55], v[168:171], v[184:187], 0
	v_mfma_f32_16x16x32_bf16 v[48:51], v[176:179], v[184:187], 0
	v_mfma_f32_16x16x32_bf16 v[36:39], v[168:171], v[192:195], 0
	v_mfma_f32_16x16x32_bf16 v[32:35], v[176:179], v[192:195], 0
	v_mfma_f32_16x16x32_bf16 v[20:23], v[168:171], v[200:203], 0
	v_mfma_f32_16x16x32_bf16 v[16:19], v[176:179], v[200:203], 0
	v_mfma_f32_16x16x32_bf16 v[4:7], v[168:171], v[208:211], 0
	v_mfma_f32_16x16x32_bf16 v[0:3], v[176:179], v[208:211], 0
	v_mfma_f32_16x16x32_bf16 v[52:55], v[172:175], v[188:191], v[52:55]
	v_mfma_f32_16x16x32_bf16 v[48:51], v[180:183], v[188:191], v[48:51]
	v_mfma_f32_16x16x32_bf16 v[36:39], v[172:175], v[196:199], v[36:39]
	v_mfma_f32_16x16x32_bf16 v[32:35], v[180:183], v[196:199], v[32:35]
	v_mfma_f32_16x16x32_bf16 v[20:23], v[172:175], v[204:207], v[20:23]
	v_mfma_f32_16x16x32_bf16 v[16:19], v[180:183], v[204:207], v[16:19]
	v_mfma_f32_16x16x32_bf16 v[4:7], v[172:175], v[212:215], v[4:7]
	v_mfma_f32_16x16x32_bf16 v[0:3], v[180:183], v[212:215], v[0:3]
	s_barrier
	s_add_i32 s44, 0, 0x18000
	s_add_i32 s68, 0, 0x1c000
	v_add_u32_e32 v164, s44, v151
	v_add_u32_e32 v180, s68, v151
	ds_read_b128 v[144:147], v164
	ds_read_b128 v[156:159], v164 offset:1024
	ds_read_b128 v[160:163], v164 offset:2048
	ds_read_b128 v[164:167], v164 offset:3072
	ds_read_b128 v[168:171], v180
	ds_read_b128 v[172:175], v180 offset:1024
	ds_read_b128 v[176:179], v180 offset:2048
	ds_read_b128 v[180:183], v180 offset:3072
	s_mov_b32 m0, s54
	v_lshl_add_u64 v[226:227], v[220:221], 0, s[6:7]
	ds_read_b128 v[184:187], v155 offset:32768
	ds_read_b128 v[188:191], v155 offset:33792
	ds_read_b128 v[192:195], v155 offset:34816
	ds_read_b128 v[196:199], v155 offset:35840
	ds_read_b128 v[200:203], v155 offset:36864
	ds_read_b128 v[204:207], v155 offset:37888
	ds_read_b128 v[208:211], v155 offset:38912
	ds_read_b128 v[212:215], v155 offset:39936
	global_load_lds_dwordx4 v[226:227], off
	s_mov_b32 m0, s55
	v_lshl_add_u64 v[226:227], v[224:225], 0, s[12:13]
	global_load_lds_dwordx4 v[226:227], off
	s_waitcnt vmcnt(8) lgkmcnt(0)
	s_barrier
	v_mfma_f32_16x16x32_bf16 v[124:127], v[144:147], v[184:187], v[124:127]
	v_mfma_f32_16x16x32_bf16 v[120:123], v[160:163], v[184:187], v[120:123]
	v_mfma_f32_16x16x32_bf16 v[108:111], v[144:147], v[192:195], v[108:111]
	v_mfma_f32_16x16x32_bf16 v[104:107], v[160:163], v[192:195], v[104:107]
	v_mfma_f32_16x16x32_bf16 v[92:95], v[144:147], v[200:203], v[92:95]
	v_mfma_f32_16x16x32_bf16 v[88:91], v[160:163], v[200:203], v[88:91]
	v_mfma_f32_16x16x32_bf16 v[76:79], v[144:147], v[208:211], v[76:79]
	v_mfma_f32_16x16x32_bf16 v[72:75], v[160:163], v[208:211], v[72:75]
	v_mfma_f32_16x16x32_bf16 v[124:127], v[156:159], v[188:191], v[124:127]
	v_mfma_f32_16x16x32_bf16 v[120:123], v[164:167], v[188:191], v[120:123]
	v_mfma_f32_16x16x32_bf16 v[108:111], v[156:159], v[196:199], v[108:111]
	v_mfma_f32_16x16x32_bf16 v[104:107], v[164:167], v[196:199], v[104:107]
	v_mfma_f32_16x16x32_bf16 v[92:95], v[156:159], v[204:207], v[92:95]
	v_mfma_f32_16x16x32_bf16 v[88:91], v[164:167], v[204:207], v[88:91]
	v_mfma_f32_16x16x32_bf16 v[76:79], v[156:159], v[212:215], v[76:79]
	v_mfma_f32_16x16x32_bf16 v[72:75], v[164:167], v[212:215], v[72:75]
	v_mfma_f32_16x16x32_bf16 v[116:119], v[168:171], v[184:187], v[116:119]
	v_mfma_f32_16x16x32_bf16 v[112:115], v[176:179], v[184:187], v[112:115]
	v_mfma_f32_16x16x32_bf16 v[100:103], v[168:171], v[192:195], v[100:103]
	v_mfma_f32_16x16x32_bf16 v[96:99], v[176:179], v[192:195], v[96:99]
	v_mfma_f32_16x16x32_bf16 v[84:87], v[168:171], v[200:203], v[84:87]
	v_mfma_f32_16x16x32_bf16 v[80:83], v[176:179], v[200:203], v[80:83]
	v_mfma_f32_16x16x32_bf16 v[68:71], v[168:171], v[208:211], v[68:71]
	v_mfma_f32_16x16x32_bf16 v[64:67], v[176:179], v[208:211], v[64:67]
	v_mfma_f32_16x16x32_bf16 v[116:119], v[172:175], v[188:191], v[116:119]
	v_mfma_f32_16x16x32_bf16 v[112:115], v[180:183], v[188:191], v[112:115]
	v_mfma_f32_16x16x32_bf16 v[100:103], v[172:175], v[196:199], v[100:103]
	v_mfma_f32_16x16x32_bf16 v[96:99], v[180:183], v[196:199], v[96:99]
	v_mfma_f32_16x16x32_bf16 v[84:87], v[172:175], v[204:207], v[84:87]
	v_mfma_f32_16x16x32_bf16 v[80:83], v[180:183], v[204:207], v[80:83]
	v_mfma_f32_16x16x32_bf16 v[68:71], v[172:175], v[212:215], v[68:71]
	v_mfma_f32_16x16x32_bf16 v[64:67], v[180:183], v[212:215], v[64:67]
	s_barrier
	s_add_i32 s44, s44, s33
	v_lshl_add_u64 v[148:149], v[148:149], 0, s[22:23]
	s_mov_b32 m0, s44
	ds_read_b128 v[184:187], v155 offset:49152
	ds_read_b128 v[188:191], v155 offset:50176
	ds_read_b128 v[192:195], v155 offset:51200
	ds_read_b128 v[196:199], v155 offset:52224
	ds_read_b128 v[200:203], v155 offset:53248
	ds_read_b128 v[204:207], v155 offset:54272
	ds_read_b128 v[208:211], v155 offset:55296
	ds_read_b128 v[212:215], v155 offset:56320
	global_load_lds_dwordx4 v[148:149], off
	s_add_i32 m0, s44, 0x2000
	s_add_u32 s44, s48, 0x20080
	v_lshl_add_u64 v[148:149], v[216:217], 0, s[22:23]
	s_addc_u32 s45, s49, 0
	s_add_i32 s48, s68, s33
	global_load_lds_dwordx4 v[148:149], off
	s_mov_b32 m0, s48
	v_lshl_add_u64 v[148:149], s[44:45], 0, v[132:133]
	global_load_lds_dwordx4 v[148:149], off
	s_add_i32 m0, s48, 0x2000
	v_lshl_add_u64 v[148:149], s[44:45], 0, v[128:129]
	global_load_lds_dwordx4 v[148:149], off
	s_mov_b32 m0, s57
	v_lshl_add_u64 v[148:149], v[220:221], 0, s[22:23]
	global_load_lds_dwordx4 v[148:149], off
	s_mov_b32 m0, s58
	v_lshl_add_u64 v[148:149], v[224:225], 0, s[24:25]
	global_load_lds_dwordx4 v[148:149], off
	s_waitcnt vmcnt(8) lgkmcnt(0)
	s_barrier
	v_mfma_f32_16x16x32_bf16 v[60:63], v[144:147], v[184:187], v[60:63]
	v_mfma_f32_16x16x32_bf16 v[56:59], v[160:163], v[184:187], v[56:59]
	v_mfma_f32_16x16x32_bf16 v[44:47], v[144:147], v[192:195], v[44:47]
	v_mfma_f32_16x16x32_bf16 v[40:43], v[160:163], v[192:195], v[40:43]
	v_mfma_f32_16x16x32_bf16 v[28:31], v[144:147], v[200:203], v[28:31]
	v_mfma_f32_16x16x32_bf16 v[24:27], v[160:163], v[200:203], v[24:27]
	v_mfma_f32_16x16x32_bf16 v[12:15], v[144:147], v[208:211], v[12:15]
	v_mfma_f32_16x16x32_bf16 v[8:11], v[160:163], v[208:211], v[8:11]
	v_mfma_f32_16x16x32_bf16 v[60:63], v[156:159], v[188:191], v[60:63]
	v_mfma_f32_16x16x32_bf16 v[56:59], v[164:167], v[188:191], v[56:59]
	v_mfma_f32_16x16x32_bf16 v[44:47], v[156:159], v[196:199], v[44:47]
	v_mfma_f32_16x16x32_bf16 v[40:43], v[164:167], v[196:199], v[40:43]
	v_mfma_f32_16x16x32_bf16 v[28:31], v[156:159], v[204:207], v[28:31]
	v_mfma_f32_16x16x32_bf16 v[24:27], v[164:167], v[204:207], v[24:27]
	v_mfma_f32_16x16x32_bf16 v[12:15], v[156:159], v[212:215], v[12:15]
	v_mfma_f32_16x16x32_bf16 v[8:11], v[164:167], v[212:215], v[8:11]
	v_mfma_f32_16x16x32_bf16 v[52:55], v[168:171], v[184:187], v[52:55]
	v_mfma_f32_16x16x32_bf16 v[48:51], v[176:179], v[184:187], v[48:51]
	v_mfma_f32_16x16x32_bf16 v[36:39], v[168:171], v[192:195], v[36:39]
	v_mfma_f32_16x16x32_bf16 v[32:35], v[176:179], v[192:195], v[32:35]
	v_mfma_f32_16x16x32_bf16 v[20:23], v[168:171], v[200:203], v[20:23]
	v_mfma_f32_16x16x32_bf16 v[16:19], v[176:179], v[200:203], v[16:19]
	v_mfma_f32_16x16x32_bf16 v[4:7], v[168:171], v[208:211], v[4:7]
	v_mfma_f32_16x16x32_bf16 v[0:3], v[176:179], v[208:211], v[0:3]
	v_mfma_f32_16x16x32_bf16 v[52:55], v[172:175], v[188:191], v[52:55]
	v_mfma_f32_16x16x32_bf16 v[48:51], v[180:183], v[188:191], v[48:51]
	v_mfma_f32_16x16x32_bf16 v[36:39], v[172:175], v[196:199], v[36:39]
	v_mfma_f32_16x16x32_bf16 v[32:35], v[180:183], v[196:199], v[32:35]
	v_mfma_f32_16x16x32_bf16 v[20:23], v[172:175], v[204:207], v[20:23]
	v_mfma_f32_16x16x32_bf16 v[16:19], v[180:183], v[204:207], v[16:19]
	v_mfma_f32_16x16x32_bf16 v[4:7], v[172:175], v[212:215], v[4:7]
	v_mfma_f32_16x16x32_bf16 v[0:3], v[180:183], v[212:215], v[0:3]
	s_barrier
	s_add_i32 s74, s74, 2
	s_add_u32 s51, s51, 0x100
	s_addc_u32 s73, s73, 0
	s_cmp_gt_u32 s74, 5
	s_mov_b64 s[44:45], s[46:47]
.LBB0_393:
	ds_read_b128 v[144:147], v153
	ds_read_b128 v[156:159], v153 offset:1024
	ds_read_b128 v[160:163], v153 offset:2048
	ds_read_b128 v[164:167], v153 offset:3072
	ds_read_b128 v[168:171], v154
	ds_read_b128 v[172:175], v154 offset:1024
	ds_read_b128 v[176:179], v154 offset:2048
	ds_read_b128 v[180:183], v154 offset:3072
	s_add_u32 s46, s44, 0x100
	s_addc_u32 s47, s45, 0
	s_cmp_eq_u32 s74, 4
	s_cselect_b32 s77, s67, s47
	s_cselect_b32 s76, s72, s46
	s_cselect_b32 s49, s39, s73
	s_cselect_b32 s48, s50, s51
	v_lshl_add_u64 v[148:149], s[44:45], 0, v[136:137]
	s_add_i32 m0, s52, 0xc000
	ds_read_b128 v[184:187], v155
	ds_read_b128 v[188:191], v155 offset:1024
	ds_read_b128 v[192:195], v155 offset:2048
	ds_read_b128 v[196:199], v155 offset:3072
	ds_read_b128 v[200:203], v155 offset:4096
	ds_read_b128 v[204:207], v155 offset:5120
	ds_read_b128 v[208:211], v155 offset:6144
	ds_read_b128 v[212:215], v155 offset:7168
	global_load_lds_dwordx4 v[148:149], off
	s_add_i32 m0, s52, 0xe000
	v_lshl_add_u64 v[148:149], s[44:45], 0, v[138:139]
	global_load_lds_dwordx4 v[148:149], off
	s_waitcnt vmcnt(8) lgkmcnt(0)
	s_barrier
	v_mfma_f32_16x16x32_bf16 v[124:127], v[144:147], v[184:187], v[124:127]
	v_mfma_f32_16x16x32_bf16 v[120:123], v[160:163], v[184:187], v[120:123]
	v_mfma_f32_16x16x32_bf16 v[108:111], v[144:147], v[192:195], v[108:111]
	v_mfma_f32_16x16x32_bf16 v[104:107], v[160:163], v[192:195], v[104:107]
	v_mfma_f32_16x16x32_bf16 v[92:95], v[144:147], v[200:203], v[92:95]
	v_mfma_f32_16x16x32_bf16 v[88:91], v[160:163], v[200:203], v[88:91]
	v_mfma_f32_16x16x32_bf16 v[76:79], v[144:147], v[208:211], v[76:79]
	v_mfma_f32_16x16x32_bf16 v[72:75], v[160:163], v[208:211], v[72:75]
	v_mfma_f32_16x16x32_bf16 v[124:127], v[156:159], v[188:191], v[124:127]
	v_mfma_f32_16x16x32_bf16 v[120:123], v[164:167], v[188:191], v[120:123]
	v_mfma_f32_16x16x32_bf16 v[108:111], v[156:159], v[196:199], v[108:111]
	v_mfma_f32_16x16x32_bf16 v[104:107], v[164:167], v[196:199], v[104:107]
	v_mfma_f32_16x16x32_bf16 v[92:95], v[156:159], v[204:207], v[92:95]
	v_mfma_f32_16x16x32_bf16 v[88:91], v[164:167], v[204:207], v[88:91]
	v_mfma_f32_16x16x32_bf16 v[76:79], v[156:159], v[212:215], v[76:79]
	v_mfma_f32_16x16x32_bf16 v[72:75], v[164:167], v[212:215], v[72:75]
	v_mfma_f32_16x16x32_bf16 v[116:119], v[168:171], v[184:187], v[116:119]
	v_mfma_f32_16x16x32_bf16 v[112:115], v[176:179], v[184:187], v[112:115]
	v_mfma_f32_16x16x32_bf16 v[100:103], v[168:171], v[192:195], v[100:103]
	v_mfma_f32_16x16x32_bf16 v[96:99], v[176:179], v[192:195], v[96:99]
	v_mfma_f32_16x16x32_bf16 v[84:87], v[168:171], v[200:203], v[84:87]
	v_mfma_f32_16x16x32_bf16 v[80:83], v[176:179], v[200:203], v[80:83]
	v_mfma_f32_16x16x32_bf16 v[68:71], v[168:171], v[208:211], v[68:71]
	v_mfma_f32_16x16x32_bf16 v[64:67], v[176:179], v[208:211], v[64:67]
	v_mfma_f32_16x16x32_bf16 v[116:119], v[172:175], v[188:191], v[116:119]
	v_mfma_f32_16x16x32_bf16 v[112:115], v[180:183], v[188:191], v[112:115]
	v_mfma_f32_16x16x32_bf16 v[100:103], v[172:175], v[196:199], v[100:103]
	v_mfma_f32_16x16x32_bf16 v[96:99], v[180:183], v[196:199], v[96:99]
	v_mfma_f32_16x16x32_bf16 v[84:87], v[172:175], v[204:207], v[84:87]
	v_mfma_f32_16x16x32_bf16 v[80:83], v[180:183], v[204:207], v[80:83]
	v_mfma_f32_16x16x32_bf16 v[68:71], v[172:175], v[212:215], v[68:71]
	v_mfma_f32_16x16x32_bf16 v[64:67], v[180:183], v[212:215], v[64:67]
	s_barrier
	s_add_i32 s44, s61, s33
	v_lshl_add_u64 v[148:149], s[48:49], 0, v[132:133]
	s_mov_b32 m0, s44
	ds_read_b128 v[184:187], v155 offset:16384
	ds_read_b128 v[188:191], v155 offset:17408
	ds_read_b128 v[192:195], v155 offset:18432
	ds_read_b128 v[196:199], v155 offset:19456
	ds_read_b128 v[200:203], v155 offset:20480
	ds_read_b128 v[204:207], v155 offset:21504
	ds_read_b128 v[208:211], v155 offset:22528
	ds_read_b128 v[212:215], v155 offset:23552
	global_load_lds_dwordx4 v[148:149], off
	s_add_i32 m0, s44, 0x2000
	s_add_u32 s44, s48, 0x20000
	v_lshl_add_u64 v[216:217], s[48:49], 0, v[128:129]
	s_addc_u32 s45, s49, 0
	s_add_i32 s68, s62, s33
	global_load_lds_dwordx4 v[216:217], off
	v_lshl_add_u64 v[220:221], s[44:45], 0, v[132:133]
	s_mov_b32 m0, s68
	v_lshl_add_u64 v[224:225], s[76:77], 0, v[130:131]
	global_load_lds_dwordx4 v[220:221], off
	v_lshl_add_u64 v[220:221], s[44:45], 0, v[128:129]
	s_add_i32 m0, s68, 0x2000
	v_lshl_add_u64 v[226:227], v[224:225], 0, s[8:9]
	global_load_lds_dwordx4 v[220:221], off
	s_mov_b32 m0, s52
	v_lshl_add_u64 v[220:221], s[76:77], 0, v[134:135]
	global_load_lds_dwordx4 v[220:221], off
	s_mov_b32 m0, s53
	s_nop 0
	global_load_lds_dwordx4 v[226:227], off
	s_waitcnt vmcnt(8) lgkmcnt(0)
	s_barrier
	v_mfma_f32_16x16x32_bf16 v[60:63], v[144:147], v[184:187], v[60:63]
	v_mfma_f32_16x16x32_bf16 v[56:59], v[160:163], v[184:187], v[56:59]
	v_mfma_f32_16x16x32_bf16 v[44:47], v[144:147], v[192:195], v[44:47]
	v_mfma_f32_16x16x32_bf16 v[40:43], v[160:163], v[192:195], v[40:43]
	v_mfma_f32_16x16x32_bf16 v[28:31], v[144:147], v[200:203], v[28:31]
	v_mfma_f32_16x16x32_bf16 v[24:27], v[160:163], v[200:203], v[24:27]
	v_mfma_f32_16x16x32_bf16 v[12:15], v[144:147], v[208:211], v[12:15]
	v_mfma_f32_16x16x32_bf16 v[8:11], v[160:163], v[208:211], v[8:11]
	v_mfma_f32_16x16x32_bf16 v[60:63], v[156:159], v[188:191], v[60:63]
	v_mfma_f32_16x16x32_bf16 v[56:59], v[164:167], v[188:191], v[56:59]
	v_mfma_f32_16x16x32_bf16 v[44:47], v[156:159], v[196:199], v[44:47]
	v_mfma_f32_16x16x32_bf16 v[40:43], v[164:167], v[196:199], v[40:43]
	v_mfma_f32_16x16x32_bf16 v[28:31], v[156:159], v[204:207], v[28:31]
	v_mfma_f32_16x16x32_bf16 v[24:27], v[164:167], v[204:207], v[24:27]
	v_mfma_f32_16x16x32_bf16 v[12:15], v[156:159], v[212:215], v[12:15]
	v_mfma_f32_16x16x32_bf16 v[8:11], v[164:167], v[212:215], v[8:11]
	v_mfma_f32_16x16x32_bf16 v[52:55], v[168:171], v[184:187], v[52:55]
	v_mfma_f32_16x16x32_bf16 v[48:51], v[176:179], v[184:187], v[48:51]
	v_mfma_f32_16x16x32_bf16 v[36:39], v[168:171], v[192:195], v[36:39]
	v_mfma_f32_16x16x32_bf16 v[32:35], v[176:179], v[192:195], v[32:35]
	v_mfma_f32_16x16x32_bf16 v[20:23], v[168:171], v[200:203], v[20:23]
	v_mfma_f32_16x16x32_bf16 v[16:19], v[176:179], v[200:203], v[16:19]
	v_mfma_f32_16x16x32_bf16 v[4:7], v[168:171], v[208:211], v[4:7]
	v_mfma_f32_16x16x32_bf16 v[0:3], v[176:179], v[208:211], v[0:3]
	v_mfma_f32_16x16x32_bf16 v[52:55], v[172:175], v[188:191], v[52:55]
	v_mfma_f32_16x16x32_bf16 v[48:51], v[180:183], v[188:191], v[48:51]
	v_mfma_f32_16x16x32_bf16 v[36:39], v[172:175], v[196:199], v[36:39]
	v_mfma_f32_16x16x32_bf16 v[32:35], v[180:183], v[196:199], v[32:35]
	v_mfma_f32_16x16x32_bf16 v[20:23], v[172:175], v[204:207], v[20:23]
	v_mfma_f32_16x16x32_bf16 v[16:19], v[180:183], v[204:207], v[16:19]
	v_mfma_f32_16x16x32_bf16 v[4:7], v[172:175], v[212:215], v[4:7]
	v_mfma_f32_16x16x32_bf16 v[0:3], v[180:183], v[212:215], v[0:3]
	s_barrier
	s_add_i32 s44, 0, 0x18000
	s_add_i32 s68, 0, 0x1c000
	v_add_u32_e32 v164, s44, v151
	v_add_u32_e32 v180, s68, v151
	ds_read_b128 v[144:147], v164
	ds_read_b128 v[156:159], v164 offset:1024
	ds_read_b128 v[160:163], v164 offset:2048
	ds_read_b128 v[164:167], v164 offset:3072
	ds_read_b128 v[168:171], v180
	ds_read_b128 v[172:175], v180 offset:1024
	ds_read_b128 v[176:179], v180 offset:2048
	ds_read_b128 v[180:183], v180 offset:3072
	s_mov_b32 m0, s54
	v_lshl_add_u64 v[226:227], v[220:221], 0, s[6:7]
	ds_read_b128 v[184:187], v155 offset:32768
	ds_read_b128 v[188:191], v155 offset:33792
	ds_read_b128 v[192:195], v155 offset:34816
	ds_read_b128 v[196:199], v155 offset:35840
	ds_read_b128 v[200:203], v155 offset:36864
	ds_read_b128 v[204:207], v155 offset:37888
	ds_read_b128 v[208:211], v155 offset:38912
	ds_read_b128 v[212:215], v155 offset:39936
	global_load_lds_dwordx4 v[226:227], off
	s_mov_b32 m0, s55
	v_lshl_add_u64 v[226:227], v[224:225], 0, s[12:13]
	global_load_lds_dwordx4 v[226:227], off
	s_waitcnt vmcnt(8) lgkmcnt(0)
	s_barrier
	v_mfma_f32_16x16x32_bf16 v[124:127], v[144:147], v[184:187], v[124:127]
	v_mfma_f32_16x16x32_bf16 v[120:123], v[160:163], v[184:187], v[120:123]
	v_mfma_f32_16x16x32_bf16 v[108:111], v[144:147], v[192:195], v[108:111]
	v_mfma_f32_16x16x32_bf16 v[104:107], v[160:163], v[192:195], v[104:107]
	v_mfma_f32_16x16x32_bf16 v[92:95], v[144:147], v[200:203], v[92:95]
	v_mfma_f32_16x16x32_bf16 v[88:91], v[160:163], v[200:203], v[88:91]
	v_mfma_f32_16x16x32_bf16 v[76:79], v[144:147], v[208:211], v[76:79]
	v_mfma_f32_16x16x32_bf16 v[72:75], v[160:163], v[208:211], v[72:75]
	v_mfma_f32_16x16x32_bf16 v[124:127], v[156:159], v[188:191], v[124:127]
	v_mfma_f32_16x16x32_bf16 v[120:123], v[164:167], v[188:191], v[120:123]
	v_mfma_f32_16x16x32_bf16 v[108:111], v[156:159], v[196:199], v[108:111]
	v_mfma_f32_16x16x32_bf16 v[104:107], v[164:167], v[196:199], v[104:107]
	v_mfma_f32_16x16x32_bf16 v[92:95], v[156:159], v[204:207], v[92:95]
	v_mfma_f32_16x16x32_bf16 v[88:91], v[164:167], v[204:207], v[88:91]
	v_mfma_f32_16x16x32_bf16 v[76:79], v[156:159], v[212:215], v[76:79]
	v_mfma_f32_16x16x32_bf16 v[72:75], v[164:167], v[212:215], v[72:75]
	v_mfma_f32_16x16x32_bf16 v[116:119], v[168:171], v[184:187], v[116:119]
	v_mfma_f32_16x16x32_bf16 v[112:115], v[176:179], v[184:187], v[112:115]
	v_mfma_f32_16x16x32_bf16 v[100:103], v[168:171], v[192:195], v[100:103]
	v_mfma_f32_16x16x32_bf16 v[96:99], v[176:179], v[192:195], v[96:99]
	v_mfma_f32_16x16x32_bf16 v[84:87], v[168:171], v[200:203], v[84:87]
	v_mfma_f32_16x16x32_bf16 v[80:83], v[176:179], v[200:203], v[80:83]
	v_mfma_f32_16x16x32_bf16 v[68:71], v[168:171], v[208:211], v[68:71]
	v_mfma_f32_16x16x32_bf16 v[64:67], v[176:179], v[208:211], v[64:67]
	v_mfma_f32_16x16x32_bf16 v[116:119], v[172:175], v[188:191], v[116:119]
	v_mfma_f32_16x16x32_bf16 v[112:115], v[180:183], v[188:191], v[112:115]
	v_mfma_f32_16x16x32_bf16 v[100:103], v[172:175], v[196:199], v[100:103]
	v_mfma_f32_16x16x32_bf16 v[96:99], v[180:183], v[196:199], v[96:99]
	v_mfma_f32_16x16x32_bf16 v[84:87], v[172:175], v[204:207], v[84:87]
	v_mfma_f32_16x16x32_bf16 v[80:83], v[180:183], v[204:207], v[80:83]
	v_mfma_f32_16x16x32_bf16 v[68:71], v[172:175], v[212:215], v[68:71]
	v_mfma_f32_16x16x32_bf16 v[64:67], v[180:183], v[212:215], v[64:67]
	s_barrier
	s_add_i32 s44, s44, s33
	v_lshl_add_u64 v[148:149], v[148:149], 0, s[22:23]
	s_mov_b32 m0, s44
	ds_read_b128 v[184:187], v155 offset:49152
	ds_read_b128 v[188:191], v155 offset:50176
	ds_read_b128 v[192:195], v155 offset:51200
	ds_read_b128 v[196:199], v155 offset:52224
	ds_read_b128 v[200:203], v155 offset:53248
	ds_read_b128 v[204:207], v155 offset:54272
	ds_read_b128 v[208:211], v155 offset:55296
	ds_read_b128 v[212:215], v155 offset:56320
	global_load_lds_dwordx4 v[148:149], off
	s_add_i32 m0, s44, 0x2000
	s_add_u32 s44, s48, 0x20080
	v_lshl_add_u64 v[148:149], v[216:217], 0, s[22:23]
	s_addc_u32 s45, s49, 0
	s_add_i32 s48, s68, s33
	global_load_lds_dwordx4 v[148:149], off
	s_mov_b32 m0, s48
	v_lshl_add_u64 v[148:149], s[44:45], 0, v[132:133]
	global_load_lds_dwordx4 v[148:149], off
	s_add_i32 m0, s48, 0x2000
	v_lshl_add_u64 v[148:149], s[44:45], 0, v[128:129]
	global_load_lds_dwordx4 v[148:149], off
	s_mov_b32 m0, s57
	v_lshl_add_u64 v[148:149], v[220:221], 0, s[22:23]
	global_load_lds_dwordx4 v[148:149], off
	s_mov_b32 m0, s58
	v_lshl_add_u64 v[148:149], v[224:225], 0, s[24:25]
	global_load_lds_dwordx4 v[148:149], off
	s_waitcnt vmcnt(8) lgkmcnt(0)
	s_barrier
	v_mfma_f32_16x16x32_bf16 v[60:63], v[144:147], v[184:187], v[60:63]
	v_mfma_f32_16x16x32_bf16 v[56:59], v[160:163], v[184:187], v[56:59]
	v_mfma_f32_16x16x32_bf16 v[44:47], v[144:147], v[192:195], v[44:47]
	v_mfma_f32_16x16x32_bf16 v[40:43], v[160:163], v[192:195], v[40:43]
	v_mfma_f32_16x16x32_bf16 v[28:31], v[144:147], v[200:203], v[28:31]
	v_mfma_f32_16x16x32_bf16 v[24:27], v[160:163], v[200:203], v[24:27]
	v_mfma_f32_16x16x32_bf16 v[12:15], v[144:147], v[208:211], v[12:15]
	v_mfma_f32_16x16x32_bf16 v[8:11], v[160:163], v[208:211], v[8:11]
	v_mfma_f32_16x16x32_bf16 v[60:63], v[156:159], v[188:191], v[60:63]
	v_mfma_f32_16x16x32_bf16 v[56:59], v[164:167], v[188:191], v[56:59]
	v_mfma_f32_16x16x32_bf16 v[44:47], v[156:159], v[196:199], v[44:47]
	v_mfma_f32_16x16x32_bf16 v[40:43], v[164:167], v[196:199], v[40:43]
	v_mfma_f32_16x16x32_bf16 v[28:31], v[156:159], v[204:207], v[28:31]
	v_mfma_f32_16x16x32_bf16 v[24:27], v[164:167], v[204:207], v[24:27]
	v_mfma_f32_16x16x32_bf16 v[12:15], v[156:159], v[212:215], v[12:15]
	v_mfma_f32_16x16x32_bf16 v[8:11], v[164:167], v[212:215], v[8:11]
	v_mfma_f32_16x16x32_bf16 v[52:55], v[168:171], v[184:187], v[52:55]
	v_mfma_f32_16x16x32_bf16 v[48:51], v[176:179], v[184:187], v[48:51]
	v_mfma_f32_16x16x32_bf16 v[36:39], v[168:171], v[192:195], v[36:39]
	v_mfma_f32_16x16x32_bf16 v[32:35], v[176:179], v[192:195], v[32:35]
	v_mfma_f32_16x16x32_bf16 v[20:23], v[168:171], v[200:203], v[20:23]
	v_mfma_f32_16x16x32_bf16 v[16:19], v[176:179], v[200:203], v[16:19]
	v_mfma_f32_16x16x32_bf16 v[4:7], v[168:171], v[208:211], v[4:7]
	v_mfma_f32_16x16x32_bf16 v[0:3], v[176:179], v[208:211], v[0:3]
	v_mfma_f32_16x16x32_bf16 v[52:55], v[172:175], v[188:191], v[52:55]
	v_mfma_f32_16x16x32_bf16 v[48:51], v[180:183], v[188:191], v[48:51]
	v_mfma_f32_16x16x32_bf16 v[36:39], v[172:175], v[196:199], v[36:39]
	v_mfma_f32_16x16x32_bf16 v[32:35], v[180:183], v[196:199], v[32:35]
	v_mfma_f32_16x16x32_bf16 v[20:23], v[172:175], v[204:207], v[20:23]
	v_mfma_f32_16x16x32_bf16 v[16:19], v[180:183], v[204:207], v[16:19]
	v_mfma_f32_16x16x32_bf16 v[4:7], v[172:175], v[212:215], v[4:7]
	v_mfma_f32_16x16x32_bf16 v[0:3], v[180:183], v[212:215], v[0:3]
	s_barrier
	s_add_i32 s74, s74, 2
	s_add_u32 s51, s51, 0x100
	s_addc_u32 s73, s73, 0
	s_cmp_gt_u32 s74, 5
	s_mov_b64 s[44:45], s[46:47]
	s_cbranch_scc0 .LBB0_393
	s_and_b64 vcc, exec, s[36:37]
	s_cbranch_vccz .LBB0_396
	s_barrier

.LBB0_465:
	s_lshl_b32 s42, s73, 8
	s_ashr_i32 s43, s42, 31
	s_lshl_b64 s[42:43], s[42:43], 11
	s_add_u32 s42, s10, s42
	s_addc_u32 s43, s11, s43
	s_and_b64 s[44:45], s[4:5], exec
	s_cselect_b32 s47, s43, s49
	s_cselect_b32 s74, s42, s48
	s_ashr_i32 s41, s40, 31
	s_lshl_b64 s[44:45], s[40:41], 19
	s_add_u32 s44, s33, s44
	s_addc_u32 s45, s34, s45
	s_and_b64 s[50:51], s[4:5], exec
	s_cselect_b32 s41, s45, s53
	s_cselect_b32 s50, s44, s52
	s_add_u32 s51, s52, 0x100
	s_addc_u32 s75, s53, 0
	s_mov_b32 s76, -2
	s_waitcnt lgkmcnt(0)
	s_waitcnt vmcnt(0)
	s_waitcnt lgkmcnt(0)
	ds_read_b128 v[144:147], v151
	ds_read_b128 v[156:159], v151 offset:1024
	ds_read_b128 v[160:163], v151 offset:2048
	ds_read_b128 v[164:167], v151 offset:3072
	ds_read_b128 v[168:171], v152
	ds_read_b128 v[172:175], v152 offset:1024
	ds_read_b128 v[176:179], v152 offset:2048
	ds_read_b128 v[180:183], v152 offset:3072
	s_add_u32 s52, s48, 0x100
	s_addc_u32 s53, s49, 0
	s_cmp_eq_u32 s76, 12
	s_cselect_b32 s79, s47, s53
	s_cselect_b32 s78, s74, s52
	s_cselect_b32 s55, s41, s75
	s_cselect_b32 s54, s50, s51
	v_lshl_add_u64 v[216:217], s[48:49], 0, v[136:137]
	s_add_i32 m0, s56, 0xc000
	ds_read_b128 v[184:187], v153
	ds_read_b128 v[188:191], v153 offset:1024
	ds_read_b128 v[192:195], v153 offset:2048
	ds_read_b128 v[196:199], v153 offset:3072
	ds_read_b128 v[200:203], v153 offset:4096
	ds_read_b128 v[204:207], v153 offset:5120
	ds_read_b128 v[208:211], v153 offset:6144
	ds_read_b128 v[212:215], v153 offset:7168
	global_load_lds_dwordx4 v[216:217], off
	s_add_i32 m0, s56, 0xe000
	v_lshl_add_u64 v[216:217], s[48:49], 0, v[138:139]
	global_load_lds_dwordx4 v[216:217], off
	s_waitcnt vmcnt(8) lgkmcnt(0)
	s_barrier
	v_mfma_f32_16x16x32_bf16 v[124:127], v[144:147], v[184:187], 0
	v_mfma_f32_16x16x32_bf16 v[120:123], v[160:163], v[184:187], 0
	v_mfma_f32_16x16x32_bf16 v[108:111], v[144:147], v[192:195], 0
	v_mfma_f32_16x16x32_bf16 v[104:107], v[160:163], v[192:195], 0
	v_mfma_f32_16x16x32_bf16 v[92:95], v[144:147], v[200:203], 0
	v_mfma_f32_16x16x32_bf16 v[88:91], v[160:163], v[200:203], 0
	v_mfma_f32_16x16x32_bf16 v[76:79], v[144:147], v[208:211], 0
	v_mfma_f32_16x16x32_bf16 v[72:75], v[160:163], v[208:211], 0
	v_mfma_f32_16x16x32_bf16 v[124:127], v[156:159], v[188:191], v[124:127]
	v_mfma_f32_16x16x32_bf16 v[120:123], v[164:167], v[188:191], v[120:123]
	v_mfma_f32_16x16x32_bf16 v[108:111], v[156:159], v[196:199], v[108:111]
	v_mfma_f32_16x16x32_bf16 v[104:107], v[164:167], v[196:199], v[104:107]
	v_mfma_f32_16x16x32_bf16 v[92:95], v[156:159], v[204:207], v[92:95]
	v_mfma_f32_16x16x32_bf16 v[88:91], v[164:167], v[204:207], v[88:91]
	v_mfma_f32_16x16x32_bf16 v[76:79], v[156:159], v[212:215], v[76:79]
	v_mfma_f32_16x16x32_bf16 v[72:75], v[164:167], v[212:215], v[72:75]
	v_mfma_f32_16x16x32_bf16 v[116:119], v[168:171], v[184:187], 0
	v_mfma_f32_16x16x32_bf16 v[112:115], v[176:179], v[184:187], 0
	v_mfma_f32_16x16x32_bf16 v[100:103], v[168:171], v[192:195], 0
	v_mfma_f32_16x16x32_bf16 v[96:99], v[176:179], v[192:195], 0
	v_mfma_f32_16x16x32_bf16 v[84:87], v[168:171], v[200:203], 0
	v_mfma_f32_16x16x32_bf16 v[80:83], v[176:179], v[200:203], 0
	v_mfma_f32_16x16x32_bf16 v[68:71], v[168:171], v[208:211], 0
	v_mfma_f32_16x16x32_bf16 v[64:67], v[176:179], v[208:211], 0
	v_mfma_f32_16x16x32_bf16 v[116:119], v[172:175], v[188:191], v[116:119]
	v_mfma_f32_16x16x32_bf16 v[112:115], v[180:183], v[188:191], v[112:115]
	v_mfma_f32_16x16x32_bf16 v[100:103], v[172:175], v[196:199], v[100:103]
	v_mfma_f32_16x16x32_bf16 v[96:99], v[180:183], v[196:199], v[96:99]
	v_mfma_f32_16x16x32_bf16 v[84:87], v[172:175], v[204:207], v[84:87]
	v_mfma_f32_16x16x32_bf16 v[80:83], v[180:183], v[204:207], v[80:83]
	v_mfma_f32_16x16x32_bf16 v[68:71], v[172:175], v[212:215], v[68:71]
	v_mfma_f32_16x16x32_bf16 v[64:67], v[180:183], v[212:215], v[64:67]
	s_barrier
	s_add_i32 s48, s67, s35
	v_lshl_add_u64 v[216:217], s[54:55], 0, v[130:131]
	s_mov_b32 m0, s48
	ds_read_b128 v[184:187], v153 offset:16384
	ds_read_b128 v[188:191], v153 offset:17408
	ds_read_b128 v[192:195], v153 offset:18432
	ds_read_b128 v[196:199], v153 offset:19456
	ds_read_b128 v[200:203], v153 offset:20480
	ds_read_b128 v[204:207], v153 offset:21504
	ds_read_b128 v[208:211], v153 offset:22528
	ds_read_b128 v[212:215], v153 offset:23552
	global_load_lds_dwordx4 v[216:217], off
	s_add_i32 m0, s48, 0x2000
	s_add_u32 s48, s54, 0x40000
	v_lshl_add_u64 v[220:221], s[54:55], 0, v[134:135]
	s_addc_u32 s49, s55, 0
	s_add_i32 s68, s72, s35
	global_load_lds_dwordx4 v[220:221], off
	v_lshl_add_u64 v[224:225], s[48:49], 0, v[130:131]
	s_mov_b32 m0, s68
	v_lshl_add_u64 v[226:227], s[78:79], 0, v[132:133]
	global_load_lds_dwordx4 v[224:225], off
	v_lshl_add_u64 v[224:225], s[48:49], 0, v[134:135]
	s_add_i32 m0, s68, 0x2000
	v_lshl_add_u64 v[228:229], v[226:227], 0, s[12:13]
	global_load_lds_dwordx4 v[224:225], off
	s_mov_b32 m0, s56
	v_lshl_add_u64 v[224:225], s[78:79], 0, v[128:129]
	global_load_lds_dwordx4 v[224:225], off
	s_mov_b32 m0, s57
	s_nop 0
	global_load_lds_dwordx4 v[228:229], off
	s_waitcnt vmcnt(8) lgkmcnt(0)
	s_barrier
	v_mfma_f32_16x16x32_bf16 v[60:63], v[144:147], v[184:187], 0
	v_mfma_f32_16x16x32_bf16 v[56:59], v[160:163], v[184:187], 0
	v_mfma_f32_16x16x32_bf16 v[44:47], v[144:147], v[192:195], 0
	v_mfma_f32_16x16x32_bf16 v[40:43], v[160:163], v[192:195], 0
	v_mfma_f32_16x16x32_bf16 v[28:31], v[144:147], v[200:203], 0
	v_mfma_f32_16x16x32_bf16 v[24:27], v[160:163], v[200:203], 0
	v_mfma_f32_16x16x32_bf16 v[12:15], v[144:147], v[208:211], 0
	v_mfma_f32_16x16x32_bf16 v[8:11], v[160:163], v[208:211], 0
	v_mfma_f32_16x16x32_bf16 v[60:63], v[156:159], v[188:191], v[60:63]
	v_mfma_f32_16x16x32_bf16 v[56:59], v[164:167], v[188:191], v[56:59]
	v_mfma_f32_16x16x32_bf16 v[44:47], v[156:159], v[196:199], v[44:47]
	v_mfma_f32_16x16x32_bf16 v[40:43], v[164:167], v[196:199], v[40:43]
	v_mfma_f32_16x16x32_bf16 v[28:31], v[156:159], v[204:207], v[28:31]
	v_mfma_f32_16x16x32_bf16 v[24:27], v[164:167], v[204:207], v[24:27]
	v_mfma_f32_16x16x32_bf16 v[12:15], v[156:159], v[212:215], v[12:15]
	v_mfma_f32_16x16x32_bf16 v[8:11], v[164:167], v[212:215], v[8:11]
	v_mfma_f32_16x16x32_bf16 v[52:55], v[168:171], v[184:187], 0
	v_mfma_f32_16x16x32_bf16 v[48:51], v[176:179], v[184:187], 0
	v_mfma_f32_16x16x32_bf16 v[36:39], v[168:171], v[192:195], 0
	v_mfma_f32_16x16x32_bf16 v[32:35], v[176:179], v[192:195], 0
	v_mfma_f32_16x16x32_bf16 v[20:23], v[168:171], v[200:203], 0
	v_mfma_f32_16x16x32_bf16 v[16:19], v[176:179], v[200:203], 0
	v_mfma_f32_16x16x32_bf16 v[4:7], v[168:171], v[208:211], 0
	v_mfma_f32_16x16x32_bf16 v[0:3], v[176:179], v[208:211], 0
	v_mfma_f32_16x16x32_bf16 v[52:55], v[172:175], v[188:191], v[52:55]
	v_mfma_f32_16x16x32_bf16 v[48:51], v[180:183], v[188:191], v[48:51]
	v_mfma_f32_16x16x32_bf16 v[36:39], v[172:175], v[196:199], v[36:39]
	v_mfma_f32_16x16x32_bf16 v[32:35], v[180:183], v[196:199], v[32:35]
	v_mfma_f32_16x16x32_bf16 v[20:23], v[172:175], v[204:207], v[20:23]
	v_mfma_f32_16x16x32_bf16 v[16:19], v[180:183], v[204:207], v[16:19]
	v_mfma_f32_16x16x32_bf16 v[4:7], v[172:175], v[212:215], v[4:7]
	v_mfma_f32_16x16x32_bf16 v[0:3], v[180:183], v[212:215], v[0:3]
	s_barrier
	s_add_i32 s48, 0, 0x18000
	v_add_u32_e32 v155, s48, v149
	s_add_i32 s68, 0, 0x1c000
	ds_read_b128 v[144:147], v155
	ds_read_b128 v[156:159], v155 offset:1024
	ds_read_b128 v[160:163], v155 offset:2048
	ds_read_b128 v[164:167], v155 offset:3072
	v_add_u32_e32 v155, s68, v149
	ds_read_b128 v[168:171], v155
	ds_read_b128 v[172:175], v155 offset:1024
	ds_read_b128 v[176:179], v155 offset:2048
	ds_read_b128 v[180:183], v155 offset:3072
	s_mov_b32 m0, s58
	v_lshl_add_u64 v[228:229], v[224:225], 0, s[8:9]
	ds_read_b128 v[184:187], v153 offset:32768
	ds_read_b128 v[188:191], v153 offset:33792
	ds_read_b128 v[192:195], v153 offset:34816
	ds_read_b128 v[196:199], v153 offset:35840
	ds_read_b128 v[200:203], v153 offset:36864
	ds_read_b128 v[204:207], v153 offset:37888
	ds_read_b128 v[208:211], v153 offset:38912
	ds_read_b128 v[212:215], v153 offset:39936
	global_load_lds_dwordx4 v[228:229], off
	s_mov_b32 m0, s59
	v_lshl_add_u64 v[228:229], v[226:227], 0, s[14:15]
	global_load_lds_dwordx4 v[228:229], off
	s_waitcnt vmcnt(8) lgkmcnt(0)
	s_barrier
	v_mfma_f32_16x16x32_bf16 v[124:127], v[144:147], v[184:187], v[124:127]
	v_mfma_f32_16x16x32_bf16 v[120:123], v[160:163], v[184:187], v[120:123]
	v_mfma_f32_16x16x32_bf16 v[108:111], v[144:147], v[192:195], v[108:111]
	v_mfma_f32_16x16x32_bf16 v[104:107], v[160:163], v[192:195], v[104:107]
	v_mfma_f32_16x16x32_bf16 v[92:95], v[144:147], v[200:203], v[92:95]
	v_mfma_f32_16x16x32_bf16 v[88:91], v[160:163], v[200:203], v[88:91]
	v_mfma_f32_16x16x32_bf16 v[76:79], v[144:147], v[208:211], v[76:79]
	v_mfma_f32_16x16x32_bf16 v[72:75], v[160:163], v[208:211], v[72:75]
	v_mfma_f32_16x16x32_bf16 v[124:127], v[156:159], v[188:191], v[124:127]
	v_mfma_f32_16x16x32_bf16 v[120:123], v[164:167], v[188:191], v[120:123]
	v_mfma_f32_16x16x32_bf16 v[108:111], v[156:159], v[196:199], v[108:111]
	v_mfma_f32_16x16x32_bf16 v[104:107], v[164:167], v[196:199], v[104:107]
	v_mfma_f32_16x16x32_bf16 v[92:95], v[156:159], v[204:207], v[92:95]
	v_mfma_f32_16x16x32_bf16 v[88:91], v[164:167], v[204:207], v[88:91]
	v_mfma_f32_16x16x32_bf16 v[76:79], v[156:159], v[212:215], v[76:79]
	v_mfma_f32_16x16x32_bf16 v[72:75], v[164:167], v[212:215], v[72:75]
	v_mfma_f32_16x16x32_bf16 v[116:119], v[168:171], v[184:187], v[116:119]
	v_mfma_f32_16x16x32_bf16 v[112:115], v[176:179], v[184:187], v[112:115]
	v_mfma_f32_16x16x32_bf16 v[100:103], v[168:171], v[192:195], v[100:103]
	v_mfma_f32_16x16x32_bf16 v[96:99], v[176:179], v[192:195], v[96:99]
	v_mfma_f32_16x16x32_bf16 v[84:87], v[168:171], v[200:203], v[84:87]
	v_mfma_f32_16x16x32_bf16 v[80:83], v[176:179], v[200:203], v[80:83]
	v_mfma_f32_16x16x32_bf16 v[68:71], v[168:171], v[208:211], v[68:71]
	v_mfma_f32_16x16x32_bf16 v[64:67], v[176:179], v[208:211], v[64:67]
	v_mfma_f32_16x16x32_bf16 v[116:119], v[172:175], v[188:191], v[116:119]
	v_mfma_f32_16x16x32_bf16 v[112:115], v[180:183], v[188:191], v[112:115]
	v_mfma_f32_16x16x32_bf16 v[100:103], v[172:175], v[196:199], v[100:103]
	v_mfma_f32_16x16x32_bf16 v[96:99], v[180:183], v[196:199], v[96:99]
	v_mfma_f32_16x16x32_bf16 v[84:87], v[172:175], v[204:207], v[84:87]
	v_mfma_f32_16x16x32_bf16 v[80:83], v[180:183], v[204:207], v[80:83]
	v_mfma_f32_16x16x32_bf16 v[68:71], v[172:175], v[212:215], v[68:71]
	v_mfma_f32_16x16x32_bf16 v[64:67], v[180:183], v[212:215], v[64:67]
	s_barrier
	s_add_i32 s48, s48, s35
	v_lshl_add_u64 v[216:217], v[216:217], 0, s[24:25]
	s_mov_b32 m0, s48
	ds_read_b128 v[184:187], v153 offset:49152
	ds_read_b128 v[188:191], v153 offset:50176
	ds_read_b128 v[192:195], v153 offset:51200
	ds_read_b128 v[196:199], v153 offset:52224
	ds_read_b128 v[200:203], v153 offset:53248
	ds_read_b128 v[204:207], v153 offset:54272
	ds_read_b128 v[208:211], v153 offset:55296
	ds_read_b128 v[212:215], v153 offset:56320
	global_load_lds_dwordx4 v[216:217], off
	s_add_i32 m0, s48, 0x2000
	s_add_u32 s48, s54, 0x40080
	v_lshl_add_u64 v[216:217], v[220:221], 0, s[24:25]
	s_addc_u32 s49, s55, 0
	s_add_i32 s54, s68, s35
	global_load_lds_dwordx4 v[216:217], off
	s_mov_b32 m0, s54
	v_lshl_add_u64 v[216:217], s[48:49], 0, v[130:131]
	global_load_lds_dwordx4 v[216:217], off
	s_add_i32 m0, s54, 0x2000
	v_lshl_add_u64 v[216:217], s[48:49], 0, v[134:135]
	global_load_lds_dwordx4 v[216:217], off
	s_mov_b32 m0, s61
	v_lshl_add_u64 v[216:217], v[224:225], 0, s[24:25]
	global_load_lds_dwordx4 v[216:217], off
	s_mov_b32 m0, s62
	v_lshl_add_u64 v[216:217], v[226:227], 0, s[36:37]
	global_load_lds_dwordx4 v[216:217], off
	s_waitcnt vmcnt(8) lgkmcnt(0)
	s_barrier
	v_mfma_f32_16x16x32_bf16 v[60:63], v[144:147], v[184:187], v[60:63]
	v_mfma_f32_16x16x32_bf16 v[56:59], v[160:163], v[184:187], v[56:59]
	v_mfma_f32_16x16x32_bf16 v[44:47], v[144:147], v[192:195], v[44:47]
	v_mfma_f32_16x16x32_bf16 v[40:43], v[160:163], v[192:195], v[40:43]
	v_mfma_f32_16x16x32_bf16 v[28:31], v[144:147], v[200:203], v[28:31]
	v_mfma_f32_16x16x32_bf16 v[24:27], v[160:163], v[200:203], v[24:27]
	v_mfma_f32_16x16x32_bf16 v[12:15], v[144:147], v[208:211], v[12:15]
	v_mfma_f32_16x16x32_bf16 v[8:11], v[160:163], v[208:211], v[8:11]
	v_mfma_f32_16x16x32_bf16 v[60:63], v[156:159], v[188:191], v[60:63]
	v_mfma_f32_16x16x32_bf16 v[56:59], v[164:167], v[188:191], v[56:59]
	v_mfma_f32_16x16x32_bf16 v[44:47], v[156:159], v[196:199], v[44:47]
	v_mfma_f32_16x16x32_bf16 v[40:43], v[164:167], v[196:199], v[40:43]
	v_mfma_f32_16x16x32_bf16 v[28:31], v[156:159], v[204:207], v[28:31]
	v_mfma_f32_16x16x32_bf16 v[24:27], v[164:167], v[204:207], v[24:27]
	v_mfma_f32_16x16x32_bf16 v[12:15], v[156:159], v[212:215], v[12:15]
	v_mfma_f32_16x16x32_bf16 v[8:11], v[164:167], v[212:215], v[8:11]
	v_mfma_f32_16x16x32_bf16 v[52:55], v[168:171], v[184:187], v[52:55]
	v_mfma_f32_16x16x32_bf16 v[48:51], v[176:179], v[184:187], v[48:51]
	v_mfma_f32_16x16x32_bf16 v[36:39], v[168:171], v[192:195], v[36:39]
	v_mfma_f32_16x16x32_bf16 v[32:35], v[176:179], v[192:195], v[32:35]
	v_mfma_f32_16x16x32_bf16 v[20:23], v[168:171], v[200:203], v[20:23]
	v_mfma_f32_16x16x32_bf16 v[16:19], v[176:179], v[200:203], v[16:19]
	v_mfma_f32_16x16x32_bf16 v[4:7], v[168:171], v[208:211], v[4:7]
	v_mfma_f32_16x16x32_bf16 v[0:3], v[176:179], v[208:211], v[0:3]
	v_mfma_f32_16x16x32_bf16 v[52:55], v[172:175], v[188:191], v[52:55]
	v_mfma_f32_16x16x32_bf16 v[48:51], v[180:183], v[188:191], v[48:51]
	v_mfma_f32_16x16x32_bf16 v[36:39], v[172:175], v[196:199], v[36:39]
	v_mfma_f32_16x16x32_bf16 v[32:35], v[180:183], v[196:199], v[32:35]
	v_mfma_f32_16x16x32_bf16 v[20:23], v[172:175], v[204:207], v[20:23]
	v_mfma_f32_16x16x32_bf16 v[16:19], v[180:183], v[204:207], v[16:19]
	v_mfma_f32_16x16x32_bf16 v[4:7], v[172:175], v[212:215], v[4:7]
	v_mfma_f32_16x16x32_bf16 v[0:3], v[180:183], v[212:215], v[0:3]
	s_barrier
	s_add_i32 s76, s76, 2
	s_add_u32 s51, s51, 0x100
	s_addc_u32 s75, s75, 0
	s_cmp_gt_u32 s76, 13
	s_mov_b64 s[48:49], s[52:53]
.LBB0_466:
	ds_read_b128 v[144:147], v151
	ds_read_b128 v[156:159], v151 offset:1024
	ds_read_b128 v[160:163], v151 offset:2048
	ds_read_b128 v[164:167], v151 offset:3072
	ds_read_b128 v[168:171], v152
	ds_read_b128 v[172:175], v152 offset:1024
	ds_read_b128 v[176:179], v152 offset:2048
	ds_read_b128 v[180:183], v152 offset:3072
	s_add_u32 s52, s48, 0x100
	s_addc_u32 s53, s49, 0
	s_cmp_eq_u32 s76, 12
	s_cselect_b32 s79, s47, s53
	s_cselect_b32 s78, s74, s52
	s_cselect_b32 s55, s41, s75
	s_cselect_b32 s54, s50, s51
	v_lshl_add_u64 v[216:217], s[48:49], 0, v[136:137]
	s_add_i32 m0, s56, 0xc000
	ds_read_b128 v[184:187], v153
	ds_read_b128 v[188:191], v153 offset:1024
	ds_read_b128 v[192:195], v153 offset:2048
	ds_read_b128 v[196:199], v153 offset:3072
	ds_read_b128 v[200:203], v153 offset:4096
	ds_read_b128 v[204:207], v153 offset:5120
	ds_read_b128 v[208:211], v153 offset:6144
	ds_read_b128 v[212:215], v153 offset:7168
	global_load_lds_dwordx4 v[216:217], off
	s_add_i32 m0, s56, 0xe000
	v_lshl_add_u64 v[216:217], s[48:49], 0, v[138:139]
	global_load_lds_dwordx4 v[216:217], off
	s_waitcnt vmcnt(8) lgkmcnt(0)
	s_barrier
	v_mfma_f32_16x16x32_bf16 v[124:127], v[144:147], v[184:187], v[124:127]
	v_mfma_f32_16x16x32_bf16 v[120:123], v[160:163], v[184:187], v[120:123]
	v_mfma_f32_16x16x32_bf16 v[108:111], v[144:147], v[192:195], v[108:111]
	v_mfma_f32_16x16x32_bf16 v[104:107], v[160:163], v[192:195], v[104:107]
	v_mfma_f32_16x16x32_bf16 v[92:95], v[144:147], v[200:203], v[92:95]
	v_mfma_f32_16x16x32_bf16 v[88:91], v[160:163], v[200:203], v[88:91]
	v_mfma_f32_16x16x32_bf16 v[76:79], v[144:147], v[208:211], v[76:79]
	v_mfma_f32_16x16x32_bf16 v[72:75], v[160:163], v[208:211], v[72:75]
	v_mfma_f32_16x16x32_bf16 v[124:127], v[156:159], v[188:191], v[124:127]
	v_mfma_f32_16x16x32_bf16 v[120:123], v[164:167], v[188:191], v[120:123]
	v_mfma_f32_16x16x32_bf16 v[108:111], v[156:159], v[196:199], v[108:111]
	v_mfma_f32_16x16x32_bf16 v[104:107], v[164:167], v[196:199], v[104:107]
	v_mfma_f32_16x16x32_bf16 v[92:95], v[156:159], v[204:207], v[92:95]
	v_mfma_f32_16x16x32_bf16 v[88:91], v[164:167], v[204:207], v[88:91]
	v_mfma_f32_16x16x32_bf16 v[76:79], v[156:159], v[212:215], v[76:79]
	v_mfma_f32_16x16x32_bf16 v[72:75], v[164:167], v[212:215], v[72:75]
	v_mfma_f32_16x16x32_bf16 v[116:119], v[168:171], v[184:187], v[116:119]
	v_mfma_f32_16x16x32_bf16 v[112:115], v[176:179], v[184:187], v[112:115]
	v_mfma_f32_16x16x32_bf16 v[100:103], v[168:171], v[192:195], v[100:103]
	v_mfma_f32_16x16x32_bf16 v[96:99], v[176:179], v[192:195], v[96:99]
	v_mfma_f32_16x16x32_bf16 v[84:87], v[168:171], v[200:203], v[84:87]
	v_mfma_f32_16x16x32_bf16 v[80:83], v[176:179], v[200:203], v[80:83]
	v_mfma_f32_16x16x32_bf16 v[68:71], v[168:171], v[208:211], v[68:71]
	v_mfma_f32_16x16x32_bf16 v[64:67], v[176:179], v[208:211], v[64:67]
	v_mfma_f32_16x16x32_bf16 v[116:119], v[172:175], v[188:191], v[116:119]
	v_mfma_f32_16x16x32_bf16 v[112:115], v[180:183], v[188:191], v[112:115]
	v_mfma_f32_16x16x32_bf16 v[100:103], v[172:175], v[196:199], v[100:103]
	v_mfma_f32_16x16x32_bf16 v[96:99], v[180:183], v[196:199], v[96:99]
	v_mfma_f32_16x16x32_bf16 v[84:87], v[172:175], v[204:207], v[84:87]
	v_mfma_f32_16x16x32_bf16 v[80:83], v[180:183], v[204:207], v[80:83]
	v_mfma_f32_16x16x32_bf16 v[68:71], v[172:175], v[212:215], v[68:71]
	v_mfma_f32_16x16x32_bf16 v[64:67], v[180:183], v[212:215], v[64:67]
	s_barrier
	s_add_i32 s48, s67, s35
	v_lshl_add_u64 v[216:217], s[54:55], 0, v[130:131]
	s_mov_b32 m0, s48
	ds_read_b128 v[184:187], v153 offset:16384
	ds_read_b128 v[188:191], v153 offset:17408
	ds_read_b128 v[192:195], v153 offset:18432
	ds_read_b128 v[196:199], v153 offset:19456
	ds_read_b128 v[200:203], v153 offset:20480
	ds_read_b128 v[204:207], v153 offset:21504
	ds_read_b128 v[208:211], v153 offset:22528
	ds_read_b128 v[212:215], v153 offset:23552
	global_load_lds_dwordx4 v[216:217], off
	s_add_i32 m0, s48, 0x2000
	s_add_u32 s48, s54, 0x40000
	v_lshl_add_u64 v[220:221], s[54:55], 0, v[134:135]
	s_addc_u32 s49, s55, 0
	s_add_i32 s68, s72, s35
	global_load_lds_dwordx4 v[220:221], off
	v_lshl_add_u64 v[224:225], s[48:49], 0, v[130:131]
	s_mov_b32 m0, s68
	v_lshl_add_u64 v[226:227], s[78:79], 0, v[132:133]
	global_load_lds_dwordx4 v[224:225], off
	v_lshl_add_u64 v[224:225], s[48:49], 0, v[134:135]
	s_add_i32 m0, s68, 0x2000
	v_lshl_add_u64 v[228:229], v[226:227], 0, s[12:13]
	global_load_lds_dwordx4 v[224:225], off
	s_mov_b32 m0, s56
	v_lshl_add_u64 v[224:225], s[78:79], 0, v[128:129]
	global_load_lds_dwordx4 v[224:225], off
	s_mov_b32 m0, s57
	s_nop 0
	global_load_lds_dwordx4 v[228:229], off
	s_waitcnt vmcnt(8) lgkmcnt(0)
	s_barrier
	v_mfma_f32_16x16x32_bf16 v[60:63], v[144:147], v[184:187], v[60:63]
	v_mfma_f32_16x16x32_bf16 v[56:59], v[160:163], v[184:187], v[56:59]
	v_mfma_f32_16x16x32_bf16 v[44:47], v[144:147], v[192:195], v[44:47]
	v_mfma_f32_16x16x32_bf16 v[40:43], v[160:163], v[192:195], v[40:43]
	v_mfma_f32_16x16x32_bf16 v[28:31], v[144:147], v[200:203], v[28:31]
	v_mfma_f32_16x16x32_bf16 v[24:27], v[160:163], v[200:203], v[24:27]
	v_mfma_f32_16x16x32_bf16 v[12:15], v[144:147], v[208:211], v[12:15]
	v_mfma_f32_16x16x32_bf16 v[8:11], v[160:163], v[208:211], v[8:11]
	v_mfma_f32_16x16x32_bf16 v[60:63], v[156:159], v[188:191], v[60:63]
	v_mfma_f32_16x16x32_bf16 v[56:59], v[164:167], v[188:191], v[56:59]
	v_mfma_f32_16x16x32_bf16 v[44:47], v[156:159], v[196:199], v[44:47]
	v_mfma_f32_16x16x32_bf16 v[40:43], v[164:167], v[196:199], v[40:43]
	v_mfma_f32_16x16x32_bf16 v[28:31], v[156:159], v[204:207], v[28:31]
	v_mfma_f32_16x16x32_bf16 v[24:27], v[164:167], v[204:207], v[24:27]
	v_mfma_f32_16x16x32_bf16 v[12:15], v[156:159], v[212:215], v[12:15]
	v_mfma_f32_16x16x32_bf16 v[8:11], v[164:167], v[212:215], v[8:11]
	v_mfma_f32_16x16x32_bf16 v[52:55], v[168:171], v[184:187], v[52:55]
	v_mfma_f32_16x16x32_bf16 v[48:51], v[176:179], v[184:187], v[48:51]
	v_mfma_f32_16x16x32_bf16 v[36:39], v[168:171], v[192:195], v[36:39]
	v_mfma_f32_16x16x32_bf16 v[32:35], v[176:179], v[192:195], v[32:35]
	v_mfma_f32_16x16x32_bf16 v[20:23], v[168:171], v[200:203], v[20:23]
	v_mfma_f32_16x16x32_bf16 v[16:19], v[176:179], v[200:203], v[16:19]
	v_mfma_f32_16x16x32_bf16 v[4:7], v[168:171], v[208:211], v[4:7]
	v_mfma_f32_16x16x32_bf16 v[0:3], v[176:179], v[208:211], v[0:3]
	v_mfma_f32_16x16x32_bf16 v[52:55], v[172:175], v[188:191], v[52:55]
	v_mfma_f32_16x16x32_bf16 v[48:51], v[180:183], v[188:191], v[48:51]
	v_mfma_f32_16x16x32_bf16 v[36:39], v[172:175], v[196:199], v[36:39]
	v_mfma_f32_16x16x32_bf16 v[32:35], v[180:183], v[196:199], v[32:35]
	v_mfma_f32_16x16x32_bf16 v[20:23], v[172:175], v[204:207], v[20:23]
	v_mfma_f32_16x16x32_bf16 v[16:19], v[180:183], v[204:207], v[16:19]
	v_mfma_f32_16x16x32_bf16 v[4:7], v[172:175], v[212:215], v[4:7]
	v_mfma_f32_16x16x32_bf16 v[0:3], v[180:183], v[212:215], v[0:3]
	s_barrier
	s_add_i32 s48, 0, 0x18000
	v_add_u32_e32 v155, s48, v149
	s_add_i32 s68, 0, 0x1c000
	ds_read_b128 v[144:147], v155
	ds_read_b128 v[156:159], v155 offset:1024
	ds_read_b128 v[160:163], v155 offset:2048
	ds_read_b128 v[164:167], v155 offset:3072
	v_add_u32_e32 v155, s68, v149
	ds_read_b128 v[168:171], v155
	ds_read_b128 v[172:175], v155 offset:1024
	ds_read_b128 v[176:179], v155 offset:2048
	ds_read_b128 v[180:183], v155 offset:3072
	s_mov_b32 m0, s58
	v_lshl_add_u64 v[228:229], v[224:225], 0, s[8:9]
	ds_read_b128 v[184:187], v153 offset:32768
	ds_read_b128 v[188:191], v153 offset:33792
	ds_read_b128 v[192:195], v153 offset:34816
	ds_read_b128 v[196:199], v153 offset:35840
	ds_read_b128 v[200:203], v153 offset:36864
	ds_read_b128 v[204:207], v153 offset:37888
	ds_read_b128 v[208:211], v153 offset:38912
	ds_read_b128 v[212:215], v153 offset:39936
	global_load_lds_dwordx4 v[228:229], off
	s_mov_b32 m0, s59
	v_lshl_add_u64 v[228:229], v[226:227], 0, s[14:15]
	global_load_lds_dwordx4 v[228:229], off
	s_waitcnt vmcnt(8) lgkmcnt(0)
	s_barrier
	v_mfma_f32_16x16x32_bf16 v[124:127], v[144:147], v[184:187], v[124:127]
	v_mfma_f32_16x16x32_bf16 v[120:123], v[160:163], v[184:187], v[120:123]
	v_mfma_f32_16x16x32_bf16 v[108:111], v[144:147], v[192:195], v[108:111]
	v_mfma_f32_16x16x32_bf16 v[104:107], v[160:163], v[192:195], v[104:107]
	v_mfma_f32_16x16x32_bf16 v[92:95], v[144:147], v[200:203], v[92:95]
	v_mfma_f32_16x16x32_bf16 v[88:91], v[160:163], v[200:203], v[88:91]
	v_mfma_f32_16x16x32_bf16 v[76:79], v[144:147], v[208:211], v[76:79]
	v_mfma_f32_16x16x32_bf16 v[72:75], v[160:163], v[208:211], v[72:75]
	v_mfma_f32_16x16x32_bf16 v[124:127], v[156:159], v[188:191], v[124:127]
	v_mfma_f32_16x16x32_bf16 v[120:123], v[164:167], v[188:191], v[120:123]
	v_mfma_f32_16x16x32_bf16 v[108:111], v[156:159], v[196:199], v[108:111]
	v_mfma_f32_16x16x32_bf16 v[104:107], v[164:167], v[196:199], v[104:107]
	v_mfma_f32_16x16x32_bf16 v[92:95], v[156:159], v[204:207], v[92:95]
	v_mfma_f32_16x16x32_bf16 v[88:91], v[164:167], v[204:207], v[88:91]
	v_mfma_f32_16x16x32_bf16 v[76:79], v[156:159], v[212:215], v[76:79]
	v_mfma_f32_16x16x32_bf16 v[72:75], v[164:167], v[212:215], v[72:75]
	v_mfma_f32_16x16x32_bf16 v[116:119], v[168:171], v[184:187], v[116:119]
	v_mfma_f32_16x16x32_bf16 v[112:115], v[176:179], v[184:187], v[112:115]
	v_mfma_f32_16x16x32_bf16 v[100:103], v[168:171], v[192:195], v[100:103]
	v_mfma_f32_16x16x32_bf16 v[96:99], v[176:179], v[192:195], v[96:99]
	v_mfma_f32_16x16x32_bf16 v[84:87], v[168:171], v[200:203], v[84:87]
	v_mfma_f32_16x16x32_bf16 v[80:83], v[176:179], v[200:203], v[80:83]
	v_mfma_f32_16x16x32_bf16 v[68:71], v[168:171], v[208:211], v[68:71]
	v_mfma_f32_16x16x32_bf16 v[64:67], v[176:179], v[208:211], v[64:67]
	v_mfma_f32_16x16x32_bf16 v[116:119], v[172:175], v[188:191], v[116:119]
	v_mfma_f32_16x16x32_bf16 v[112:115], v[180:183], v[188:191], v[112:115]
	v_mfma_f32_16x16x32_bf16 v[100:103], v[172:175], v[196:199], v[100:103]
	v_mfma_f32_16x16x32_bf16 v[96:99], v[180:183], v[196:199], v[96:99]
	v_mfma_f32_16x16x32_bf16 v[84:87], v[172:175], v[204:207], v[84:87]
	v_mfma_f32_16x16x32_bf16 v[80:83], v[180:183], v[204:207], v[80:83]
	v_mfma_f32_16x16x32_bf16 v[68:71], v[172:175], v[212:215], v[68:71]
	v_mfma_f32_16x16x32_bf16 v[64:67], v[180:183], v[212:215], v[64:67]
	s_barrier
	s_add_i32 s48, s48, s35
	v_lshl_add_u64 v[216:217], v[216:217], 0, s[24:25]
	s_mov_b32 m0, s48
	ds_read_b128 v[184:187], v153 offset:49152
	ds_read_b128 v[188:191], v153 offset:50176
	ds_read_b128 v[192:195], v153 offset:51200
	ds_read_b128 v[196:199], v153 offset:52224
	ds_read_b128 v[200:203], v153 offset:53248
	ds_read_b128 v[204:207], v153 offset:54272
	ds_read_b128 v[208:211], v153 offset:55296
	ds_read_b128 v[212:215], v153 offset:56320
	global_load_lds_dwordx4 v[216:217], off
	s_add_i32 m0, s48, 0x2000
	s_add_u32 s48, s54, 0x40080
	v_lshl_add_u64 v[216:217], v[220:221], 0, s[24:25]
	s_addc_u32 s49, s55, 0
	s_add_i32 s54, s68, s35
	global_load_lds_dwordx4 v[216:217], off
	s_mov_b32 m0, s54
	v_lshl_add_u64 v[216:217], s[48:49], 0, v[130:131]
	global_load_lds_dwordx4 v[216:217], off
	s_add_i32 m0, s54, 0x2000
	v_lshl_add_u64 v[216:217], s[48:49], 0, v[134:135]
	global_load_lds_dwordx4 v[216:217], off
	s_mov_b32 m0, s61
	v_lshl_add_u64 v[216:217], v[224:225], 0, s[24:25]
	global_load_lds_dwordx4 v[216:217], off
	s_mov_b32 m0, s62
	v_lshl_add_u64 v[216:217], v[226:227], 0, s[36:37]
	global_load_lds_dwordx4 v[216:217], off
	s_waitcnt vmcnt(8) lgkmcnt(0)
	s_barrier
	v_mfma_f32_16x16x32_bf16 v[60:63], v[144:147], v[184:187], v[60:63]
	v_mfma_f32_16x16x32_bf16 v[56:59], v[160:163], v[184:187], v[56:59]
	v_mfma_f32_16x16x32_bf16 v[44:47], v[144:147], v[192:195], v[44:47]
	v_mfma_f32_16x16x32_bf16 v[40:43], v[160:163], v[192:195], v[40:43]
	v_mfma_f32_16x16x32_bf16 v[28:31], v[144:147], v[200:203], v[28:31]
	v_mfma_f32_16x16x32_bf16 v[24:27], v[160:163], v[200:203], v[24:27]
	v_mfma_f32_16x16x32_bf16 v[12:15], v[144:147], v[208:211], v[12:15]
	v_mfma_f32_16x16x32_bf16 v[8:11], v[160:163], v[208:211], v[8:11]
	v_mfma_f32_16x16x32_bf16 v[60:63], v[156:159], v[188:191], v[60:63]
	v_mfma_f32_16x16x32_bf16 v[56:59], v[164:167], v[188:191], v[56:59]
	v_mfma_f32_16x16x32_bf16 v[44:47], v[156:159], v[196:199], v[44:47]
	v_mfma_f32_16x16x32_bf16 v[40:43], v[164:167], v[196:199], v[40:43]
	v_mfma_f32_16x16x32_bf16 v[28:31], v[156:159], v[204:207], v[28:31]
	v_mfma_f32_16x16x32_bf16 v[24:27], v[164:167], v[204:207], v[24:27]
	v_mfma_f32_16x16x32_bf16 v[12:15], v[156:159], v[212:215], v[12:15]
	v_mfma_f32_16x16x32_bf16 v[8:11], v[164:167], v[212:215], v[8:11]
	v_mfma_f32_16x16x32_bf16 v[52:55], v[168:171], v[184:187], v[52:55]
	v_mfma_f32_16x16x32_bf16 v[48:51], v[176:179], v[184:187], v[48:51]
	v_mfma_f32_16x16x32_bf16 v[36:39], v[168:171], v[192:195], v[36:39]
	v_mfma_f32_16x16x32_bf16 v[32:35], v[176:179], v[192:195], v[32:35]
	v_mfma_f32_16x16x32_bf16 v[20:23], v[168:171], v[200:203], v[20:23]
	v_mfma_f32_16x16x32_bf16 v[16:19], v[176:179], v[200:203], v[16:19]
	v_mfma_f32_16x16x32_bf16 v[4:7], v[168:171], v[208:211], v[4:7]
	v_mfma_f32_16x16x32_bf16 v[0:3], v[176:179], v[208:211], v[0:3]
	v_mfma_f32_16x16x32_bf16 v[52:55], v[172:175], v[188:191], v[52:55]
	v_mfma_f32_16x16x32_bf16 v[48:51], v[180:183], v[188:191], v[48:51]
	v_mfma_f32_16x16x32_bf16 v[36:39], v[172:175], v[196:199], v[36:39]
	v_mfma_f32_16x16x32_bf16 v[32:35], v[180:183], v[196:199], v[32:35]
	v_mfma_f32_16x16x32_bf16 v[20:23], v[172:175], v[204:207], v[20:23]
	v_mfma_f32_16x16x32_bf16 v[16:19], v[180:183], v[204:207], v[16:19]
	v_mfma_f32_16x16x32_bf16 v[4:7], v[172:175], v[212:215], v[4:7]
	v_mfma_f32_16x16x32_bf16 v[0:3], v[180:183], v[212:215], v[0:3]
	s_barrier
	s_add_i32 s76, s76, 2
	s_add_u32 s51, s51, 0x100
	s_addc_u32 s75, s75, 0
	s_cmp_gt_u32 s76, 13
	s_mov_b64 s[48:49], s[52:53]
	s_cbranch_scc0 .LBB0_466

.LBB0_564:
	s_ashr_i32 s77, s76, 31
	s_lshl_b64 s[50:51], s[76:77], 19
	s_add_u32 s82, s49, s50
	s_addc_u32 s83, s53, s51
	s_and_b64 s[0:1], s[0:1], exec
	s_cselect_b32 s13, s83, s89
	s_cselect_b32 s77, s82, s88
	v_lshl_add_u64 v[92:93], s[84:85], 0, v[168:169]
	s_add_u32 vcc_lo, s88, 0x100
	v_lshl_add_u64 v[130:131], v[92:93], 0, s[86:87]
	s_addc_u32 vcc_hi, s89, 0
	s_mov_b32 s50, -2
	s_mov_b64 s[0:1], 0
	s_waitcnt vmcnt(0)
	ds_read_b128 v[132:135], v207
	ds_read_b128 v[136:139], v207 offset:1024
	ds_read_b128 v[140:143], v207 offset:2048
	ds_read_b128 v[144:147], v207 offset:3072
	ds_read_b128 v[148:151], v208
	ds_read_b128 v[152:155], v208 offset:1024
	ds_read_b128 v[156:159], v208 offset:2048
	ds_read_b128 v[174:177], v208 offset:3072
	s_add_u32 s51, s84, s0
	s_addc_u32 s68, s85, s1
	s_add_u32 s51, s51, 0x100
	s_addc_u32 s68, s68, 0
	s_add_u32 s69, vcc_lo, s0
	s_addc_u32 s70, vcc_hi, s1
	s_cmpk_eq_i32 s0, 0x700
	s_cselect_b32 s91, s79, s68
	s_cselect_b32 s90, s78, s51
	s_cselect_b32 s51, s81, s87
	s_cselect_b32 s71, s80, s86
	s_cselect_b32 s89, s13, s70
	s_cselect_b32 s88, s77, s69
	v_lshl_add_u64 v[160:161], v[92:93], 0, s[0:1]
	s_add_i32 m0, s59, 0xc000
	ds_read_b128 v[194:197], v209
	ds_read_b128 v[198:201], v209 offset:1024
	ds_read_b128 v[212:215], v209 offset:2048
	ds_read_b128 v[224:227], v209 offset:3072
	ds_read_b128 v[228:231], v209 offset:4096
	ds_read_b128 v[232:235], v209 offset:5120
	ds_read_b128 v[236:239], v209 offset:6144
	ds_read_b128 v[240:243], v209 offset:7168
	global_load_lds_dwordx4 v[160:161], off
	s_add_i32 m0, s59, 0xe000
	v_lshl_add_u64 v[160:161], v[130:131], 0, s[0:1]
	global_load_lds_dwordx4 v[160:161], off
	s_waitcnt vmcnt(8) lgkmcnt(0)
	s_barrier
	v_mfma_f32_16x16x32_bf16 v[126:129], v[132:135], v[194:197], 0
	v_mfma_f32_16x16x32_bf16 v[60:63], v[140:143], v[194:197], 0
	v_mfma_f32_16x16x32_bf16 v[118:121], v[132:135], v[212:215], 0
	v_mfma_f32_16x16x32_bf16 v[52:55], v[140:143], v[212:215], 0
	v_mfma_f32_16x16x32_bf16 v[110:113], v[132:135], v[228:231], 0
	v_mfma_f32_16x16x32_bf16 v[44:47], v[140:143], v[228:231], 0
	v_mfma_f32_16x16x32_bf16 v[94:97], v[132:135], v[236:239], 0
	v_mfma_f32_16x16x32_bf16 v[28:31], v[140:143], v[236:239], 0
	v_mfma_f32_16x16x32_bf16 v[126:129], v[136:139], v[198:201], v[126:129]
	v_mfma_f32_16x16x32_bf16 v[60:63], v[144:147], v[198:201], v[60:63]
	v_mfma_f32_16x16x32_bf16 v[118:121], v[136:139], v[224:227], v[118:121]
	v_mfma_f32_16x16x32_bf16 v[52:55], v[144:147], v[224:227], v[52:55]
	v_mfma_f32_16x16x32_bf16 v[110:113], v[136:139], v[232:235], v[110:113]
	v_mfma_f32_16x16x32_bf16 v[44:47], v[144:147], v[232:235], v[44:47]
	v_mfma_f32_16x16x32_bf16 v[94:97], v[136:139], v[240:243], v[94:97]
	v_mfma_f32_16x16x32_bf16 v[28:31], v[144:147], v[240:243], v[28:31]
	v_mfma_f32_16x16x32_bf16 v[122:125], v[148:151], v[194:197], 0
	v_mfma_f32_16x16x32_bf16 v[56:59], v[156:159], v[194:197], 0
	v_mfma_f32_16x16x32_bf16 v[114:117], v[148:151], v[212:215], 0
	v_mfma_f32_16x16x32_bf16 v[48:51], v[156:159], v[212:215], 0
	v_mfma_f32_16x16x32_bf16 v[102:105], v[148:151], v[228:231], 0
	v_mfma_f32_16x16x32_bf16 v[36:39], v[156:159], v[228:231], 0
	v_mfma_f32_16x16x32_bf16 v[88:91], v[148:151], v[236:239], 0
	v_mfma_f32_16x16x32_bf16 v[24:27], v[156:159], v[236:239], 0
	v_mfma_f32_16x16x32_bf16 v[122:125], v[152:155], v[198:201], v[122:125]
	v_mfma_f32_16x16x32_bf16 v[56:59], v[174:177], v[198:201], v[56:59]
	v_mfma_f32_16x16x32_bf16 v[114:117], v[152:155], v[224:227], v[114:117]
	v_mfma_f32_16x16x32_bf16 v[48:51], v[174:177], v[224:227], v[48:51]
	v_mfma_f32_16x16x32_bf16 v[102:105], v[152:155], v[232:235], v[102:105]
	v_mfma_f32_16x16x32_bf16 v[36:39], v[174:177], v[232:235], v[36:39]
	v_mfma_f32_16x16x32_bf16 v[88:91], v[152:155], v[240:243], v[88:91]
	v_mfma_f32_16x16x32_bf16 v[24:27], v[174:177], v[240:243], v[24:27]
	s_barrier
	s_add_i32 s68, s95, s57
	v_lshl_add_u64 v[160:161], s[88:89], 0, v[164:165]
	s_mov_b32 m0, s68
	ds_read_b128 v[194:197], v209 offset:16384
	ds_read_b128 v[198:201], v209 offset:17408
	ds_read_b128 v[212:215], v209 offset:18432
	ds_read_b128 v[224:227], v209 offset:19456
	ds_read_b128 v[228:231], v209 offset:20480
	ds_read_b128 v[232:235], v209 offset:21504
	ds_read_b128 v[236:239], v209 offset:22528
	ds_read_b128 v[240:243], v209 offset:23552
	global_load_lds_dwordx4 v[160:161], off
	s_add_i32 m0, s68, 0x2000
	s_add_u32 s68, s88, 0x40000
	v_lshl_add_u64 v[216:217], s[88:89], 0, v[166:167]
	s_addc_u32 s69, s89, 0
	s_add_i32 s70, s96, s57
	global_load_lds_dwordx4 v[216:217], off
	s_mov_b32 m0, s70
	v_lshl_add_u64 v[220:221], s[68:69], 0, v[164:165]
	global_load_lds_dwordx4 v[220:221], off
	s_add_i32 m0, s70, 0x2000
	v_lshl_add_u64 v[220:221], s[68:69], 0, v[166:167]
	s_add_u32 s68, s90, s71
	global_load_lds_dwordx4 v[220:221], off
	v_lshl_add_u64 v[220:221], s[90:91], 0, v[162:163]
	s_mov_b32 m0, s59
	s_addc_u32 s69, s91, s51
	global_load_lds_dwordx4 v[220:221], off
	s_mov_b32 m0, s61
	v_lshl_add_u64 v[244:245], s[68:69], 0, v[162:163]
	global_load_lds_dwordx4 v[244:245], off
	s_waitcnt vmcnt(8) lgkmcnt(0)
	s_barrier
	v_mfma_f32_16x16x32_bf16 v[84:87], v[132:135], v[194:197], 0
	v_mfma_f32_16x16x32_bf16 v[20:23], v[140:143], v[194:197], 0
	v_mfma_f32_16x16x32_bf16 v[76:79], v[132:135], v[212:215], 0
	v_mfma_f32_16x16x32_bf16 v[12:15], v[140:143], v[212:215], 0
	v_mfma_f32_16x16x32_bf16 v[68:71], v[132:135], v[228:231], 0
	v_mfma_f32_16x16x32_bf16 v[4:7], v[140:143], v[228:231], 0
	v_mfma_f32_16x16x32_bf16 v[106:109], v[132:135], v[236:239], 0
	v_mfma_f32_16x16x32_bf16 v[40:43], v[140:143], v[236:239], 0
	v_mfma_f32_16x16x32_bf16 v[84:87], v[136:139], v[198:201], v[84:87]
	v_mfma_f32_16x16x32_bf16 v[20:23], v[144:147], v[198:201], v[20:23]
	v_mfma_f32_16x16x32_bf16 v[76:79], v[136:139], v[224:227], v[76:79]
	v_mfma_f32_16x16x32_bf16 v[12:15], v[144:147], v[224:227], v[12:15]
	v_mfma_f32_16x16x32_bf16 v[68:71], v[136:139], v[232:235], v[68:71]
	v_mfma_f32_16x16x32_bf16 v[4:7], v[144:147], v[232:235], v[4:7]
	v_mfma_f32_16x16x32_bf16 v[106:109], v[136:139], v[240:243], v[106:109]
	v_mfma_f32_16x16x32_bf16 v[40:43], v[144:147], v[240:243], v[40:43]
	v_mfma_f32_16x16x32_bf16 v[80:83], v[148:151], v[194:197], 0
	v_mfma_f32_16x16x32_bf16 v[16:19], v[156:159], v[194:197], 0
	v_mfma_f32_16x16x32_bf16 v[72:75], v[148:151], v[212:215], 0
	v_mfma_f32_16x16x32_bf16 v[8:11], v[156:159], v[212:215], 0
	v_mfma_f32_16x16x32_bf16 v[64:67], v[148:151], v[228:231], 0
	v_mfma_f32_16x16x32_bf16 v[0:3], v[156:159], v[228:231], 0
	v_mfma_f32_16x16x32_bf16 v[98:101], v[148:151], v[236:239], 0
	v_mfma_f32_16x16x32_bf16 v[32:35], v[156:159], v[236:239], 0
	v_mfma_f32_16x16x32_bf16 v[80:83], v[152:155], v[198:201], v[80:83]
	v_mfma_f32_16x16x32_bf16 v[16:19], v[174:177], v[198:201], v[16:19]
	v_mfma_f32_16x16x32_bf16 v[72:75], v[152:155], v[224:227], v[72:75]
	v_mfma_f32_16x16x32_bf16 v[8:11], v[174:177], v[224:227], v[8:11]
	v_mfma_f32_16x16x32_bf16 v[64:67], v[152:155], v[232:235], v[64:67]
	v_mfma_f32_16x16x32_bf16 v[0:3], v[174:177], v[232:235], v[0:3]
	v_mfma_f32_16x16x32_bf16 v[98:101], v[152:155], v[240:243], v[98:101]
	v_mfma_f32_16x16x32_bf16 v[32:35], v[174:177], v[240:243], v[32:35]
	s_barrier
	s_add_i32 s70, 0, 0x18000
	s_add_i32 s14, 0, 0x1c000
	v_add_u32_e32 v144, s70, v203
	v_add_u32_e32 v174, s14, v203
	ds_read_b128 v[132:135], v144
	ds_read_b128 v[136:139], v144 offset:1024
	ds_read_b128 v[140:143], v144 offset:2048
	ds_read_b128 v[144:147], v144 offset:3072
	ds_read_b128 v[148:151], v174
	ds_read_b128 v[152:155], v174 offset:1024
	ds_read_b128 v[156:159], v174 offset:2048
	ds_read_b128 v[174:177], v174 offset:3072
	s_add_u32 s68, s90, 0x2000
	s_addc_u32 s69, s91, 0
	v_lshl_add_u64 v[246:247], s[68:69], 0, v[162:163]
	s_add_u32 s68, s68, s71
	s_mov_b32 m0, s63
	s_addc_u32 s69, s69, s51
	ds_read_b128 v[194:197], v209 offset:32768
	ds_read_b128 v[198:201], v209 offset:33792
	ds_read_b128 v[212:215], v209 offset:34816
	ds_read_b128 v[224:227], v209 offset:35840
	ds_read_b128 v[228:231], v209 offset:36864
	ds_read_b128 v[232:235], v209 offset:37888
	ds_read_b128 v[236:239], v209 offset:38912
	ds_read_b128 v[240:243], v209 offset:39936
	global_load_lds_dwordx4 v[246:247], off
	s_mov_b32 m0, s67
	v_lshl_add_u64 v[246:247], s[68:69], 0, v[162:163]
	global_load_lds_dwordx4 v[246:247], off
	s_waitcnt vmcnt(8) lgkmcnt(0)
	s_barrier
	v_mfma_f32_16x16x32_bf16 v[126:129], v[132:135], v[194:197], v[126:129]
	v_mfma_f32_16x16x32_bf16 v[60:63], v[140:143], v[194:197], v[60:63]
	v_mfma_f32_16x16x32_bf16 v[118:121], v[132:135], v[212:215], v[118:121]
	v_mfma_f32_16x16x32_bf16 v[52:55], v[140:143], v[212:215], v[52:55]
	v_mfma_f32_16x16x32_bf16 v[110:113], v[132:135], v[228:231], v[110:113]
	v_mfma_f32_16x16x32_bf16 v[44:47], v[140:143], v[228:231], v[44:47]
	v_mfma_f32_16x16x32_bf16 v[94:97], v[132:135], v[236:239], v[94:97]
	v_mfma_f32_16x16x32_bf16 v[28:31], v[140:143], v[236:239], v[28:31]
	v_mfma_f32_16x16x32_bf16 v[126:129], v[136:139], v[198:201], v[126:129]
	v_mfma_f32_16x16x32_bf16 v[60:63], v[144:147], v[198:201], v[60:63]
	v_mfma_f32_16x16x32_bf16 v[118:121], v[136:139], v[224:227], v[118:121]
	v_mfma_f32_16x16x32_bf16 v[52:55], v[144:147], v[224:227], v[52:55]
	v_mfma_f32_16x16x32_bf16 v[110:113], v[136:139], v[232:235], v[110:113]
	v_mfma_f32_16x16x32_bf16 v[44:47], v[144:147], v[232:235], v[44:47]
	v_mfma_f32_16x16x32_bf16 v[94:97], v[136:139], v[240:243], v[94:97]
	v_mfma_f32_16x16x32_bf16 v[28:31], v[144:147], v[240:243], v[28:31]
	v_mfma_f32_16x16x32_bf16 v[122:125], v[148:151], v[194:197], v[122:125]
	v_mfma_f32_16x16x32_bf16 v[56:59], v[156:159], v[194:197], v[56:59]
	v_mfma_f32_16x16x32_bf16 v[114:117], v[148:151], v[212:215], v[114:117]
	v_mfma_f32_16x16x32_bf16 v[48:51], v[156:159], v[212:215], v[48:51]
	v_mfma_f32_16x16x32_bf16 v[102:105], v[148:151], v[228:231], v[102:105]
	v_mfma_f32_16x16x32_bf16 v[36:39], v[156:159], v[228:231], v[36:39]
	v_mfma_f32_16x16x32_bf16 v[88:91], v[148:151], v[236:239], v[88:91]
	v_mfma_f32_16x16x32_bf16 v[24:27], v[156:159], v[236:239], v[24:27]
	v_mfma_f32_16x16x32_bf16 v[122:125], v[152:155], v[198:201], v[122:125]
	v_mfma_f32_16x16x32_bf16 v[56:59], v[174:177], v[198:201], v[56:59]
	v_mfma_f32_16x16x32_bf16 v[114:117], v[152:155], v[224:227], v[114:117]
	v_mfma_f32_16x16x32_bf16 v[48:51], v[174:177], v[224:227], v[48:51]
	v_mfma_f32_16x16x32_bf16 v[102:105], v[152:155], v[232:235], v[102:105]
	v_mfma_f32_16x16x32_bf16 v[36:39], v[174:177], v[232:235], v[36:39]
	v_mfma_f32_16x16x32_bf16 v[88:91], v[152:155], v[240:243], v[88:91]
	v_mfma_f32_16x16x32_bf16 v[24:27], v[174:177], v[240:243], v[24:27]
	s_barrier
	s_add_i32 s15, s70, s57
	v_lshl_add_u64 v[160:161], v[160:161], 0, s[22:23]
	s_mov_b32 m0, s15
	ds_read_b128 v[194:197], v209 offset:49152
	ds_read_b128 v[198:201], v209 offset:50176
	ds_read_b128 v[212:215], v209 offset:51200
	ds_read_b128 v[224:227], v209 offset:52224
	ds_read_b128 v[228:231], v209 offset:53248
	ds_read_b128 v[232:235], v209 offset:54272
	ds_read_b128 v[236:239], v209 offset:55296
	ds_read_b128 v[240:243], v209 offset:56320
	global_load_lds_dwordx4 v[160:161], off
	s_add_i32 m0, s15, 0x2000
	s_add_u32 s68, s88, 0x40080
	v_lshl_add_u64 v[160:161], v[216:217], 0, s[22:23]
	s_addc_u32 s69, s89, 0
	s_add_i32 s14, s14, s57
	global_load_lds_dwordx4 v[160:161], off
	s_mov_b32 m0, s14
	v_lshl_add_u64 v[160:161], s[68:69], 0, v[164:165]
	global_load_lds_dwordx4 v[160:161], off
	s_add_i32 m0, s14, 0x2000
	v_lshl_add_u64 v[160:161], s[68:69], 0, v[166:167]
	global_load_lds_dwordx4 v[160:161], off
	s_mov_b32 m0, s75
	v_lshl_add_u64 v[160:161], v[220:221], 0, s[22:23]
	global_load_lds_dwordx4 v[160:161], off
	s_mov_b32 m0, s92
	v_lshl_add_u64 v[160:161], v[244:245], 0, s[22:23]
	global_load_lds_dwordx4 v[160:161], off
	s_waitcnt vmcnt(8) lgkmcnt(0)
	s_barrier
	v_mfma_f32_16x16x32_bf16 v[84:87], v[132:135], v[194:197], v[84:87]
	v_mfma_f32_16x16x32_bf16 v[20:23], v[140:143], v[194:197], v[20:23]
	v_mfma_f32_16x16x32_bf16 v[76:79], v[132:135], v[212:215], v[76:79]
	v_mfma_f32_16x16x32_bf16 v[12:15], v[140:143], v[212:215], v[12:15]
	v_mfma_f32_16x16x32_bf16 v[68:71], v[132:135], v[228:231], v[68:71]
	v_mfma_f32_16x16x32_bf16 v[4:7], v[140:143], v[228:231], v[4:7]
	v_mfma_f32_16x16x32_bf16 v[106:109], v[132:135], v[236:239], v[106:109]
	v_mfma_f32_16x16x32_bf16 v[40:43], v[140:143], v[236:239], v[40:43]
	v_mfma_f32_16x16x32_bf16 v[84:87], v[136:139], v[198:201], v[84:87]
	v_mfma_f32_16x16x32_bf16 v[20:23], v[144:147], v[198:201], v[20:23]
	v_mfma_f32_16x16x32_bf16 v[76:79], v[136:139], v[224:227], v[76:79]
	v_mfma_f32_16x16x32_bf16 v[12:15], v[144:147], v[224:227], v[12:15]
	v_mfma_f32_16x16x32_bf16 v[68:71], v[136:139], v[232:235], v[68:71]
	v_mfma_f32_16x16x32_bf16 v[4:7], v[144:147], v[232:235], v[4:7]
	v_mfma_f32_16x16x32_bf16 v[106:109], v[136:139], v[240:243], v[106:109]
	v_mfma_f32_16x16x32_bf16 v[40:43], v[144:147], v[240:243], v[40:43]
	v_mfma_f32_16x16x32_bf16 v[80:83], v[148:151], v[194:197], v[80:83]
	v_mfma_f32_16x16x32_bf16 v[16:19], v[156:159], v[194:197], v[16:19]
	v_mfma_f32_16x16x32_bf16 v[72:75], v[148:151], v[212:215], v[72:75]
	v_mfma_f32_16x16x32_bf16 v[8:11], v[156:159], v[212:215], v[8:11]
	v_mfma_f32_16x16x32_bf16 v[64:67], v[148:151], v[228:231], v[64:67]
	v_mfma_f32_16x16x32_bf16 v[0:3], v[156:159], v[228:231], v[0:3]
	v_mfma_f32_16x16x32_bf16 v[98:101], v[148:151], v[236:239], v[98:101]
	v_mfma_f32_16x16x32_bf16 v[32:35], v[156:159], v[236:239], v[32:35]
	v_mfma_f32_16x16x32_bf16 v[80:83], v[152:155], v[198:201], v[80:83]
	v_mfma_f32_16x16x32_bf16 v[16:19], v[174:177], v[198:201], v[16:19]
	v_mfma_f32_16x16x32_bf16 v[72:75], v[152:155], v[224:227], v[72:75]
	v_mfma_f32_16x16x32_bf16 v[8:11], v[174:177], v[224:227], v[8:11]
	v_mfma_f32_16x16x32_bf16 v[64:67], v[152:155], v[232:235], v[64:67]
	v_mfma_f32_16x16x32_bf16 v[0:3], v[174:177], v[232:235], v[0:3]
	v_mfma_f32_16x16x32_bf16 v[98:101], v[152:155], v[240:243], v[98:101]
	v_mfma_f32_16x16x32_bf16 v[32:35], v[174:177], v[240:243], v[32:35]
	s_barrier
	s_add_i32 s50, s50, 2
	s_add_u32 s0, s0, 0x100
	s_addc_u32 s1, s1, 0
	s_cmp_gt_u32 s50, 13
.LBB0_565:
	ds_read_b128 v[132:135], v207
	ds_read_b128 v[136:139], v207 offset:1024
	ds_read_b128 v[140:143], v207 offset:2048
	ds_read_b128 v[144:147], v207 offset:3072
	ds_read_b128 v[148:151], v208
	ds_read_b128 v[152:155], v208 offset:1024
	ds_read_b128 v[156:159], v208 offset:2048
	ds_read_b128 v[174:177], v208 offset:3072
	s_add_u32 s51, s84, s0
	s_addc_u32 s68, s85, s1
	s_add_u32 s51, s51, 0x100
	s_addc_u32 s68, s68, 0
	s_add_u32 s69, vcc_lo, s0
	s_addc_u32 s70, vcc_hi, s1
	s_cmpk_eq_i32 s0, 0x700
	s_cselect_b32 s91, s79, s68
	s_cselect_b32 s90, s78, s51
	s_cselect_b32 s51, s81, s87
	s_cselect_b32 s71, s80, s86
	s_cselect_b32 s89, s13, s70
	s_cselect_b32 s88, s77, s69
	v_lshl_add_u64 v[160:161], v[92:93], 0, s[0:1]
	s_add_i32 m0, s59, 0xc000
	ds_read_b128 v[194:197], v209
	ds_read_b128 v[198:201], v209 offset:1024
	ds_read_b128 v[212:215], v209 offset:2048
	ds_read_b128 v[224:227], v209 offset:3072
	ds_read_b128 v[228:231], v209 offset:4096
	ds_read_b128 v[232:235], v209 offset:5120
	ds_read_b128 v[236:239], v209 offset:6144
	ds_read_b128 v[240:243], v209 offset:7168
	global_load_lds_dwordx4 v[160:161], off
	s_add_i32 m0, s59, 0xe000
	v_lshl_add_u64 v[160:161], v[130:131], 0, s[0:1]
	global_load_lds_dwordx4 v[160:161], off
	s_waitcnt vmcnt(8) lgkmcnt(0)
	s_barrier
	v_mfma_f32_16x16x32_bf16 v[126:129], v[132:135], v[194:197], v[126:129]
	v_mfma_f32_16x16x32_bf16 v[60:63], v[140:143], v[194:197], v[60:63]
	v_mfma_f32_16x16x32_bf16 v[118:121], v[132:135], v[212:215], v[118:121]
	v_mfma_f32_16x16x32_bf16 v[52:55], v[140:143], v[212:215], v[52:55]
	v_mfma_f32_16x16x32_bf16 v[110:113], v[132:135], v[228:231], v[110:113]
	v_mfma_f32_16x16x32_bf16 v[44:47], v[140:143], v[228:231], v[44:47]
	v_mfma_f32_16x16x32_bf16 v[94:97], v[132:135], v[236:239], v[94:97]
	v_mfma_f32_16x16x32_bf16 v[28:31], v[140:143], v[236:239], v[28:31]
	v_mfma_f32_16x16x32_bf16 v[126:129], v[136:139], v[198:201], v[126:129]
	v_mfma_f32_16x16x32_bf16 v[60:63], v[144:147], v[198:201], v[60:63]
	v_mfma_f32_16x16x32_bf16 v[118:121], v[136:139], v[224:227], v[118:121]
	v_mfma_f32_16x16x32_bf16 v[52:55], v[144:147], v[224:227], v[52:55]
	v_mfma_f32_16x16x32_bf16 v[110:113], v[136:139], v[232:235], v[110:113]
	v_mfma_f32_16x16x32_bf16 v[44:47], v[144:147], v[232:235], v[44:47]
	v_mfma_f32_16x16x32_bf16 v[94:97], v[136:139], v[240:243], v[94:97]
	v_mfma_f32_16x16x32_bf16 v[28:31], v[144:147], v[240:243], v[28:31]
	v_mfma_f32_16x16x32_bf16 v[122:125], v[148:151], v[194:197], v[122:125]
	v_mfma_f32_16x16x32_bf16 v[56:59], v[156:159], v[194:197], v[56:59]
	v_mfma_f32_16x16x32_bf16 v[114:117], v[148:151], v[212:215], v[114:117]
	v_mfma_f32_16x16x32_bf16 v[48:51], v[156:159], v[212:215], v[48:51]
	v_mfma_f32_16x16x32_bf16 v[102:105], v[148:151], v[228:231], v[102:105]
	v_mfma_f32_16x16x32_bf16 v[36:39], v[156:159], v[228:231], v[36:39]
	v_mfma_f32_16x16x32_bf16 v[88:91], v[148:151], v[236:239], v[88:91]
	v_mfma_f32_16x16x32_bf16 v[24:27], v[156:159], v[236:239], v[24:27]
	v_mfma_f32_16x16x32_bf16 v[122:125], v[152:155], v[198:201], v[122:125]
	v_mfma_f32_16x16x32_bf16 v[56:59], v[174:177], v[198:201], v[56:59]
	v_mfma_f32_16x16x32_bf16 v[114:117], v[152:155], v[224:227], v[114:117]
	v_mfma_f32_16x16x32_bf16 v[48:51], v[174:177], v[224:227], v[48:51]
	v_mfma_f32_16x16x32_bf16 v[102:105], v[152:155], v[232:235], v[102:105]
	v_mfma_f32_16x16x32_bf16 v[36:39], v[174:177], v[232:235], v[36:39]
	v_mfma_f32_16x16x32_bf16 v[88:91], v[152:155], v[240:243], v[88:91]
	v_mfma_f32_16x16x32_bf16 v[24:27], v[174:177], v[240:243], v[24:27]
	s_barrier
	s_add_i32 s68, s95, s57
	v_lshl_add_u64 v[160:161], s[88:89], 0, v[164:165]
	s_mov_b32 m0, s68
	ds_read_b128 v[194:197], v209 offset:16384
	ds_read_b128 v[198:201], v209 offset:17408
	ds_read_b128 v[212:215], v209 offset:18432
	ds_read_b128 v[224:227], v209 offset:19456
	ds_read_b128 v[228:231], v209 offset:20480
	ds_read_b128 v[232:235], v209 offset:21504
	ds_read_b128 v[236:239], v209 offset:22528
	ds_read_b128 v[240:243], v209 offset:23552
	global_load_lds_dwordx4 v[160:161], off
	s_add_i32 m0, s68, 0x2000
	s_add_u32 s68, s88, 0x40000
	v_lshl_add_u64 v[216:217], s[88:89], 0, v[166:167]
	s_addc_u32 s69, s89, 0
	s_add_i32 s70, s96, s57
	global_load_lds_dwordx4 v[216:217], off
	s_mov_b32 m0, s70
	v_lshl_add_u64 v[220:221], s[68:69], 0, v[164:165]
	global_load_lds_dwordx4 v[220:221], off
	s_add_i32 m0, s70, 0x2000
	v_lshl_add_u64 v[220:221], s[68:69], 0, v[166:167]
	s_add_u32 s68, s90, s71
	global_load_lds_dwordx4 v[220:221], off
	v_lshl_add_u64 v[220:221], s[90:91], 0, v[162:163]
	s_mov_b32 m0, s59
	s_addc_u32 s69, s91, s51
	global_load_lds_dwordx4 v[220:221], off
	s_mov_b32 m0, s61
	v_lshl_add_u64 v[244:245], s[68:69], 0, v[162:163]
	global_load_lds_dwordx4 v[244:245], off
	s_waitcnt vmcnt(8) lgkmcnt(0)
	s_barrier
	v_mfma_f32_16x16x32_bf16 v[84:87], v[132:135], v[194:197], v[84:87]
	v_mfma_f32_16x16x32_bf16 v[20:23], v[140:143], v[194:197], v[20:23]
	v_mfma_f32_16x16x32_bf16 v[76:79], v[132:135], v[212:215], v[76:79]
	v_mfma_f32_16x16x32_bf16 v[12:15], v[140:143], v[212:215], v[12:15]
	v_mfma_f32_16x16x32_bf16 v[68:71], v[132:135], v[228:231], v[68:71]
	v_mfma_f32_16x16x32_bf16 v[4:7], v[140:143], v[228:231], v[4:7]
	v_mfma_f32_16x16x32_bf16 v[106:109], v[132:135], v[236:239], v[106:109]
	v_mfma_f32_16x16x32_bf16 v[40:43], v[140:143], v[236:239], v[40:43]
	v_mfma_f32_16x16x32_bf16 v[84:87], v[136:139], v[198:201], v[84:87]
	v_mfma_f32_16x16x32_bf16 v[20:23], v[144:147], v[198:201], v[20:23]
	v_mfma_f32_16x16x32_bf16 v[76:79], v[136:139], v[224:227], v[76:79]
	v_mfma_f32_16x16x32_bf16 v[12:15], v[144:147], v[224:227], v[12:15]
	v_mfma_f32_16x16x32_bf16 v[68:71], v[136:139], v[232:235], v[68:71]
	v_mfma_f32_16x16x32_bf16 v[4:7], v[144:147], v[232:235], v[4:7]
	v_mfma_f32_16x16x32_bf16 v[106:109], v[136:139], v[240:243], v[106:109]
	v_mfma_f32_16x16x32_bf16 v[40:43], v[144:147], v[240:243], v[40:43]
	v_mfma_f32_16x16x32_bf16 v[80:83], v[148:151], v[194:197], v[80:83]
	v_mfma_f32_16x16x32_bf16 v[16:19], v[156:159], v[194:197], v[16:19]
	v_mfma_f32_16x16x32_bf16 v[72:75], v[148:151], v[212:215], v[72:75]
	v_mfma_f32_16x16x32_bf16 v[8:11], v[156:159], v[212:215], v[8:11]
	v_mfma_f32_16x16x32_bf16 v[64:67], v[148:151], v[228:231], v[64:67]
	v_mfma_f32_16x16x32_bf16 v[0:3], v[156:159], v[228:231], v[0:3]
	v_mfma_f32_16x16x32_bf16 v[98:101], v[148:151], v[236:239], v[98:101]
	v_mfma_f32_16x16x32_bf16 v[32:35], v[156:159], v[236:239], v[32:35]
	v_mfma_f32_16x16x32_bf16 v[80:83], v[152:155], v[198:201], v[80:83]
	v_mfma_f32_16x16x32_bf16 v[16:19], v[174:177], v[198:201], v[16:19]
	v_mfma_f32_16x16x32_bf16 v[72:75], v[152:155], v[224:227], v[72:75]
	v_mfma_f32_16x16x32_bf16 v[8:11], v[174:177], v[224:227], v[8:11]
	v_mfma_f32_16x16x32_bf16 v[64:67], v[152:155], v[232:235], v[64:67]
	v_mfma_f32_16x16x32_bf16 v[0:3], v[174:177], v[232:235], v[0:3]
	v_mfma_f32_16x16x32_bf16 v[98:101], v[152:155], v[240:243], v[98:101]
	v_mfma_f32_16x16x32_bf16 v[32:35], v[174:177], v[240:243], v[32:35]
	s_barrier
	s_add_i32 s70, 0, 0x18000
	s_add_i32 s14, 0, 0x1c000
	v_add_u32_e32 v144, s70, v203
	v_add_u32_e32 v174, s14, v203
	ds_read_b128 v[132:135], v144
	ds_read_b128 v[136:139], v144 offset:1024
	ds_read_b128 v[140:143], v144 offset:2048
	ds_read_b128 v[144:147], v144 offset:3072
	ds_read_b128 v[148:151], v174
	ds_read_b128 v[152:155], v174 offset:1024
	ds_read_b128 v[156:159], v174 offset:2048
	ds_read_b128 v[174:177], v174 offset:3072
	s_add_u32 s68, s90, 0x2000
	s_addc_u32 s69, s91, 0
	v_lshl_add_u64 v[246:247], s[68:69], 0, v[162:163]
	s_add_u32 s68, s68, s71
	s_mov_b32 m0, s63
	s_addc_u32 s69, s69, s51
	ds_read_b128 v[194:197], v209 offset:32768
	ds_read_b128 v[198:201], v209 offset:33792
	ds_read_b128 v[212:215], v209 offset:34816
	ds_read_b128 v[224:227], v209 offset:35840
	ds_read_b128 v[228:231], v209 offset:36864
	ds_read_b128 v[232:235], v209 offset:37888
	ds_read_b128 v[236:239], v209 offset:38912
	ds_read_b128 v[240:243], v209 offset:39936
	global_load_lds_dwordx4 v[246:247], off
	s_mov_b32 m0, s67
	v_lshl_add_u64 v[246:247], s[68:69], 0, v[162:163]
	global_load_lds_dwordx4 v[246:247], off
	s_waitcnt vmcnt(8) lgkmcnt(0)
	s_barrier
	v_mfma_f32_16x16x32_bf16 v[126:129], v[132:135], v[194:197], v[126:129]
	v_mfma_f32_16x16x32_bf16 v[60:63], v[140:143], v[194:197], v[60:63]
	v_mfma_f32_16x16x32_bf16 v[118:121], v[132:135], v[212:215], v[118:121]
	v_mfma_f32_16x16x32_bf16 v[52:55], v[140:143], v[212:215], v[52:55]
	v_mfma_f32_16x16x32_bf16 v[110:113], v[132:135], v[228:231], v[110:113]
	v_mfma_f32_16x16x32_bf16 v[44:47], v[140:143], v[228:231], v[44:47]
	v_mfma_f32_16x16x32_bf16 v[94:97], v[132:135], v[236:239], v[94:97]
	v_mfma_f32_16x16x32_bf16 v[28:31], v[140:143], v[236:239], v[28:31]
	v_mfma_f32_16x16x32_bf16 v[126:129], v[136:139], v[198:201], v[126:129]
	v_mfma_f32_16x16x32_bf16 v[60:63], v[144:147], v[198:201], v[60:63]
	v_mfma_f32_16x16x32_bf16 v[118:121], v[136:139], v[224:227], v[118:121]
	v_mfma_f32_16x16x32_bf16 v[52:55], v[144:147], v[224:227], v[52:55]
	v_mfma_f32_16x16x32_bf16 v[110:113], v[136:139], v[232:235], v[110:113]
	v_mfma_f32_16x16x32_bf16 v[44:47], v[144:147], v[232:235], v[44:47]
	v_mfma_f32_16x16x32_bf16 v[94:97], v[136:139], v[240:243], v[94:97]
	v_mfma_f32_16x16x32_bf16 v[28:31], v[144:147], v[240:243], v[28:31]
	v_mfma_f32_16x16x32_bf16 v[122:125], v[148:151], v[194:197], v[122:125]
	v_mfma_f32_16x16x32_bf16 v[56:59], v[156:159], v[194:197], v[56:59]
	v_mfma_f32_16x16x32_bf16 v[114:117], v[148:151], v[212:215], v[114:117]
	v_mfma_f32_16x16x32_bf16 v[48:51], v[156:159], v[212:215], v[48:51]
	v_mfma_f32_16x16x32_bf16 v[102:105], v[148:151], v[228:231], v[102:105]
	v_mfma_f32_16x16x32_bf16 v[36:39], v[156:159], v[228:231], v[36:39]
	v_mfma_f32_16x16x32_bf16 v[88:91], v[148:151], v[236:239], v[88:91]
	v_mfma_f32_16x16x32_bf16 v[24:27], v[156:159], v[236:239], v[24:27]
	v_mfma_f32_16x16x32_bf16 v[122:125], v[152:155], v[198:201], v[122:125]
	v_mfma_f32_16x16x32_bf16 v[56:59], v[174:177], v[198:201], v[56:59]
	v_mfma_f32_16x16x32_bf16 v[114:117], v[152:155], v[224:227], v[114:117]
	v_mfma_f32_16x16x32_bf16 v[48:51], v[174:177], v[224:227], v[48:51]
	v_mfma_f32_16x16x32_bf16 v[102:105], v[152:155], v[232:235], v[102:105]
	v_mfma_f32_16x16x32_bf16 v[36:39], v[174:177], v[232:235], v[36:39]
	v_mfma_f32_16x16x32_bf16 v[88:91], v[152:155], v[240:243], v[88:91]
	v_mfma_f32_16x16x32_bf16 v[24:27], v[174:177], v[240:243], v[24:27]
	s_barrier
	s_add_i32 s15, s70, s57
	v_lshl_add_u64 v[160:161], v[160:161], 0, s[22:23]
	s_mov_b32 m0, s15
	ds_read_b128 v[194:197], v209 offset:49152
	ds_read_b128 v[198:201], v209 offset:50176
	ds_read_b128 v[212:215], v209 offset:51200
	ds_read_b128 v[224:227], v209 offset:52224
	ds_read_b128 v[228:231], v209 offset:53248
	ds_read_b128 v[232:235], v209 offset:54272
	ds_read_b128 v[236:239], v209 offset:55296
	ds_read_b128 v[240:243], v209 offset:56320
	global_load_lds_dwordx4 v[160:161], off
	s_add_i32 m0, s15, 0x2000
	s_add_u32 s68, s88, 0x40080
	v_lshl_add_u64 v[160:161], v[216:217], 0, s[22:23]
	s_addc_u32 s69, s89, 0
	s_add_i32 s14, s14, s57
	global_load_lds_dwordx4 v[160:161], off
	s_mov_b32 m0, s14
	v_lshl_add_u64 v[160:161], s[68:69], 0, v[164:165]
	global_load_lds_dwordx4 v[160:161], off
	s_add_i32 m0, s14, 0x2000
	v_lshl_add_u64 v[160:161], s[68:69], 0, v[166:167]
	global_load_lds_dwordx4 v[160:161], off
	s_mov_b32 m0, s75
	v_lshl_add_u64 v[160:161], v[220:221], 0, s[22:23]
	global_load_lds_dwordx4 v[160:161], off
	s_mov_b32 m0, s92
	v_lshl_add_u64 v[160:161], v[244:245], 0, s[22:23]
	global_load_lds_dwordx4 v[160:161], off
	s_waitcnt vmcnt(8) lgkmcnt(0)
	s_barrier
	v_mfma_f32_16x16x32_bf16 v[84:87], v[132:135], v[194:197], v[84:87]
	v_mfma_f32_16x16x32_bf16 v[20:23], v[140:143], v[194:197], v[20:23]
	v_mfma_f32_16x16x32_bf16 v[76:79], v[132:135], v[212:215], v[76:79]
	v_mfma_f32_16x16x32_bf16 v[12:15], v[140:143], v[212:215], v[12:15]
	v_mfma_f32_16x16x32_bf16 v[68:71], v[132:135], v[228:231], v[68:71]
	v_mfma_f32_16x16x32_bf16 v[4:7], v[140:143], v[228:231], v[4:7]
	v_mfma_f32_16x16x32_bf16 v[106:109], v[132:135], v[236:239], v[106:109]
	v_mfma_f32_16x16x32_bf16 v[40:43], v[140:143], v[236:239], v[40:43]
	v_mfma_f32_16x16x32_bf16 v[84:87], v[136:139], v[198:201], v[84:87]
	v_mfma_f32_16x16x32_bf16 v[20:23], v[144:147], v[198:201], v[20:23]
	v_mfma_f32_16x16x32_bf16 v[76:79], v[136:139], v[224:227], v[76:79]
	v_mfma_f32_16x16x32_bf16 v[12:15], v[144:147], v[224:227], v[12:15]
	v_mfma_f32_16x16x32_bf16 v[68:71], v[136:139], v[232:235], v[68:71]
	v_mfma_f32_16x16x32_bf16 v[4:7], v[144:147], v[232:235], v[4:7]
	v_mfma_f32_16x16x32_bf16 v[106:109], v[136:139], v[240:243], v[106:109]
	v_mfma_f32_16x16x32_bf16 v[40:43], v[144:147], v[240:243], v[40:43]
	v_mfma_f32_16x16x32_bf16 v[80:83], v[148:151], v[194:197], v[80:83]
	v_mfma_f32_16x16x32_bf16 v[16:19], v[156:159], v[194:197], v[16:19]
	v_mfma_f32_16x16x32_bf16 v[72:75], v[148:151], v[212:215], v[72:75]
	v_mfma_f32_16x16x32_bf16 v[8:11], v[156:159], v[212:215], v[8:11]
	v_mfma_f32_16x16x32_bf16 v[64:67], v[148:151], v[228:231], v[64:67]
	v_mfma_f32_16x16x32_bf16 v[0:3], v[156:159], v[228:231], v[0:3]
	v_mfma_f32_16x16x32_bf16 v[98:101], v[148:151], v[236:239], v[98:101]
	v_mfma_f32_16x16x32_bf16 v[32:35], v[156:159], v[236:239], v[32:35]
	v_mfma_f32_16x16x32_bf16 v[80:83], v[152:155], v[198:201], v[80:83]
	v_mfma_f32_16x16x32_bf16 v[16:19], v[174:177], v[198:201], v[16:19]
	v_mfma_f32_16x16x32_bf16 v[72:75], v[152:155], v[224:227], v[72:75]
	v_mfma_f32_16x16x32_bf16 v[8:11], v[174:177], v[224:227], v[8:11]
	v_mfma_f32_16x16x32_bf16 v[64:67], v[152:155], v[232:235], v[64:67]
	v_mfma_f32_16x16x32_bf16 v[0:3], v[174:177], v[232:235], v[0:3]
	v_mfma_f32_16x16x32_bf16 v[98:101], v[152:155], v[240:243], v[98:101]
	v_mfma_f32_16x16x32_bf16 v[32:35], v[174:177], v[240:243], v[32:35]
	s_barrier
	s_add_i32 s50, s50, 2
	s_add_u32 s0, s0, 0x100
	s_addc_u32 s1, s1, 0
	s_cmp_gt_u32 s50, 13
	s_cbranch_scc0 .LBB0_565

.LBB0_585:
	s_add_u32 s58, s46, s52
	s_addc_u32 s59, s47, s53
	s_add_u32 s56, s58, 0x100
	s_addc_u32 s57, s59, 0
	s_and_b64 s[54:55], s[50:51], exec
	s_cselect_b32 s54, s81, s56
	s_cselect_b32 s55, s13, s57
	s_add_u32 s52, s44, s52
	s_addc_u32 s53, s45, s53
	s_add_u32 s52, s52, 0x100
	ds_read_b128 v[148:151], v145
	ds_read_b128 v[152:155], v145 offset:1024
	ds_read_b128 v[156:159], v145 offset:2048
	ds_read_b128 v[160:163], v145 offset:3072
	ds_read_b128 v[164:167], v146
	ds_read_b128 v[168:171], v146 offset:1024
	ds_read_b128 v[172:175], v146 offset:2048
	ds_read_b128 v[176:179], v146 offset:3072
	s_addc_u32 s53, s53, 0
	s_and_b64 s[50:51], s[50:51], exec
	s_cselect_b32 s53, s39, s53
	s_cselect_b32 s52, s82, s52
	s_add_i32 s92, s75, s35
	s_add_i32 m0, s62, 0xc000
	s_add_i32 s93, s62, 0xe000
	s_add_i32 s89, s92, 0x2000
	s_add_u32 s56, s52, 0x10000
	s_addc_u32 s57, s53, 0
	s_add_i32 s88, 0, 0x18000
	s_add_i32 s91, s76, s35
	s_add_i32 s86, s88, s35
	s_add_i32 s90, s91, 0x2000
	s_add_i32 s87, 0, 0x1c000
	s_add_i32 s84, s86, 0x2000
	s_add_u32 s50, s52, 0x10080
	s_addc_u32 s51, s53, 0
	s_add_i32 s85, s87, s35
	s_add_i32 s83, s85, 0x2000
	v_lshl_add_u64 v[140:141], s[58:59], 0, v[134:135]
	v_lshl_add_u64 v[140:141], v[140:141], 0, s[68:69]
	ds_read_b128 v[180:183], v147
	ds_read_b128 v[184:187], v147 offset:1024
	ds_read_b128 v[188:191], v147 offset:2048
	ds_read_b128 v[192:195], v147 offset:3072
	ds_read_b128 v[196:199], v147 offset:4096
	ds_read_b128 v[200:203], v147 offset:5120
	ds_read_b128 v[204:207], v147 offset:6144
	ds_read_b128 v[208:211], v147 offset:7168
	global_load_lds_dwordx4 v[140:141], off
	v_lshl_add_u64 v[140:141], s[58:59], 0, v[130:131]
	s_mov_b64 s[58:59], 0x18080
	s_mov_b32 m0, s93
	v_lshl_add_u64 v[140:141], v[140:141], 0, s[58:59]
	global_load_lds_dwordx4 v[140:141], off
	s_waitcnt vmcnt(8) lgkmcnt(0)
	s_barrier
	v_mfma_f32_16x16x32_bf16 v[124:127], v[148:151], v[180:183], v[124:127]
	v_mfma_f32_16x16x32_bf16 v[120:123], v[156:159], v[180:183], v[120:123]
	v_mfma_f32_16x16x32_bf16 v[112:115], v[148:151], v[188:191], v[112:115]
	v_mfma_f32_16x16x32_bf16 v[104:107], v[156:159], v[188:191], v[104:107]
	v_mfma_f32_16x16x32_bf16 v[96:99], v[148:151], v[196:199], v[96:99]
	v_mfma_f32_16x16x32_bf16 v[88:91], v[156:159], v[196:199], v[88:91]
	v_mfma_f32_16x16x32_bf16 v[80:83], v[148:151], v[204:207], v[80:83]
	v_mfma_f32_16x16x32_bf16 v[72:75], v[156:159], v[204:207], v[72:75]
	v_mfma_f32_16x16x32_bf16 v[124:127], v[152:155], v[184:187], v[124:127]
	v_mfma_f32_16x16x32_bf16 v[120:123], v[160:163], v[184:187], v[120:123]
	v_mfma_f32_16x16x32_bf16 v[112:115], v[152:155], v[192:195], v[112:115]
	v_mfma_f32_16x16x32_bf16 v[104:107], v[160:163], v[192:195], v[104:107]
	v_mfma_f32_16x16x32_bf16 v[96:99], v[152:155], v[200:203], v[96:99]
	v_mfma_f32_16x16x32_bf16 v[88:91], v[160:163], v[200:203], v[88:91]
	v_mfma_f32_16x16x32_bf16 v[80:83], v[152:155], v[208:211], v[80:83]
	v_mfma_f32_16x16x32_bf16 v[72:75], v[160:163], v[208:211], v[72:75]
	v_mfma_f32_16x16x32_bf16 v[116:119], v[164:167], v[180:183], v[116:119]
	v_mfma_f32_16x16x32_bf16 v[108:111], v[172:175], v[180:183], v[108:111]
	v_mfma_f32_16x16x32_bf16 v[100:103], v[164:167], v[188:191], v[100:103]
	v_mfma_f32_16x16x32_bf16 v[92:95], v[172:175], v[188:191], v[92:95]
	v_mfma_f32_16x16x32_bf16 v[84:87], v[164:167], v[196:199], v[84:87]
	v_mfma_f32_16x16x32_bf16 v[76:79], v[172:175], v[196:199], v[76:79]
	v_mfma_f32_16x16x32_bf16 v[68:71], v[164:167], v[204:207], v[68:71]
	v_mfma_f32_16x16x32_bf16 v[64:67], v[172:175], v[204:207], v[64:67]
	v_mfma_f32_16x16x32_bf16 v[116:119], v[168:171], v[184:187], v[116:119]
	v_mfma_f32_16x16x32_bf16 v[108:111], v[176:179], v[184:187], v[108:111]
	v_mfma_f32_16x16x32_bf16 v[100:103], v[168:171], v[192:195], v[100:103]
	v_mfma_f32_16x16x32_bf16 v[92:95], v[176:179], v[192:195], v[92:95]
	v_mfma_f32_16x16x32_bf16 v[84:87], v[168:171], v[200:203], v[84:87]
	v_mfma_f32_16x16x32_bf16 v[76:79], v[176:179], v[200:203], v[76:79]
	v_mfma_f32_16x16x32_bf16 v[68:71], v[168:171], v[208:211], v[68:71]
	v_mfma_f32_16x16x32_bf16 v[64:67], v[176:179], v[208:211], v[64:67]
	s_barrier
	s_mov_b32 m0, s92
	v_lshl_add_u64 v[140:141], s[52:53], 0, v[132:133]
	ds_read_b128 v[180:183], v147 offset:16384
	ds_read_b128 v[184:187], v147 offset:17408
	ds_read_b128 v[188:191], v147 offset:18432
	ds_read_b128 v[192:195], v147 offset:19456
	ds_read_b128 v[196:199], v147 offset:20480
	ds_read_b128 v[200:203], v147 offset:21504
	ds_read_b128 v[204:207], v147 offset:22528
	ds_read_b128 v[208:211], v147 offset:23552
	global_load_lds_dwordx4 v[140:141], off
	v_lshl_add_u64 v[212:213], s[52:53], 0, v[128:129]
	s_mov_b32 m0, s89
	v_lshl_add_u64 v[214:215], s[56:57], 0, v[132:133]
	global_load_lds_dwordx4 v[212:213], off
	s_mov_b32 m0, s91
	v_lshl_add_u64 v[216:217], s[54:55], 0, v[130:131]
	global_load_lds_dwordx4 v[214:215], off
	v_lshl_add_u64 v[214:215], s[56:57], 0, v[128:129]
	s_mov_b32 m0, s90
	v_lshl_add_u64 v[220:221], v[216:217], 0, s[6:7]
	global_load_lds_dwordx4 v[214:215], off
	s_mov_b32 m0, s62
	v_lshl_add_u64 v[214:215], s[54:55], 0, v[134:135]
	global_load_lds_dwordx4 v[214:215], off
	s_mov_b32 m0, s63
	s_nop 0
	global_load_lds_dwordx4 v[220:221], off
	s_waitcnt vmcnt(8) lgkmcnt(0)
	s_barrier
	v_mfma_f32_16x16x32_bf16 v[60:63], v[148:151], v[180:183], v[60:63]
	v_mfma_f32_16x16x32_bf16 v[56:59], v[156:159], v[180:183], v[56:59]
	v_mfma_f32_16x16x32_bf16 v[52:55], v[148:151], v[188:191], v[52:55]
	v_mfma_f32_16x16x32_bf16 v[44:47], v[156:159], v[188:191], v[44:47]
	v_mfma_f32_16x16x32_bf16 v[36:39], v[148:151], v[196:199], v[36:39]
	v_mfma_f32_16x16x32_bf16 v[28:31], v[156:159], v[196:199], v[28:31]
	v_mfma_f32_16x16x32_bf16 v[20:23], v[148:151], v[204:207], v[20:23]
	v_mfma_f32_16x16x32_bf16 v[12:15], v[156:159], v[204:207], v[12:15]
	v_mfma_f32_16x16x32_bf16 v[60:63], v[152:155], v[184:187], v[60:63]
	v_mfma_f32_16x16x32_bf16 v[56:59], v[160:163], v[184:187], v[56:59]
	v_mfma_f32_16x16x32_bf16 v[52:55], v[152:155], v[192:195], v[52:55]
	v_mfma_f32_16x16x32_bf16 v[44:47], v[160:163], v[192:195], v[44:47]
	v_mfma_f32_16x16x32_bf16 v[36:39], v[152:155], v[200:203], v[36:39]
	v_mfma_f32_16x16x32_bf16 v[28:31], v[160:163], v[200:203], v[28:31]
	v_mfma_f32_16x16x32_bf16 v[20:23], v[152:155], v[208:211], v[20:23]
	v_mfma_f32_16x16x32_bf16 v[12:15], v[160:163], v[208:211], v[12:15]
	v_mfma_f32_16x16x32_bf16 v[48:51], v[164:167], v[180:183], v[48:51]
	v_mfma_f32_16x16x32_bf16 v[40:43], v[172:175], v[180:183], v[40:43]
	v_mfma_f32_16x16x32_bf16 v[32:35], v[164:167], v[188:191], v[32:35]
	v_mfma_f32_16x16x32_bf16 v[24:27], v[172:175], v[188:191], v[24:27]
	v_mfma_f32_16x16x32_bf16 v[16:19], v[164:167], v[196:199], v[16:19]
	v_mfma_f32_16x16x32_bf16 v[8:11], v[172:175], v[196:199], v[8:11]
	v_mfma_f32_16x16x32_bf16 v[4:7], v[164:167], v[204:207], v[4:7]
	v_mfma_f32_16x16x32_bf16 v[0:3], v[172:175], v[204:207], v[0:3]
	v_mfma_f32_16x16x32_bf16 v[48:51], v[168:171], v[184:187], v[48:51]
	v_mfma_f32_16x16x32_bf16 v[40:43], v[176:179], v[184:187], v[40:43]
	v_mfma_f32_16x16x32_bf16 v[32:35], v[168:171], v[192:195], v[32:35]
	v_mfma_f32_16x16x32_bf16 v[24:27], v[176:179], v[192:195], v[24:27]
	v_mfma_f32_16x16x32_bf16 v[16:19], v[168:171], v[200:203], v[16:19]
	v_mfma_f32_16x16x32_bf16 v[8:11], v[176:179], v[200:203], v[8:11]
	v_mfma_f32_16x16x32_bf16 v[4:7], v[168:171], v[208:211], v[4:7]
	v_mfma_f32_16x16x32_bf16 v[0:3], v[176:179], v[208:211], v[0:3]
	s_barrier
	v_add_u32_e32 v160, s88, v143
	v_add_u32_e32 v176, s87, v143
	ds_read_b128 v[148:151], v160
	ds_read_b128 v[152:155], v160 offset:1024
	ds_read_b128 v[156:159], v160 offset:2048
	ds_read_b128 v[160:163], v160 offset:3072
	ds_read_b128 v[164:167], v176
	ds_read_b128 v[168:171], v176 offset:1024
	ds_read_b128 v[172:175], v176 offset:2048
	ds_read_b128 v[176:179], v176 offset:3072
	s_mov_b32 m0, s64
	v_lshl_add_u64 v[220:221], v[214:215], 0, s[4:5]
	ds_read_b128 v[180:183], v147 offset:32768
	ds_read_b128 v[184:187], v147 offset:33792
	ds_read_b128 v[188:191], v147 offset:34816
	ds_read_b128 v[192:195], v147 offset:35840
	ds_read_b128 v[196:199], v147 offset:36864
	ds_read_b128 v[200:203], v147 offset:37888
	ds_read_b128 v[204:207], v147 offset:38912
	ds_read_b128 v[208:211], v147 offset:39936
	global_load_lds_dwordx4 v[220:221], off
	s_mov_b32 m0, s65
	v_lshl_add_u64 v[220:221], v[216:217], 0, s[8:9]
	global_load_lds_dwordx4 v[220:221], off
	s_waitcnt vmcnt(8) lgkmcnt(0)
	s_barrier
	v_mfma_f32_16x16x32_bf16 v[124:127], v[148:151], v[180:183], v[124:127]
	v_mfma_f32_16x16x32_bf16 v[120:123], v[156:159], v[180:183], v[120:123]
	v_mfma_f32_16x16x32_bf16 v[112:115], v[148:151], v[188:191], v[112:115]
	v_mfma_f32_16x16x32_bf16 v[104:107], v[156:159], v[188:191], v[104:107]
	v_mfma_f32_16x16x32_bf16 v[96:99], v[148:151], v[196:199], v[96:99]
	v_mfma_f32_16x16x32_bf16 v[88:91], v[156:159], v[196:199], v[88:91]
	v_mfma_f32_16x16x32_bf16 v[80:83], v[148:151], v[204:207], v[80:83]
	v_mfma_f32_16x16x32_bf16 v[72:75], v[156:159], v[204:207], v[72:75]
	v_mfma_f32_16x16x32_bf16 v[124:127], v[152:155], v[184:187], v[124:127]
	v_mfma_f32_16x16x32_bf16 v[120:123], v[160:163], v[184:187], v[120:123]
	v_mfma_f32_16x16x32_bf16 v[112:115], v[152:155], v[192:195], v[112:115]
	v_mfma_f32_16x16x32_bf16 v[104:107], v[160:163], v[192:195], v[104:107]
	v_mfma_f32_16x16x32_bf16 v[96:99], v[152:155], v[200:203], v[96:99]
	v_mfma_f32_16x16x32_bf16 v[88:91], v[160:163], v[200:203], v[88:91]
	v_mfma_f32_16x16x32_bf16 v[80:83], v[152:155], v[208:211], v[80:83]
	v_mfma_f32_16x16x32_bf16 v[72:75], v[160:163], v[208:211], v[72:75]
	v_mfma_f32_16x16x32_bf16 v[116:119], v[164:167], v[180:183], v[116:119]
	v_mfma_f32_16x16x32_bf16 v[108:111], v[172:175], v[180:183], v[108:111]
	v_mfma_f32_16x16x32_bf16 v[100:103], v[164:167], v[188:191], v[100:103]
	v_mfma_f32_16x16x32_bf16 v[92:95], v[172:175], v[188:191], v[92:95]
	v_mfma_f32_16x16x32_bf16 v[84:87], v[164:167], v[196:199], v[84:87]
	v_mfma_f32_16x16x32_bf16 v[76:79], v[172:175], v[196:199], v[76:79]
	v_mfma_f32_16x16x32_bf16 v[68:71], v[164:167], v[204:207], v[68:71]
	v_mfma_f32_16x16x32_bf16 v[64:67], v[172:175], v[204:207], v[64:67]
	v_mfma_f32_16x16x32_bf16 v[116:119], v[168:171], v[184:187], v[116:119]
	v_mfma_f32_16x16x32_bf16 v[108:111], v[176:179], v[184:187], v[108:111]
	v_mfma_f32_16x16x32_bf16 v[100:103], v[168:171], v[192:195], v[100:103]
	v_mfma_f32_16x16x32_bf16 v[92:95], v[176:179], v[192:195], v[92:95]
	v_mfma_f32_16x16x32_bf16 v[84:87], v[168:171], v[200:203], v[84:87]
	v_mfma_f32_16x16x32_bf16 v[76:79], v[176:179], v[200:203], v[76:79]
	v_mfma_f32_16x16x32_bf16 v[68:71], v[168:171], v[208:211], v[68:71]
	v_mfma_f32_16x16x32_bf16 v[64:67], v[176:179], v[208:211], v[64:67]
	s_barrier
	s_mov_b32 m0, s86
	v_lshl_add_u64 v[140:141], v[140:141], 0, s[18:19]
	ds_read_b128 v[180:183], v147 offset:49152
	ds_read_b128 v[184:187], v147 offset:50176
	ds_read_b128 v[188:191], v147 offset:51200
	ds_read_b128 v[192:195], v147 offset:52224
	ds_read_b128 v[196:199], v147 offset:53248
	ds_read_b128 v[200:203], v147 offset:54272
	ds_read_b128 v[204:207], v147 offset:55296
	ds_read_b128 v[208:211], v147 offset:56320
	global_load_lds_dwordx4 v[140:141], off
	s_mov_b32 m0, s84
	v_lshl_add_u64 v[140:141], v[212:213], 0, s[18:19]
	global_load_lds_dwordx4 v[140:141], off
	s_mov_b32 m0, s85
	v_lshl_add_u64 v[140:141], s[50:51], 0, v[132:133]
	global_load_lds_dwordx4 v[140:141], off
	s_mov_b32 m0, s83
	v_lshl_add_u64 v[140:141], s[50:51], 0, v[128:129]
	global_load_lds_dwordx4 v[140:141], off
	s_mov_b32 m0, s67
	v_lshl_add_u64 v[140:141], v[214:215], 0, s[18:19]
	global_load_lds_dwordx4 v[140:141], off
	s_mov_b32 m0, s72
	v_lshl_add_u64 v[140:141], v[216:217], 0, s[20:21]
	global_load_lds_dwordx4 v[140:141], off
	s_waitcnt vmcnt(8) lgkmcnt(0)
	s_barrier
	v_mfma_f32_16x16x32_bf16 v[60:63], v[148:151], v[180:183], v[60:63]
	v_mfma_f32_16x16x32_bf16 v[56:59], v[156:159], v[180:183], v[56:59]
	v_mfma_f32_16x16x32_bf16 v[52:55], v[148:151], v[188:191], v[52:55]
	v_mfma_f32_16x16x32_bf16 v[44:47], v[156:159], v[188:191], v[44:47]
	v_mfma_f32_16x16x32_bf16 v[36:39], v[148:151], v[196:199], v[36:39]
	v_mfma_f32_16x16x32_bf16 v[28:31], v[156:159], v[196:199], v[28:31]
	v_mfma_f32_16x16x32_bf16 v[20:23], v[148:151], v[204:207], v[20:23]
	v_mfma_f32_16x16x32_bf16 v[12:15], v[156:159], v[204:207], v[12:15]
	v_mfma_f32_16x16x32_bf16 v[60:63], v[152:155], v[184:187], v[60:63]
	v_mfma_f32_16x16x32_bf16 v[56:59], v[160:163], v[184:187], v[56:59]
	v_mfma_f32_16x16x32_bf16 v[52:55], v[152:155], v[192:195], v[52:55]
	v_mfma_f32_16x16x32_bf16 v[44:47], v[160:163], v[192:195], v[44:47]
	v_mfma_f32_16x16x32_bf16 v[36:39], v[152:155], v[200:203], v[36:39]
	v_mfma_f32_16x16x32_bf16 v[28:31], v[160:163], v[200:203], v[28:31]
	v_mfma_f32_16x16x32_bf16 v[20:23], v[152:155], v[208:211], v[20:23]
	v_mfma_f32_16x16x32_bf16 v[12:15], v[160:163], v[208:211], v[12:15]
	v_mfma_f32_16x16x32_bf16 v[48:51], v[164:167], v[180:183], v[48:51]
	v_mfma_f32_16x16x32_bf16 v[40:43], v[172:175], v[180:183], v[40:43]
	v_mfma_f32_16x16x32_bf16 v[32:35], v[164:167], v[188:191], v[32:35]
	v_mfma_f32_16x16x32_bf16 v[24:27], v[172:175], v[188:191], v[24:27]
	v_mfma_f32_16x16x32_bf16 v[16:19], v[164:167], v[196:199], v[16:19]
	v_mfma_f32_16x16x32_bf16 v[8:11], v[172:175], v[196:199], v[8:11]
	v_mfma_f32_16x16x32_bf16 v[4:7], v[164:167], v[204:207], v[4:7]
	v_mfma_f32_16x16x32_bf16 v[0:3], v[172:175], v[204:207], v[0:3]
	v_mfma_f32_16x16x32_bf16 v[48:51], v[168:171], v[184:187], v[48:51]
	v_mfma_f32_16x16x32_bf16 v[40:43], v[176:179], v[184:187], v[40:43]
	v_mfma_f32_16x16x32_bf16 v[32:35], v[168:171], v[192:195], v[32:35]
	v_mfma_f32_16x16x32_bf16 v[24:27], v[176:179], v[192:195], v[24:27]
	v_mfma_f32_16x16x32_bf16 v[16:19], v[168:171], v[200:203], v[16:19]
	v_mfma_f32_16x16x32_bf16 v[8:11], v[176:179], v[200:203], v[8:11]
	v_mfma_f32_16x16x32_bf16 v[4:7], v[168:171], v[208:211], v[4:7]
	v_mfma_f32_16x16x32_bf16 v[0:3], v[176:179], v[208:211], v[0:3]
	s_barrier
	s_andn2_b64 vcc, exec, s[48:49]
	s_mov_b64 s[50:51], -1
	s_mov_b64 s[48:49], 0
	s_mov_b64 s[52:53], 0x100
	s_cbranch_vccz .LBB0_585
	s_and_b64 vcc, exec, s[22:23]
	s_cbranch_vccz .LBB0_588
	s_barrier

.LBB0_661:
	s_add_u32 s64, s44, 0x100
	s_addc_u32 s65, s45, 0
	s_mov_b32 s66, -2
	s_waitcnt lgkmcnt(0)
	s_waitcnt vmcnt(0)
	ds_read_b128 v[144:147], v151
	ds_read_b128 v[156:159], v151 offset:1024
	ds_read_b128 v[160:163], v151 offset:2048
	ds_read_b128 v[164:167], v151 offset:3072
	ds_read_b128 v[168:171], v152
	ds_read_b128 v[172:175], v152 offset:1024
	ds_read_b128 v[176:179], v152 offset:2048
	ds_read_b128 v[180:183], v152 offset:3072
	s_add_u32 s44, s42, 0x100
	s_addc_u32 s45, s43, 0
	s_cmp_eq_u32 s66, 40
	s_cselect_b32 s69, s1, s45
	s_cselect_b32 s68, s0, s44
	s_cselect_b32 s47, s41, s65
	s_cselect_b32 s46, s40, s64
	v_lshl_add_u64 v[216:217], s[42:43], 0, v[136:137]
	s_add_i32 m0, s48, 0xc000
	ds_read_b128 v[184:187], v153
	ds_read_b128 v[188:191], v153 offset:1024
	ds_read_b128 v[192:195], v153 offset:2048
	ds_read_b128 v[196:199], v153 offset:3072
	ds_read_b128 v[200:203], v153 offset:4096
	ds_read_b128 v[204:207], v153 offset:5120
	ds_read_b128 v[208:211], v153 offset:6144
	ds_read_b128 v[212:215], v153 offset:7168
	global_load_lds_dwordx4 v[216:217], off
	s_add_i32 m0, s48, 0xe000
	v_lshl_add_u64 v[216:217], s[42:43], 0, v[138:139]
	global_load_lds_dwordx4 v[216:217], off
	s_waitcnt vmcnt(8) lgkmcnt(0)
	s_barrier
	v_mfma_f32_16x16x32_bf16 v[124:127], v[144:147], v[184:187], 0
	v_mfma_f32_16x16x32_bf16 v[120:123], v[160:163], v[184:187], 0
	v_mfma_f32_16x16x32_bf16 v[108:111], v[144:147], v[192:195], 0
	v_mfma_f32_16x16x32_bf16 v[104:107], v[160:163], v[192:195], 0
	v_mfma_f32_16x16x32_bf16 v[92:95], v[144:147], v[200:203], 0
	v_mfma_f32_16x16x32_bf16 v[88:91], v[160:163], v[200:203], 0
	v_mfma_f32_16x16x32_bf16 v[76:79], v[144:147], v[208:211], 0
	v_mfma_f32_16x16x32_bf16 v[72:75], v[160:163], v[208:211], 0
	v_mfma_f32_16x16x32_bf16 v[124:127], v[156:159], v[188:191], v[124:127]
	v_mfma_f32_16x16x32_bf16 v[120:123], v[164:167], v[188:191], v[120:123]
	v_mfma_f32_16x16x32_bf16 v[108:111], v[156:159], v[196:199], v[108:111]
	v_mfma_f32_16x16x32_bf16 v[104:107], v[164:167], v[196:199], v[104:107]
	v_mfma_f32_16x16x32_bf16 v[92:95], v[156:159], v[204:207], v[92:95]
	v_mfma_f32_16x16x32_bf16 v[88:91], v[164:167], v[204:207], v[88:91]
	v_mfma_f32_16x16x32_bf16 v[76:79], v[156:159], v[212:215], v[76:79]
	v_mfma_f32_16x16x32_bf16 v[72:75], v[164:167], v[212:215], v[72:75]
	v_mfma_f32_16x16x32_bf16 v[116:119], v[168:171], v[184:187], 0
	v_mfma_f32_16x16x32_bf16 v[112:115], v[176:179], v[184:187], 0
	v_mfma_f32_16x16x32_bf16 v[100:103], v[168:171], v[192:195], 0
	v_mfma_f32_16x16x32_bf16 v[96:99], v[176:179], v[192:195], 0
	v_mfma_f32_16x16x32_bf16 v[84:87], v[168:171], v[200:203], 0
	v_mfma_f32_16x16x32_bf16 v[80:83], v[176:179], v[200:203], 0
	v_mfma_f32_16x16x32_bf16 v[68:71], v[168:171], v[208:211], 0
	v_mfma_f32_16x16x32_bf16 v[64:67], v[176:179], v[208:211], 0
	v_mfma_f32_16x16x32_bf16 v[116:119], v[172:175], v[188:191], v[116:119]
	v_mfma_f32_16x16x32_bf16 v[112:115], v[180:183], v[188:191], v[112:115]
	v_mfma_f32_16x16x32_bf16 v[100:103], v[172:175], v[196:199], v[100:103]
	v_mfma_f32_16x16x32_bf16 v[96:99], v[180:183], v[196:199], v[96:99]
	v_mfma_f32_16x16x32_bf16 v[84:87], v[172:175], v[204:207], v[84:87]
	v_mfma_f32_16x16x32_bf16 v[80:83], v[180:183], v[204:207], v[80:83]
	v_mfma_f32_16x16x32_bf16 v[68:71], v[172:175], v[212:215], v[68:71]
	v_mfma_f32_16x16x32_bf16 v[64:67], v[180:183], v[212:215], v[64:67]
	s_barrier
	s_add_i32 s42, s59, s35
	v_lshl_add_u64 v[216:217], s[46:47], 0, v[130:131]
	s_mov_b32 m0, s42
	ds_read_b128 v[184:187], v153 offset:16384
	ds_read_b128 v[188:191], v153 offset:17408
	ds_read_b128 v[192:195], v153 offset:18432
	ds_read_b128 v[196:199], v153 offset:19456
	ds_read_b128 v[200:203], v153 offset:20480
	ds_read_b128 v[204:207], v153 offset:21504
	ds_read_b128 v[208:211], v153 offset:22528
	ds_read_b128 v[212:215], v153 offset:23552
	global_load_lds_dwordx4 v[216:217], off
	s_add_i32 m0, s42, 0x2000
	s_add_u32 s42, s46, 0xb0000
	v_lshl_add_u64 v[220:221], s[46:47], 0, v[134:135]
	s_addc_u32 s43, s47, 0
	s_add_i32 s67, s60, s35
	global_load_lds_dwordx4 v[220:221], off
	v_lshl_add_u64 v[224:225], s[42:43], 0, v[130:131]
	s_mov_b32 m0, s67
	v_lshl_add_u64 v[226:227], s[68:69], 0, v[132:133]
	global_load_lds_dwordx4 v[224:225], off
	v_lshl_add_u64 v[224:225], s[42:43], 0, v[134:135]
	s_add_i32 m0, s67, 0x2000
	v_lshl_add_u64 v[228:229], v[226:227], 0, s[14:15]
	global_load_lds_dwordx4 v[224:225], off
	s_mov_b32 m0, s48
	v_lshl_add_u64 v[224:225], s[68:69], 0, v[128:129]
	global_load_lds_dwordx4 v[224:225], off
	s_mov_b32 m0, s49
	s_nop 0
	global_load_lds_dwordx4 v[228:229], off
	s_waitcnt vmcnt(8) lgkmcnt(0)
	s_barrier
	v_mfma_f32_16x16x32_bf16 v[60:63], v[144:147], v[184:187], 0
	v_mfma_f32_16x16x32_bf16 v[56:59], v[160:163], v[184:187], 0
	v_mfma_f32_16x16x32_bf16 v[44:47], v[144:147], v[192:195], 0
	v_mfma_f32_16x16x32_bf16 v[40:43], v[160:163], v[192:195], 0
	v_mfma_f32_16x16x32_bf16 v[28:31], v[144:147], v[200:203], 0
	v_mfma_f32_16x16x32_bf16 v[24:27], v[160:163], v[200:203], 0
	v_mfma_f32_16x16x32_bf16 v[12:15], v[144:147], v[208:211], 0
	v_mfma_f32_16x16x32_bf16 v[8:11], v[160:163], v[208:211], 0
	v_mfma_f32_16x16x32_bf16 v[60:63], v[156:159], v[188:191], v[60:63]
	v_mfma_f32_16x16x32_bf16 v[56:59], v[164:167], v[188:191], v[56:59]
	v_mfma_f32_16x16x32_bf16 v[44:47], v[156:159], v[196:199], v[44:47]
	v_mfma_f32_16x16x32_bf16 v[40:43], v[164:167], v[196:199], v[40:43]
	v_mfma_f32_16x16x32_bf16 v[28:31], v[156:159], v[204:207], v[28:31]
	v_mfma_f32_16x16x32_bf16 v[24:27], v[164:167], v[204:207], v[24:27]
	v_mfma_f32_16x16x32_bf16 v[12:15], v[156:159], v[212:215], v[12:15]
	v_mfma_f32_16x16x32_bf16 v[8:11], v[164:167], v[212:215], v[8:11]
	v_mfma_f32_16x16x32_bf16 v[52:55], v[168:171], v[184:187], 0
	v_mfma_f32_16x16x32_bf16 v[48:51], v[176:179], v[184:187], 0
	v_mfma_f32_16x16x32_bf16 v[36:39], v[168:171], v[192:195], 0
	v_mfma_f32_16x16x32_bf16 v[32:35], v[176:179], v[192:195], 0
	v_mfma_f32_16x16x32_bf16 v[20:23], v[168:171], v[200:203], 0
	v_mfma_f32_16x16x32_bf16 v[16:19], v[176:179], v[200:203], 0
	v_mfma_f32_16x16x32_bf16 v[4:7], v[168:171], v[208:211], 0
	v_mfma_f32_16x16x32_bf16 v[0:3], v[176:179], v[208:211], 0
	v_mfma_f32_16x16x32_bf16 v[52:55], v[172:175], v[188:191], v[52:55]
	v_mfma_f32_16x16x32_bf16 v[48:51], v[180:183], v[188:191], v[48:51]
	v_mfma_f32_16x16x32_bf16 v[36:39], v[172:175], v[196:199], v[36:39]
	v_mfma_f32_16x16x32_bf16 v[32:35], v[180:183], v[196:199], v[32:35]
	v_mfma_f32_16x16x32_bf16 v[20:23], v[172:175], v[204:207], v[20:23]
	v_mfma_f32_16x16x32_bf16 v[16:19], v[180:183], v[204:207], v[16:19]
	v_mfma_f32_16x16x32_bf16 v[4:7], v[172:175], v[212:215], v[4:7]
	v_mfma_f32_16x16x32_bf16 v[0:3], v[180:183], v[212:215], v[0:3]
	s_barrier
	s_add_i32 s42, 0, 0x18000
	v_add_u32_e32 v155, s42, v149
	s_add_i32 s67, 0, 0x1c000
	ds_read_b128 v[144:147], v155
	ds_read_b128 v[156:159], v155 offset:1024
	ds_read_b128 v[160:163], v155 offset:2048
	ds_read_b128 v[164:167], v155 offset:3072
	v_add_u32_e32 v155, s67, v149
	ds_read_b128 v[168:171], v155
	ds_read_b128 v[172:175], v155 offset:1024
	ds_read_b128 v[176:179], v155 offset:2048
	ds_read_b128 v[180:183], v155 offset:3072
	s_mov_b32 m0, s50
	v_lshl_add_u64 v[228:229], v[224:225], 0, s[12:13]
	ds_read_b128 v[184:187], v153 offset:32768
	ds_read_b128 v[188:191], v153 offset:33792
	ds_read_b128 v[192:195], v153 offset:34816
	ds_read_b128 v[196:199], v153 offset:35840
	ds_read_b128 v[200:203], v153 offset:36864
	ds_read_b128 v[204:207], v153 offset:37888
	ds_read_b128 v[208:211], v153 offset:38912
	ds_read_b128 v[212:215], v153 offset:39936
	global_load_lds_dwordx4 v[228:229], off
	s_mov_b32 m0, s51
	v_lshl_add_u64 v[228:229], v[226:227], 0, s[16:17]
	global_load_lds_dwordx4 v[228:229], off
	s_waitcnt vmcnt(8) lgkmcnt(0)
	s_barrier
	v_mfma_f32_16x16x32_bf16 v[124:127], v[144:147], v[184:187], v[124:127]
	v_mfma_f32_16x16x32_bf16 v[120:123], v[160:163], v[184:187], v[120:123]
	v_mfma_f32_16x16x32_bf16 v[108:111], v[144:147], v[192:195], v[108:111]
	v_mfma_f32_16x16x32_bf16 v[104:107], v[160:163], v[192:195], v[104:107]
	v_mfma_f32_16x16x32_bf16 v[92:95], v[144:147], v[200:203], v[92:95]
	v_mfma_f32_16x16x32_bf16 v[88:91], v[160:163], v[200:203], v[88:91]
	v_mfma_f32_16x16x32_bf16 v[76:79], v[144:147], v[208:211], v[76:79]
	v_mfma_f32_16x16x32_bf16 v[72:75], v[160:163], v[208:211], v[72:75]
	v_mfma_f32_16x16x32_bf16 v[124:127], v[156:159], v[188:191], v[124:127]
	v_mfma_f32_16x16x32_bf16 v[120:123], v[164:167], v[188:191], v[120:123]
	v_mfma_f32_16x16x32_bf16 v[108:111], v[156:159], v[196:199], v[108:111]
	v_mfma_f32_16x16x32_bf16 v[104:107], v[164:167], v[196:199], v[104:107]
	v_mfma_f32_16x16x32_bf16 v[92:95], v[156:159], v[204:207], v[92:95]
	v_mfma_f32_16x16x32_bf16 v[88:91], v[164:167], v[204:207], v[88:91]
	v_mfma_f32_16x16x32_bf16 v[76:79], v[156:159], v[212:215], v[76:79]
	v_mfma_f32_16x16x32_bf16 v[72:75], v[164:167], v[212:215], v[72:75]
	v_mfma_f32_16x16x32_bf16 v[116:119], v[168:171], v[184:187], v[116:119]
	v_mfma_f32_16x16x32_bf16 v[112:115], v[176:179], v[184:187], v[112:115]
	v_mfma_f32_16x16x32_bf16 v[100:103], v[168:171], v[192:195], v[100:103]
	v_mfma_f32_16x16x32_bf16 v[96:99], v[176:179], v[192:195], v[96:99]
	v_mfma_f32_16x16x32_bf16 v[84:87], v[168:171], v[200:203], v[84:87]
	v_mfma_f32_16x16x32_bf16 v[80:83], v[176:179], v[200:203], v[80:83]
	v_mfma_f32_16x16x32_bf16 v[68:71], v[168:171], v[208:211], v[68:71]
	v_mfma_f32_16x16x32_bf16 v[64:67], v[176:179], v[208:211], v[64:67]
	v_mfma_f32_16x16x32_bf16 v[116:119], v[172:175], v[188:191], v[116:119]
	v_mfma_f32_16x16x32_bf16 v[112:115], v[180:183], v[188:191], v[112:115]
	v_mfma_f32_16x16x32_bf16 v[100:103], v[172:175], v[196:199], v[100:103]
	v_mfma_f32_16x16x32_bf16 v[96:99], v[180:183], v[196:199], v[96:99]
	v_mfma_f32_16x16x32_bf16 v[84:87], v[172:175], v[204:207], v[84:87]
	v_mfma_f32_16x16x32_bf16 v[80:83], v[180:183], v[204:207], v[80:83]
	v_mfma_f32_16x16x32_bf16 v[68:71], v[172:175], v[212:215], v[68:71]
	v_mfma_f32_16x16x32_bf16 v[64:67], v[180:183], v[212:215], v[64:67]
	s_barrier
	s_add_i32 s42, s42, s35
	v_lshl_add_u64 v[216:217], v[216:217], 0, s[24:25]
	s_mov_b32 m0, s42
	ds_read_b128 v[184:187], v153 offset:49152
	ds_read_b128 v[188:191], v153 offset:50176
	ds_read_b128 v[192:195], v153 offset:51200
	ds_read_b128 v[196:199], v153 offset:52224
	ds_read_b128 v[200:203], v153 offset:53248
	ds_read_b128 v[204:207], v153 offset:54272
	ds_read_b128 v[208:211], v153 offset:55296
	ds_read_b128 v[212:215], v153 offset:56320
	global_load_lds_dwordx4 v[216:217], off
	s_add_i32 m0, s42, 0x2000
	s_add_u32 s42, s46, 0xb0080
	v_lshl_add_u64 v[216:217], v[220:221], 0, s[24:25]
	s_addc_u32 s43, s47, 0
	s_add_i32 s46, s67, s35
	global_load_lds_dwordx4 v[216:217], off
	s_mov_b32 m0, s46
	v_lshl_add_u64 v[216:217], s[42:43], 0, v[130:131]
	global_load_lds_dwordx4 v[216:217], off
	s_add_i32 m0, s46, 0x2000
	v_lshl_add_u64 v[216:217], s[42:43], 0, v[134:135]
	global_load_lds_dwordx4 v[216:217], off
	s_mov_b32 m0, s53
	v_lshl_add_u64 v[216:217], v[224:225], 0, s[24:25]
	global_load_lds_dwordx4 v[216:217], off
	s_mov_b32 m0, s54
	v_lshl_add_u64 v[216:217], v[226:227], 0, s[36:37]
	global_load_lds_dwordx4 v[216:217], off
	s_waitcnt vmcnt(8) lgkmcnt(0)
	s_barrier
	v_mfma_f32_16x16x32_bf16 v[60:63], v[144:147], v[184:187], v[60:63]
	v_mfma_f32_16x16x32_bf16 v[56:59], v[160:163], v[184:187], v[56:59]
	v_mfma_f32_16x16x32_bf16 v[44:47], v[144:147], v[192:195], v[44:47]
	v_mfma_f32_16x16x32_bf16 v[40:43], v[160:163], v[192:195], v[40:43]
	v_mfma_f32_16x16x32_bf16 v[28:31], v[144:147], v[200:203], v[28:31]
	v_mfma_f32_16x16x32_bf16 v[24:27], v[160:163], v[200:203], v[24:27]
	v_mfma_f32_16x16x32_bf16 v[12:15], v[144:147], v[208:211], v[12:15]
	v_mfma_f32_16x16x32_bf16 v[8:11], v[160:163], v[208:211], v[8:11]
	v_mfma_f32_16x16x32_bf16 v[60:63], v[156:159], v[188:191], v[60:63]
	v_mfma_f32_16x16x32_bf16 v[56:59], v[164:167], v[188:191], v[56:59]
	v_mfma_f32_16x16x32_bf16 v[44:47], v[156:159], v[196:199], v[44:47]
	v_mfma_f32_16x16x32_bf16 v[40:43], v[164:167], v[196:199], v[40:43]
	v_mfma_f32_16x16x32_bf16 v[28:31], v[156:159], v[204:207], v[28:31]
	v_mfma_f32_16x16x32_bf16 v[24:27], v[164:167], v[204:207], v[24:27]
	v_mfma_f32_16x16x32_bf16 v[12:15], v[156:159], v[212:215], v[12:15]
	v_mfma_f32_16x16x32_bf16 v[8:11], v[164:167], v[212:215], v[8:11]
	v_mfma_f32_16x16x32_bf16 v[52:55], v[168:171], v[184:187], v[52:55]
	v_mfma_f32_16x16x32_bf16 v[48:51], v[176:179], v[184:187], v[48:51]
	v_mfma_f32_16x16x32_bf16 v[36:39], v[168:171], v[192:195], v[36:39]
	v_mfma_f32_16x16x32_bf16 v[32:35], v[176:179], v[192:195], v[32:35]
	v_mfma_f32_16x16x32_bf16 v[20:23], v[168:171], v[200:203], v[20:23]
	v_mfma_f32_16x16x32_bf16 v[16:19], v[176:179], v[200:203], v[16:19]
	v_mfma_f32_16x16x32_bf16 v[4:7], v[168:171], v[208:211], v[4:7]
	v_mfma_f32_16x16x32_bf16 v[0:3], v[176:179], v[208:211], v[0:3]
	v_mfma_f32_16x16x32_bf16 v[52:55], v[172:175], v[188:191], v[52:55]
	v_mfma_f32_16x16x32_bf16 v[48:51], v[180:183], v[188:191], v[48:51]
	v_mfma_f32_16x16x32_bf16 v[36:39], v[172:175], v[196:199], v[36:39]
	v_mfma_f32_16x16x32_bf16 v[32:35], v[180:183], v[196:199], v[32:35]
	v_mfma_f32_16x16x32_bf16 v[20:23], v[172:175], v[204:207], v[20:23]
	v_mfma_f32_16x16x32_bf16 v[16:19], v[180:183], v[204:207], v[16:19]
	v_mfma_f32_16x16x32_bf16 v[4:7], v[172:175], v[212:215], v[4:7]
	v_mfma_f32_16x16x32_bf16 v[0:3], v[180:183], v[212:215], v[0:3]
	s_barrier
	s_add_i32 s66, s66, 2
	s_add_u32 s64, s64, 0x100
	s_addc_u32 s65, s65, 0
	s_cmp_gt_u32 s66, 41
	s_mov_b64 s[42:43], s[44:45]
.LBB0_662:
	ds_read_b128 v[144:147], v151
	ds_read_b128 v[156:159], v151 offset:1024
	ds_read_b128 v[160:163], v151 offset:2048
	ds_read_b128 v[164:167], v151 offset:3072
	ds_read_b128 v[168:171], v152
	ds_read_b128 v[172:175], v152 offset:1024
	ds_read_b128 v[176:179], v152 offset:2048
	ds_read_b128 v[180:183], v152 offset:3072
	s_add_u32 s44, s42, 0x100
	s_addc_u32 s45, s43, 0
	s_cmp_eq_u32 s66, 40
	s_cselect_b32 s69, s1, s45
	s_cselect_b32 s68, s0, s44
	s_cselect_b32 s47, s41, s65
	s_cselect_b32 s46, s40, s64
	v_lshl_add_u64 v[216:217], s[42:43], 0, v[136:137]
	s_add_i32 m0, s48, 0xc000
	ds_read_b128 v[184:187], v153
	ds_read_b128 v[188:191], v153 offset:1024
	ds_read_b128 v[192:195], v153 offset:2048
	ds_read_b128 v[196:199], v153 offset:3072
	ds_read_b128 v[200:203], v153 offset:4096
	ds_read_b128 v[204:207], v153 offset:5120
	ds_read_b128 v[208:211], v153 offset:6144
	ds_read_b128 v[212:215], v153 offset:7168
	global_load_lds_dwordx4 v[216:217], off
	s_add_i32 m0, s48, 0xe000
	v_lshl_add_u64 v[216:217], s[42:43], 0, v[138:139]
	global_load_lds_dwordx4 v[216:217], off
	s_waitcnt vmcnt(8) lgkmcnt(0)
	s_barrier
	v_mfma_f32_16x16x32_bf16 v[124:127], v[144:147], v[184:187], v[124:127]
	v_mfma_f32_16x16x32_bf16 v[120:123], v[160:163], v[184:187], v[120:123]
	v_mfma_f32_16x16x32_bf16 v[108:111], v[144:147], v[192:195], v[108:111]
	v_mfma_f32_16x16x32_bf16 v[104:107], v[160:163], v[192:195], v[104:107]
	v_mfma_f32_16x16x32_bf16 v[92:95], v[144:147], v[200:203], v[92:95]
	v_mfma_f32_16x16x32_bf16 v[88:91], v[160:163], v[200:203], v[88:91]
	v_mfma_f32_16x16x32_bf16 v[76:79], v[144:147], v[208:211], v[76:79]
	v_mfma_f32_16x16x32_bf16 v[72:75], v[160:163], v[208:211], v[72:75]
	v_mfma_f32_16x16x32_bf16 v[124:127], v[156:159], v[188:191], v[124:127]
	v_mfma_f32_16x16x32_bf16 v[120:123], v[164:167], v[188:191], v[120:123]
	v_mfma_f32_16x16x32_bf16 v[108:111], v[156:159], v[196:199], v[108:111]
	v_mfma_f32_16x16x32_bf16 v[104:107], v[164:167], v[196:199], v[104:107]
	v_mfma_f32_16x16x32_bf16 v[92:95], v[156:159], v[204:207], v[92:95]
	v_mfma_f32_16x16x32_bf16 v[88:91], v[164:167], v[204:207], v[88:91]
	v_mfma_f32_16x16x32_bf16 v[76:79], v[156:159], v[212:215], v[76:79]
	v_mfma_f32_16x16x32_bf16 v[72:75], v[164:167], v[212:215], v[72:75]
	v_mfma_f32_16x16x32_bf16 v[116:119], v[168:171], v[184:187], v[116:119]
	v_mfma_f32_16x16x32_bf16 v[112:115], v[176:179], v[184:187], v[112:115]
	v_mfma_f32_16x16x32_bf16 v[100:103], v[168:171], v[192:195], v[100:103]
	v_mfma_f32_16x16x32_bf16 v[96:99], v[176:179], v[192:195], v[96:99]
	v_mfma_f32_16x16x32_bf16 v[84:87], v[168:171], v[200:203], v[84:87]
	v_mfma_f32_16x16x32_bf16 v[80:83], v[176:179], v[200:203], v[80:83]
	v_mfma_f32_16x16x32_bf16 v[68:71], v[168:171], v[208:211], v[68:71]
	v_mfma_f32_16x16x32_bf16 v[64:67], v[176:179], v[208:211], v[64:67]
	v_mfma_f32_16x16x32_bf16 v[116:119], v[172:175], v[188:191], v[116:119]
	v_mfma_f32_16x16x32_bf16 v[112:115], v[180:183], v[188:191], v[112:115]
	v_mfma_f32_16x16x32_bf16 v[100:103], v[172:175], v[196:199], v[100:103]
	v_mfma_f32_16x16x32_bf16 v[96:99], v[180:183], v[196:199], v[96:99]
	v_mfma_f32_16x16x32_bf16 v[84:87], v[172:175], v[204:207], v[84:87]
	v_mfma_f32_16x16x32_bf16 v[80:83], v[180:183], v[204:207], v[80:83]
	v_mfma_f32_16x16x32_bf16 v[68:71], v[172:175], v[212:215], v[68:71]
	v_mfma_f32_16x16x32_bf16 v[64:67], v[180:183], v[212:215], v[64:67]
	s_barrier
	s_add_i32 s42, s59, s35
	v_lshl_add_u64 v[216:217], s[46:47], 0, v[130:131]
	s_mov_b32 m0, s42
	ds_read_b128 v[184:187], v153 offset:16384
	ds_read_b128 v[188:191], v153 offset:17408
	ds_read_b128 v[192:195], v153 offset:18432
	ds_read_b128 v[196:199], v153 offset:19456
	ds_read_b128 v[200:203], v153 offset:20480
	ds_read_b128 v[204:207], v153 offset:21504
	ds_read_b128 v[208:211], v153 offset:22528
	ds_read_b128 v[212:215], v153 offset:23552
	global_load_lds_dwordx4 v[216:217], off
	s_add_i32 m0, s42, 0x2000
	s_add_u32 s42, s46, 0xb0000
	v_lshl_add_u64 v[220:221], s[46:47], 0, v[134:135]
	s_addc_u32 s43, s47, 0
	s_add_i32 s67, s60, s35
	global_load_lds_dwordx4 v[220:221], off
	v_lshl_add_u64 v[224:225], s[42:43], 0, v[130:131]
	s_mov_b32 m0, s67
	v_lshl_add_u64 v[226:227], s[68:69], 0, v[132:133]
	global_load_lds_dwordx4 v[224:225], off
	v_lshl_add_u64 v[224:225], s[42:43], 0, v[134:135]
	s_add_i32 m0, s67, 0x2000
	v_lshl_add_u64 v[228:229], v[226:227], 0, s[14:15]
	global_load_lds_dwordx4 v[224:225], off
	s_mov_b32 m0, s48
	v_lshl_add_u64 v[224:225], s[68:69], 0, v[128:129]
	global_load_lds_dwordx4 v[224:225], off
	s_mov_b32 m0, s49
	s_nop 0
	global_load_lds_dwordx4 v[228:229], off
	s_waitcnt vmcnt(8) lgkmcnt(0)
	s_barrier
	v_mfma_f32_16x16x32_bf16 v[60:63], v[144:147], v[184:187], v[60:63]
	v_mfma_f32_16x16x32_bf16 v[56:59], v[160:163], v[184:187], v[56:59]
	v_mfma_f32_16x16x32_bf16 v[44:47], v[144:147], v[192:195], v[44:47]
	v_mfma_f32_16x16x32_bf16 v[40:43], v[160:163], v[192:195], v[40:43]
	v_mfma_f32_16x16x32_bf16 v[28:31], v[144:147], v[200:203], v[28:31]
	v_mfma_f32_16x16x32_bf16 v[24:27], v[160:163], v[200:203], v[24:27]
	v_mfma_f32_16x16x32_bf16 v[12:15], v[144:147], v[208:211], v[12:15]
	v_mfma_f32_16x16x32_bf16 v[8:11], v[160:163], v[208:211], v[8:11]
	v_mfma_f32_16x16x32_bf16 v[60:63], v[156:159], v[188:191], v[60:63]
	v_mfma_f32_16x16x32_bf16 v[56:59], v[164:167], v[188:191], v[56:59]
	v_mfma_f32_16x16x32_bf16 v[44:47], v[156:159], v[196:199], v[44:47]
	v_mfma_f32_16x16x32_bf16 v[40:43], v[164:167], v[196:199], v[40:43]
	v_mfma_f32_16x16x32_bf16 v[28:31], v[156:159], v[204:207], v[28:31]
	v_mfma_f32_16x16x32_bf16 v[24:27], v[164:167], v[204:207], v[24:27]
	v_mfma_f32_16x16x32_bf16 v[12:15], v[156:159], v[212:215], v[12:15]
	v_mfma_f32_16x16x32_bf16 v[8:11], v[164:167], v[212:215], v[8:11]
	v_mfma_f32_16x16x32_bf16 v[52:55], v[168:171], v[184:187], v[52:55]
	v_mfma_f32_16x16x32_bf16 v[48:51], v[176:179], v[184:187], v[48:51]
	v_mfma_f32_16x16x32_bf16 v[36:39], v[168:171], v[192:195], v[36:39]
	v_mfma_f32_16x16x32_bf16 v[32:35], v[176:179], v[192:195], v[32:35]
	v_mfma_f32_16x16x32_bf16 v[20:23], v[168:171], v[200:203], v[20:23]
	v_mfma_f32_16x16x32_bf16 v[16:19], v[176:179], v[200:203], v[16:19]
	v_mfma_f32_16x16x32_bf16 v[4:7], v[168:171], v[208:211], v[4:7]
	v_mfma_f32_16x16x32_bf16 v[0:3], v[176:179], v[208:211], v[0:3]
	v_mfma_f32_16x16x32_bf16 v[52:55], v[172:175], v[188:191], v[52:55]
	v_mfma_f32_16x16x32_bf16 v[48:51], v[180:183], v[188:191], v[48:51]
	v_mfma_f32_16x16x32_bf16 v[36:39], v[172:175], v[196:199], v[36:39]
	v_mfma_f32_16x16x32_bf16 v[32:35], v[180:183], v[196:199], v[32:35]
	v_mfma_f32_16x16x32_bf16 v[20:23], v[172:175], v[204:207], v[20:23]
	v_mfma_f32_16x16x32_bf16 v[16:19], v[180:183], v[204:207], v[16:19]
	v_mfma_f32_16x16x32_bf16 v[4:7], v[172:175], v[212:215], v[4:7]
	v_mfma_f32_16x16x32_bf16 v[0:3], v[180:183], v[212:215], v[0:3]
	s_barrier
	s_add_i32 s42, 0, 0x18000
	v_add_u32_e32 v155, s42, v149
	s_add_i32 s67, 0, 0x1c000
	ds_read_b128 v[144:147], v155
	ds_read_b128 v[156:159], v155 offset:1024
	ds_read_b128 v[160:163], v155 offset:2048
	ds_read_b128 v[164:167], v155 offset:3072
	v_add_u32_e32 v155, s67, v149
	ds_read_b128 v[168:171], v155
	ds_read_b128 v[172:175], v155 offset:1024
	ds_read_b128 v[176:179], v155 offset:2048
	ds_read_b128 v[180:183], v155 offset:3072
	s_mov_b32 m0, s50
	v_lshl_add_u64 v[228:229], v[224:225], 0, s[12:13]
	ds_read_b128 v[184:187], v153 offset:32768
	ds_read_b128 v[188:191], v153 offset:33792
	ds_read_b128 v[192:195], v153 offset:34816
	ds_read_b128 v[196:199], v153 offset:35840
	ds_read_b128 v[200:203], v153 offset:36864
	ds_read_b128 v[204:207], v153 offset:37888
	ds_read_b128 v[208:211], v153 offset:38912
	ds_read_b128 v[212:215], v153 offset:39936
	global_load_lds_dwordx4 v[228:229], off
	s_mov_b32 m0, s51
	v_lshl_add_u64 v[228:229], v[226:227], 0, s[16:17]
	global_load_lds_dwordx4 v[228:229], off
	s_waitcnt vmcnt(8) lgkmcnt(0)
	s_barrier
	v_mfma_f32_16x16x32_bf16 v[124:127], v[144:147], v[184:187], v[124:127]
	v_mfma_f32_16x16x32_bf16 v[120:123], v[160:163], v[184:187], v[120:123]
	v_mfma_f32_16x16x32_bf16 v[108:111], v[144:147], v[192:195], v[108:111]
	v_mfma_f32_16x16x32_bf16 v[104:107], v[160:163], v[192:195], v[104:107]
	v_mfma_f32_16x16x32_bf16 v[92:95], v[144:147], v[200:203], v[92:95]
	v_mfma_f32_16x16x32_bf16 v[88:91], v[160:163], v[200:203], v[88:91]
	v_mfma_f32_16x16x32_bf16 v[76:79], v[144:147], v[208:211], v[76:79]
	v_mfma_f32_16x16x32_bf16 v[72:75], v[160:163], v[208:211], v[72:75]
	v_mfma_f32_16x16x32_bf16 v[124:127], v[156:159], v[188:191], v[124:127]
	v_mfma_f32_16x16x32_bf16 v[120:123], v[164:167], v[188:191], v[120:123]
	v_mfma_f32_16x16x32_bf16 v[108:111], v[156:159], v[196:199], v[108:111]
	v_mfma_f32_16x16x32_bf16 v[104:107], v[164:167], v[196:199], v[104:107]
	v_mfma_f32_16x16x32_bf16 v[92:95], v[156:159], v[204:207], v[92:95]
	v_mfma_f32_16x16x32_bf16 v[88:91], v[164:167], v[204:207], v[88:91]
	v_mfma_f32_16x16x32_bf16 v[76:79], v[156:159], v[212:215], v[76:79]
	v_mfma_f32_16x16x32_bf16 v[72:75], v[164:167], v[212:215], v[72:75]
	v_mfma_f32_16x16x32_bf16 v[116:119], v[168:171], v[184:187], v[116:119]
	v_mfma_f32_16x16x32_bf16 v[112:115], v[176:179], v[184:187], v[112:115]
	v_mfma_f32_16x16x32_bf16 v[100:103], v[168:171], v[192:195], v[100:103]
	v_mfma_f32_16x16x32_bf16 v[96:99], v[176:179], v[192:195], v[96:99]
	v_mfma_f32_16x16x32_bf16 v[84:87], v[168:171], v[200:203], v[84:87]
	v_mfma_f32_16x16x32_bf16 v[80:83], v[176:179], v[200:203], v[80:83]
	v_mfma_f32_16x16x32_bf16 v[68:71], v[168:171], v[208:211], v[68:71]
	v_mfma_f32_16x16x32_bf16 v[64:67], v[176:179], v[208:211], v[64:67]
	v_mfma_f32_16x16x32_bf16 v[116:119], v[172:175], v[188:191], v[116:119]
	v_mfma_f32_16x16x32_bf16 v[112:115], v[180:183], v[188:191], v[112:115]
	v_mfma_f32_16x16x32_bf16 v[100:103], v[172:175], v[196:199], v[100:103]
	v_mfma_f32_16x16x32_bf16 v[96:99], v[180:183], v[196:199], v[96:99]
	v_mfma_f32_16x16x32_bf16 v[84:87], v[172:175], v[204:207], v[84:87]
	v_mfma_f32_16x16x32_bf16 v[80:83], v[180:183], v[204:207], v[80:83]
	v_mfma_f32_16x16x32_bf16 v[68:71], v[172:175], v[212:215], v[68:71]
	v_mfma_f32_16x16x32_bf16 v[64:67], v[180:183], v[212:215], v[64:67]
	s_barrier
	s_add_i32 s42, s42, s35
	v_lshl_add_u64 v[216:217], v[216:217], 0, s[24:25]
	s_mov_b32 m0, s42
	ds_read_b128 v[184:187], v153 offset:49152
	ds_read_b128 v[188:191], v153 offset:50176
	ds_read_b128 v[192:195], v153 offset:51200
	ds_read_b128 v[196:199], v153 offset:52224
	ds_read_b128 v[200:203], v153 offset:53248
	ds_read_b128 v[204:207], v153 offset:54272
	ds_read_b128 v[208:211], v153 offset:55296
	ds_read_b128 v[212:215], v153 offset:56320
	global_load_lds_dwordx4 v[216:217], off
	s_add_i32 m0, s42, 0x2000
	s_add_u32 s42, s46, 0xb0080
	v_lshl_add_u64 v[216:217], v[220:221], 0, s[24:25]
	s_addc_u32 s43, s47, 0
	s_add_i32 s46, s67, s35
	global_load_lds_dwordx4 v[216:217], off
	s_mov_b32 m0, s46
	v_lshl_add_u64 v[216:217], s[42:43], 0, v[130:131]
	global_load_lds_dwordx4 v[216:217], off
	s_add_i32 m0, s46, 0x2000
	v_lshl_add_u64 v[216:217], s[42:43], 0, v[134:135]
	global_load_lds_dwordx4 v[216:217], off
	s_mov_b32 m0, s53
	v_lshl_add_u64 v[216:217], v[224:225], 0, s[24:25]
	global_load_lds_dwordx4 v[216:217], off
	s_mov_b32 m0, s54
	v_lshl_add_u64 v[216:217], v[226:227], 0, s[36:37]
	global_load_lds_dwordx4 v[216:217], off
	s_waitcnt vmcnt(8) lgkmcnt(0)
	s_barrier
	v_mfma_f32_16x16x32_bf16 v[60:63], v[144:147], v[184:187], v[60:63]
	v_mfma_f32_16x16x32_bf16 v[56:59], v[160:163], v[184:187], v[56:59]
	v_mfma_f32_16x16x32_bf16 v[44:47], v[144:147], v[192:195], v[44:47]
	v_mfma_f32_16x16x32_bf16 v[40:43], v[160:163], v[192:195], v[40:43]
	v_mfma_f32_16x16x32_bf16 v[28:31], v[144:147], v[200:203], v[28:31]
	v_mfma_f32_16x16x32_bf16 v[24:27], v[160:163], v[200:203], v[24:27]
	v_mfma_f32_16x16x32_bf16 v[12:15], v[144:147], v[208:211], v[12:15]
	v_mfma_f32_16x16x32_bf16 v[8:11], v[160:163], v[208:211], v[8:11]
	v_mfma_f32_16x16x32_bf16 v[60:63], v[156:159], v[188:191], v[60:63]
	v_mfma_f32_16x16x32_bf16 v[56:59], v[164:167], v[188:191], v[56:59]
	v_mfma_f32_16x16x32_bf16 v[44:47], v[156:159], v[196:199], v[44:47]
	v_mfma_f32_16x16x32_bf16 v[40:43], v[164:167], v[196:199], v[40:43]
	v_mfma_f32_16x16x32_bf16 v[28:31], v[156:159], v[204:207], v[28:31]
	v_mfma_f32_16x16x32_bf16 v[24:27], v[164:167], v[204:207], v[24:27]
	v_mfma_f32_16x16x32_bf16 v[12:15], v[156:159], v[212:215], v[12:15]
	v_mfma_f32_16x16x32_bf16 v[8:11], v[164:167], v[212:215], v[8:11]
	v_mfma_f32_16x16x32_bf16 v[52:55], v[168:171], v[184:187], v[52:55]
	v_mfma_f32_16x16x32_bf16 v[48:51], v[176:179], v[184:187], v[48:51]
	v_mfma_f32_16x16x32_bf16 v[36:39], v[168:171], v[192:195], v[36:39]
	v_mfma_f32_16x16x32_bf16 v[32:35], v[176:179], v[192:195], v[32:35]
	v_mfma_f32_16x16x32_bf16 v[20:23], v[168:171], v[200:203], v[20:23]
	v_mfma_f32_16x16x32_bf16 v[16:19], v[176:179], v[200:203], v[16:19]
	v_mfma_f32_16x16x32_bf16 v[4:7], v[168:171], v[208:211], v[4:7]
	v_mfma_f32_16x16x32_bf16 v[0:3], v[176:179], v[208:211], v[0:3]
	v_mfma_f32_16x16x32_bf16 v[52:55], v[172:175], v[188:191], v[52:55]
	v_mfma_f32_16x16x32_bf16 v[48:51], v[180:183], v[188:191], v[48:51]
	v_mfma_f32_16x16x32_bf16 v[36:39], v[172:175], v[196:199], v[36:39]
	v_mfma_f32_16x16x32_bf16 v[32:35], v[180:183], v[196:199], v[32:35]
	v_mfma_f32_16x16x32_bf16 v[20:23], v[172:175], v[204:207], v[20:23]
	v_mfma_f32_16x16x32_bf16 v[16:19], v[180:183], v[204:207], v[16:19]
	v_mfma_f32_16x16x32_bf16 v[4:7], v[172:175], v[212:215], v[4:7]
	v_mfma_f32_16x16x32_bf16 v[0:3], v[180:183], v[212:215], v[0:3]
	s_barrier
	s_add_i32 s66, s66, 2
	s_add_u32 s64, s64, 0x100
	s_addc_u32 s65, s65, 0
	s_cmp_gt_u32 s66, 41
	s_mov_b64 s[42:43], s[44:45]
	s_cbranch_scc0 .LBB0_662

.LBB0_750:
	s_lshl_b32 s38, s65, 8
	s_ashr_i32 s39, s38, 31
	s_lshl_b64 s[38:39], s[38:39], 11
	s_add_u32 s38, s8, s38
	s_addc_u32 s39, s9, s39
	s_and_b64 s[40:41], s[4:5], exec
	s_cselect_b32 s43, s39, s45
	s_cselect_b32 s67, s38, s44
	s_ashr_i32 s37, s36, 31
	s_lshl_b64 s[40:41], s[36:37], 19
	s_add_u32 s40, s3, s40
	s_addc_u32 s41, s33, s41
	s_and_b64 s[48:49], s[4:5], exec
	s_cselect_b32 s37, s41, s47
	s_cselect_b32 s68, s40, s46
	s_add_u32 s69, s46, 0x100
	s_addc_u32 s71, s47, 0
	s_mov_b32 s72, -2
	s_waitcnt vmcnt(0)
	ds_read_b128 v[144:147], v189
	ds_read_b128 v[148:151], v189 offset:1024
	ds_read_b128 v[152:155], v189 offset:2048
	ds_read_b128 v[156:159], v189 offset:3072
	ds_read_b128 v[160:163], v190
	ds_read_b128 v[164:167], v190 offset:1024
	ds_read_b128 v[168:171], v190 offset:2048
	ds_read_b128 v[172:175], v190 offset:3072
	s_add_u32 s46, s44, 0x100
	s_addc_u32 s47, s45, 0
	s_cmp_eq_u32 s72, 12
	s_cselect_b32 s75, s43, s47
	s_cselect_b32 s74, s67, s46
	s_cselect_b32 s49, s37, s71
	s_cselect_b32 s48, s68, s69
	v_lshl_add_u64 v[184:185], s[44:45], 0, v[136:137]
	s_add_i32 m0, s51, 0xc000
	ds_read_b128 v[176:179], v191
	ds_read_b128 v[180:183], v191 offset:1024
	ds_read_b128 v[194:197], v191 offset:2048
	ds_read_b128 v[198:201], v191 offset:3072
	ds_read_b128 v[202:205], v191 offset:4096
	ds_read_b128 v[206:209], v191 offset:5120
	ds_read_b128 v[210:213], v191 offset:6144
	ds_read_b128 v[214:217], v191 offset:7168
	global_load_lds_dwordx4 v[184:185], off
	s_add_i32 m0, s51, 0xe000
	v_lshl_add_u64 v[184:185], s[44:45], 0, v[138:139]
	global_load_lds_dwordx4 v[184:185], off
	s_waitcnt vmcnt(8) lgkmcnt(0)
	s_barrier
	v_mfma_f32_16x16x32_bf16 v[124:127], v[144:147], v[176:179], 0
	v_mfma_f32_16x16x32_bf16 v[120:123], v[152:155], v[176:179], 0
	v_mfma_f32_16x16x32_bf16 v[108:111], v[144:147], v[194:197], 0
	v_mfma_f32_16x16x32_bf16 v[104:107], v[152:155], v[194:197], 0
	v_mfma_f32_16x16x32_bf16 v[92:95], v[144:147], v[202:205], 0
	v_mfma_f32_16x16x32_bf16 v[88:91], v[152:155], v[202:205], 0
	v_mfma_f32_16x16x32_bf16 v[76:79], v[144:147], v[210:213], 0
	v_mfma_f32_16x16x32_bf16 v[72:75], v[152:155], v[210:213], 0
	v_mfma_f32_16x16x32_bf16 v[124:127], v[148:151], v[180:183], v[124:127]
	v_mfma_f32_16x16x32_bf16 v[120:123], v[156:159], v[180:183], v[120:123]
	v_mfma_f32_16x16x32_bf16 v[108:111], v[148:151], v[198:201], v[108:111]
	v_mfma_f32_16x16x32_bf16 v[104:107], v[156:159], v[198:201], v[104:107]
	v_mfma_f32_16x16x32_bf16 v[92:95], v[148:151], v[206:209], v[92:95]
	v_mfma_f32_16x16x32_bf16 v[88:91], v[156:159], v[206:209], v[88:91]
	v_mfma_f32_16x16x32_bf16 v[76:79], v[148:151], v[214:217], v[76:79]
	v_mfma_f32_16x16x32_bf16 v[72:75], v[156:159], v[214:217], v[72:75]
	v_mfma_f32_16x16x32_bf16 v[116:119], v[160:163], v[176:179], 0
	v_mfma_f32_16x16x32_bf16 v[112:115], v[168:171], v[176:179], 0
	v_mfma_f32_16x16x32_bf16 v[100:103], v[160:163], v[194:197], 0
	v_mfma_f32_16x16x32_bf16 v[96:99], v[168:171], v[194:197], 0
	v_mfma_f32_16x16x32_bf16 v[84:87], v[160:163], v[202:205], 0
	v_mfma_f32_16x16x32_bf16 v[80:83], v[168:171], v[202:205], 0
	v_mfma_f32_16x16x32_bf16 v[68:71], v[160:163], v[210:213], 0
	v_mfma_f32_16x16x32_bf16 v[64:67], v[168:171], v[210:213], 0
	v_mfma_f32_16x16x32_bf16 v[116:119], v[164:167], v[180:183], v[116:119]
	v_mfma_f32_16x16x32_bf16 v[112:115], v[172:175], v[180:183], v[112:115]
	v_mfma_f32_16x16x32_bf16 v[100:103], v[164:167], v[198:201], v[100:103]
	v_mfma_f32_16x16x32_bf16 v[96:99], v[172:175], v[198:201], v[96:99]
	v_mfma_f32_16x16x32_bf16 v[84:87], v[164:167], v[206:209], v[84:87]
	v_mfma_f32_16x16x32_bf16 v[80:83], v[172:175], v[206:209], v[80:83]
	v_mfma_f32_16x16x32_bf16 v[68:71], v[164:167], v[214:217], v[68:71]
	v_mfma_f32_16x16x32_bf16 v[64:67], v[172:175], v[214:217], v[64:67]
	s_barrier
	s_add_i32 s44, s63, s50
	v_lshl_add_u64 v[184:185], s[48:49], 0, v[130:131]
	s_mov_b32 m0, s44
	ds_read_b128 v[176:179], v191 offset:16384
	ds_read_b128 v[180:183], v191 offset:17408
	ds_read_b128 v[194:197], v191 offset:18432
	ds_read_b128 v[198:201], v191 offset:19456
	ds_read_b128 v[202:205], v191 offset:20480
	ds_read_b128 v[206:209], v191 offset:21504
	ds_read_b128 v[210:213], v191 offset:22528
	ds_read_b128 v[214:217], v191 offset:23552
	global_load_lds_dwordx4 v[184:185], off
	s_add_i32 m0, s44, 0x2000
	s_add_u32 s44, s48, 0x40000
	v_lshl_add_u64 v[218:219], s[48:49], 0, v[134:135]
	s_addc_u32 s45, s49, 0
	s_add_i32 s70, s64, s50
	global_load_lds_dwordx4 v[218:219], off
	v_lshl_add_u64 v[220:221], s[44:45], 0, v[130:131]
	s_mov_b32 m0, s70
	v_lshl_add_u64 v[222:223], s[74:75], 0, v[132:133]
	global_load_lds_dwordx4 v[220:221], off
	v_lshl_add_u64 v[220:221], s[44:45], 0, v[134:135]
	s_add_i32 m0, s70, 0x2000
	v_lshl_add_u64 v[224:225], v[222:223], 0, s[12:13]
	global_load_lds_dwordx4 v[220:221], off
	s_mov_b32 m0, s51
	v_lshl_add_u64 v[220:221], s[74:75], 0, v[128:129]
	global_load_lds_dwordx4 v[220:221], off
	s_mov_b32 m0, s52
	s_nop 0
	global_load_lds_dwordx4 v[224:225], off
	s_waitcnt vmcnt(8) lgkmcnt(0)
	s_barrier
	v_mfma_f32_16x16x32_bf16 v[60:63], v[144:147], v[176:179], 0
	v_mfma_f32_16x16x32_bf16 v[56:59], v[152:155], v[176:179], 0
	v_mfma_f32_16x16x32_bf16 v[44:47], v[144:147], v[194:197], 0
	v_mfma_f32_16x16x32_bf16 v[40:43], v[152:155], v[194:197], 0
	v_mfma_f32_16x16x32_bf16 v[28:31], v[144:147], v[202:205], 0
	v_mfma_f32_16x16x32_bf16 v[24:27], v[152:155], v[202:205], 0
	v_mfma_f32_16x16x32_bf16 v[12:15], v[144:147], v[210:213], 0
	v_mfma_f32_16x16x32_bf16 v[8:11], v[152:155], v[210:213], 0
	v_mfma_f32_16x16x32_bf16 v[60:63], v[148:151], v[180:183], v[60:63]
	v_mfma_f32_16x16x32_bf16 v[56:59], v[156:159], v[180:183], v[56:59]
	v_mfma_f32_16x16x32_bf16 v[44:47], v[148:151], v[198:201], v[44:47]
	v_mfma_f32_16x16x32_bf16 v[40:43], v[156:159], v[198:201], v[40:43]
	v_mfma_f32_16x16x32_bf16 v[28:31], v[148:151], v[206:209], v[28:31]
	v_mfma_f32_16x16x32_bf16 v[24:27], v[156:159], v[206:209], v[24:27]
	v_mfma_f32_16x16x32_bf16 v[12:15], v[148:151], v[214:217], v[12:15]
	v_mfma_f32_16x16x32_bf16 v[8:11], v[156:159], v[214:217], v[8:11]
	v_mfma_f32_16x16x32_bf16 v[52:55], v[160:163], v[176:179], 0
	v_mfma_f32_16x16x32_bf16 v[48:51], v[168:171], v[176:179], 0
	v_mfma_f32_16x16x32_bf16 v[36:39], v[160:163], v[194:197], 0
	v_mfma_f32_16x16x32_bf16 v[32:35], v[168:171], v[194:197], 0
	v_mfma_f32_16x16x32_bf16 v[20:23], v[160:163], v[202:205], 0
	v_mfma_f32_16x16x32_bf16 v[16:19], v[168:171], v[202:205], 0
	v_mfma_f32_16x16x32_bf16 v[4:7], v[160:163], v[210:213], 0
	v_mfma_f32_16x16x32_bf16 v[0:3], v[168:171], v[210:213], 0
	v_mfma_f32_16x16x32_bf16 v[52:55], v[164:167], v[180:183], v[52:55]
	v_mfma_f32_16x16x32_bf16 v[48:51], v[172:175], v[180:183], v[48:51]
	v_mfma_f32_16x16x32_bf16 v[36:39], v[164:167], v[198:201], v[36:39]
	v_mfma_f32_16x16x32_bf16 v[32:35], v[172:175], v[198:201], v[32:35]
	v_mfma_f32_16x16x32_bf16 v[20:23], v[164:167], v[206:209], v[20:23]
	v_mfma_f32_16x16x32_bf16 v[16:19], v[172:175], v[206:209], v[16:19]
	v_mfma_f32_16x16x32_bf16 v[4:7], v[164:167], v[214:217], v[4:7]
	v_mfma_f32_16x16x32_bf16 v[0:3], v[172:175], v[214:217], v[0:3]
	s_barrier
	s_add_i32 s44, 0, 0x18000
	s_add_i32 s70, 0, 0x1c000
	v_add_u32_e32 v156, s44, v187
	v_add_u32_e32 v172, s70, v187
	ds_read_b128 v[144:147], v156
	ds_read_b128 v[148:151], v156 offset:1024
	ds_read_b128 v[152:155], v156 offset:2048
	ds_read_b128 v[156:159], v156 offset:3072
	ds_read_b128 v[160:163], v172
	ds_read_b128 v[164:167], v172 offset:1024
	ds_read_b128 v[168:171], v172 offset:2048
	ds_read_b128 v[172:175], v172 offset:3072
	s_mov_b32 m0, s53
	v_lshl_add_u64 v[224:225], v[220:221], 0, s[10:11]
	ds_read_b128 v[176:179], v191 offset:32768
	ds_read_b128 v[180:183], v191 offset:33792
	ds_read_b128 v[194:197], v191 offset:34816
	ds_read_b128 v[198:201], v191 offset:35840
	ds_read_b128 v[202:205], v191 offset:36864
	ds_read_b128 v[206:209], v191 offset:37888
	ds_read_b128 v[210:213], v191 offset:38912
	ds_read_b128 v[214:217], v191 offset:39936
	global_load_lds_dwordx4 v[224:225], off
	s_mov_b32 m0, s54
	v_lshl_add_u64 v[224:225], v[222:223], 0, s[14:15]
	global_load_lds_dwordx4 v[224:225], off
	s_waitcnt vmcnt(8) lgkmcnt(0)
	s_barrier
	v_mfma_f32_16x16x32_bf16 v[124:127], v[144:147], v[176:179], v[124:127]
	v_mfma_f32_16x16x32_bf16 v[120:123], v[152:155], v[176:179], v[120:123]
	v_mfma_f32_16x16x32_bf16 v[108:111], v[144:147], v[194:197], v[108:111]
	v_mfma_f32_16x16x32_bf16 v[104:107], v[152:155], v[194:197], v[104:107]
	v_mfma_f32_16x16x32_bf16 v[92:95], v[144:147], v[202:205], v[92:95]
	v_mfma_f32_16x16x32_bf16 v[88:91], v[152:155], v[202:205], v[88:91]
	v_mfma_f32_16x16x32_bf16 v[76:79], v[144:147], v[210:213], v[76:79]
	v_mfma_f32_16x16x32_bf16 v[72:75], v[152:155], v[210:213], v[72:75]
	v_mfma_f32_16x16x32_bf16 v[124:127], v[148:151], v[180:183], v[124:127]
	v_mfma_f32_16x16x32_bf16 v[120:123], v[156:159], v[180:183], v[120:123]
	v_mfma_f32_16x16x32_bf16 v[108:111], v[148:151], v[198:201], v[108:111]
	v_mfma_f32_16x16x32_bf16 v[104:107], v[156:159], v[198:201], v[104:107]
	v_mfma_f32_16x16x32_bf16 v[92:95], v[148:151], v[206:209], v[92:95]
	v_mfma_f32_16x16x32_bf16 v[88:91], v[156:159], v[206:209], v[88:91]
	v_mfma_f32_16x16x32_bf16 v[76:79], v[148:151], v[214:217], v[76:79]
	v_mfma_f32_16x16x32_bf16 v[72:75], v[156:159], v[214:217], v[72:75]
	v_mfma_f32_16x16x32_bf16 v[116:119], v[160:163], v[176:179], v[116:119]
	v_mfma_f32_16x16x32_bf16 v[112:115], v[168:171], v[176:179], v[112:115]
	v_mfma_f32_16x16x32_bf16 v[100:103], v[160:163], v[194:197], v[100:103]
	v_mfma_f32_16x16x32_bf16 v[96:99], v[168:171], v[194:197], v[96:99]
	v_mfma_f32_16x16x32_bf16 v[84:87], v[160:163], v[202:205], v[84:87]
	v_mfma_f32_16x16x32_bf16 v[80:83], v[168:171], v[202:205], v[80:83]
	v_mfma_f32_16x16x32_bf16 v[68:71], v[160:163], v[210:213], v[68:71]
	v_mfma_f32_16x16x32_bf16 v[64:67], v[168:171], v[210:213], v[64:67]
	v_mfma_f32_16x16x32_bf16 v[116:119], v[164:167], v[180:183], v[116:119]
	v_mfma_f32_16x16x32_bf16 v[112:115], v[172:175], v[180:183], v[112:115]
	v_mfma_f32_16x16x32_bf16 v[100:103], v[164:167], v[198:201], v[100:103]
	v_mfma_f32_16x16x32_bf16 v[96:99], v[172:175], v[198:201], v[96:99]
	v_mfma_f32_16x16x32_bf16 v[84:87], v[164:167], v[206:209], v[84:87]
	v_mfma_f32_16x16x32_bf16 v[80:83], v[172:175], v[206:209], v[80:83]
	v_mfma_f32_16x16x32_bf16 v[68:71], v[164:167], v[214:217], v[68:71]
	v_mfma_f32_16x16x32_bf16 v[64:67], v[172:175], v[214:217], v[64:67]
	s_barrier
	s_add_i32 s44, s44, s50
	v_lshl_add_u64 v[184:185], v[184:185], 0, s[24:25]
	s_mov_b32 m0, s44
	ds_read_b128 v[176:179], v191 offset:49152
	ds_read_b128 v[180:183], v191 offset:50176
	ds_read_b128 v[194:197], v191 offset:51200
	ds_read_b128 v[198:201], v191 offset:52224
	ds_read_b128 v[202:205], v191 offset:53248
	ds_read_b128 v[206:209], v191 offset:54272
	ds_read_b128 v[210:213], v191 offset:55296
	ds_read_b128 v[214:217], v191 offset:56320
	global_load_lds_dwordx4 v[184:185], off
	s_add_i32 m0, s44, 0x2000
	s_add_u32 s44, s48, 0x40080
	v_lshl_add_u64 v[184:185], v[218:219], 0, s[24:25]
	s_addc_u32 s45, s49, 0
	s_add_i32 s48, s70, s50
	global_load_lds_dwordx4 v[184:185], off
	s_mov_b32 m0, s48
	v_lshl_add_u64 v[184:185], s[44:45], 0, v[130:131]
	global_load_lds_dwordx4 v[184:185], off
	s_add_i32 m0, s48, 0x2000
	v_lshl_add_u64 v[184:185], s[44:45], 0, v[134:135]
	global_load_lds_dwordx4 v[184:185], off
	s_mov_b32 m0, s58
	v_lshl_add_u64 v[184:185], v[220:221], 0, s[24:25]
	global_load_lds_dwordx4 v[184:185], off
	s_mov_b32 m0, s59
	v_lshl_add_u64 v[184:185], v[222:223], 0, s[30:31]
	global_load_lds_dwordx4 v[184:185], off
	s_waitcnt vmcnt(8) lgkmcnt(0)
	s_barrier
	v_mfma_f32_16x16x32_bf16 v[60:63], v[144:147], v[176:179], v[60:63]
	v_mfma_f32_16x16x32_bf16 v[56:59], v[152:155], v[176:179], v[56:59]
	v_mfma_f32_16x16x32_bf16 v[44:47], v[144:147], v[194:197], v[44:47]
	v_mfma_f32_16x16x32_bf16 v[40:43], v[152:155], v[194:197], v[40:43]
	v_mfma_f32_16x16x32_bf16 v[28:31], v[144:147], v[202:205], v[28:31]
	v_mfma_f32_16x16x32_bf16 v[24:27], v[152:155], v[202:205], v[24:27]
	v_mfma_f32_16x16x32_bf16 v[12:15], v[144:147], v[210:213], v[12:15]
	v_mfma_f32_16x16x32_bf16 v[8:11], v[152:155], v[210:213], v[8:11]
	v_mfma_f32_16x16x32_bf16 v[60:63], v[148:151], v[180:183], v[60:63]
	v_mfma_f32_16x16x32_bf16 v[56:59], v[156:159], v[180:183], v[56:59]
	v_mfma_f32_16x16x32_bf16 v[44:47], v[148:151], v[198:201], v[44:47]
	v_mfma_f32_16x16x32_bf16 v[40:43], v[156:159], v[198:201], v[40:43]
	v_mfma_f32_16x16x32_bf16 v[28:31], v[148:151], v[206:209], v[28:31]
	v_mfma_f32_16x16x32_bf16 v[24:27], v[156:159], v[206:209], v[24:27]
	v_mfma_f32_16x16x32_bf16 v[12:15], v[148:151], v[214:217], v[12:15]
	v_mfma_f32_16x16x32_bf16 v[8:11], v[156:159], v[214:217], v[8:11]
	v_mfma_f32_16x16x32_bf16 v[52:55], v[160:163], v[176:179], v[52:55]
	v_mfma_f32_16x16x32_bf16 v[48:51], v[168:171], v[176:179], v[48:51]
	v_mfma_f32_16x16x32_bf16 v[36:39], v[160:163], v[194:197], v[36:39]
	v_mfma_f32_16x16x32_bf16 v[32:35], v[168:171], v[194:197], v[32:35]
	v_mfma_f32_16x16x32_bf16 v[20:23], v[160:163], v[202:205], v[20:23]
	v_mfma_f32_16x16x32_bf16 v[16:19], v[168:171], v[202:205], v[16:19]
	v_mfma_f32_16x16x32_bf16 v[4:7], v[160:163], v[210:213], v[4:7]
	v_mfma_f32_16x16x32_bf16 v[0:3], v[168:171], v[210:213], v[0:3]
	v_mfma_f32_16x16x32_bf16 v[52:55], v[164:167], v[180:183], v[52:55]
	v_mfma_f32_16x16x32_bf16 v[48:51], v[172:175], v[180:183], v[48:51]
	v_mfma_f32_16x16x32_bf16 v[36:39], v[164:167], v[198:201], v[36:39]
	v_mfma_f32_16x16x32_bf16 v[32:35], v[172:175], v[198:201], v[32:35]
	v_mfma_f32_16x16x32_bf16 v[20:23], v[164:167], v[206:209], v[20:23]
	v_mfma_f32_16x16x32_bf16 v[16:19], v[172:175], v[206:209], v[16:19]
	v_mfma_f32_16x16x32_bf16 v[4:7], v[164:167], v[214:217], v[4:7]
	v_mfma_f32_16x16x32_bf16 v[0:3], v[172:175], v[214:217], v[0:3]
	s_barrier
	s_add_i32 s72, s72, 2
	s_add_u32 s69, s69, 0x100
	s_addc_u32 s71, s71, 0
	s_cmp_gt_u32 s72, 13
	s_mov_b64 s[44:45], s[46:47]
.LBB0_751:
	ds_read_b128 v[144:147], v189
	ds_read_b128 v[148:151], v189 offset:1024
	ds_read_b128 v[152:155], v189 offset:2048
	ds_read_b128 v[156:159], v189 offset:3072
	ds_read_b128 v[160:163], v190
	ds_read_b128 v[164:167], v190 offset:1024
	ds_read_b128 v[168:171], v190 offset:2048
	ds_read_b128 v[172:175], v190 offset:3072
	s_add_u32 s46, s44, 0x100
	s_addc_u32 s47, s45, 0
	s_cmp_eq_u32 s72, 12
	s_cselect_b32 s75, s43, s47
	s_cselect_b32 s74, s67, s46
	s_cselect_b32 s49, s37, s71
	s_cselect_b32 s48, s68, s69
	v_lshl_add_u64 v[184:185], s[44:45], 0, v[136:137]
	s_add_i32 m0, s51, 0xc000
	ds_read_b128 v[176:179], v191
	ds_read_b128 v[180:183], v191 offset:1024
	ds_read_b128 v[194:197], v191 offset:2048
	ds_read_b128 v[198:201], v191 offset:3072
	ds_read_b128 v[202:205], v191 offset:4096
	ds_read_b128 v[206:209], v191 offset:5120
	ds_read_b128 v[210:213], v191 offset:6144
	ds_read_b128 v[214:217], v191 offset:7168
	global_load_lds_dwordx4 v[184:185], off
	s_add_i32 m0, s51, 0xe000
	v_lshl_add_u64 v[184:185], s[44:45], 0, v[138:139]
	global_load_lds_dwordx4 v[184:185], off
	s_waitcnt vmcnt(8) lgkmcnt(0)
	s_barrier
	v_mfma_f32_16x16x32_bf16 v[124:127], v[144:147], v[176:179], v[124:127]
	v_mfma_f32_16x16x32_bf16 v[120:123], v[152:155], v[176:179], v[120:123]
	v_mfma_f32_16x16x32_bf16 v[108:111], v[144:147], v[194:197], v[108:111]
	v_mfma_f32_16x16x32_bf16 v[104:107], v[152:155], v[194:197], v[104:107]
	v_mfma_f32_16x16x32_bf16 v[92:95], v[144:147], v[202:205], v[92:95]
	v_mfma_f32_16x16x32_bf16 v[88:91], v[152:155], v[202:205], v[88:91]
	v_mfma_f32_16x16x32_bf16 v[76:79], v[144:147], v[210:213], v[76:79]
	v_mfma_f32_16x16x32_bf16 v[72:75], v[152:155], v[210:213], v[72:75]
	v_mfma_f32_16x16x32_bf16 v[124:127], v[148:151], v[180:183], v[124:127]
	v_mfma_f32_16x16x32_bf16 v[120:123], v[156:159], v[180:183], v[120:123]
	v_mfma_f32_16x16x32_bf16 v[108:111], v[148:151], v[198:201], v[108:111]
	v_mfma_f32_16x16x32_bf16 v[104:107], v[156:159], v[198:201], v[104:107]
	v_mfma_f32_16x16x32_bf16 v[92:95], v[148:151], v[206:209], v[92:95]
	v_mfma_f32_16x16x32_bf16 v[88:91], v[156:159], v[206:209], v[88:91]
	v_mfma_f32_16x16x32_bf16 v[76:79], v[148:151], v[214:217], v[76:79]
	v_mfma_f32_16x16x32_bf16 v[72:75], v[156:159], v[214:217], v[72:75]
	v_mfma_f32_16x16x32_bf16 v[116:119], v[160:163], v[176:179], v[116:119]
	v_mfma_f32_16x16x32_bf16 v[112:115], v[168:171], v[176:179], v[112:115]
	v_mfma_f32_16x16x32_bf16 v[100:103], v[160:163], v[194:197], v[100:103]
	v_mfma_f32_16x16x32_bf16 v[96:99], v[168:171], v[194:197], v[96:99]
	v_mfma_f32_16x16x32_bf16 v[84:87], v[160:163], v[202:205], v[84:87]
	v_mfma_f32_16x16x32_bf16 v[80:83], v[168:171], v[202:205], v[80:83]
	v_mfma_f32_16x16x32_bf16 v[68:71], v[160:163], v[210:213], v[68:71]
	v_mfma_f32_16x16x32_bf16 v[64:67], v[168:171], v[210:213], v[64:67]
	v_mfma_f32_16x16x32_bf16 v[116:119], v[164:167], v[180:183], v[116:119]
	v_mfma_f32_16x16x32_bf16 v[112:115], v[172:175], v[180:183], v[112:115]
	v_mfma_f32_16x16x32_bf16 v[100:103], v[164:167], v[198:201], v[100:103]
	v_mfma_f32_16x16x32_bf16 v[96:99], v[172:175], v[198:201], v[96:99]
	v_mfma_f32_16x16x32_bf16 v[84:87], v[164:167], v[206:209], v[84:87]
	v_mfma_f32_16x16x32_bf16 v[80:83], v[172:175], v[206:209], v[80:83]
	v_mfma_f32_16x16x32_bf16 v[68:71], v[164:167], v[214:217], v[68:71]
	v_mfma_f32_16x16x32_bf16 v[64:67], v[172:175], v[214:217], v[64:67]
	s_barrier
	s_add_i32 s44, s63, s50
	v_lshl_add_u64 v[184:185], s[48:49], 0, v[130:131]
	s_mov_b32 m0, s44
	ds_read_b128 v[176:179], v191 offset:16384
	ds_read_b128 v[180:183], v191 offset:17408
	ds_read_b128 v[194:197], v191 offset:18432
	ds_read_b128 v[198:201], v191 offset:19456
	ds_read_b128 v[202:205], v191 offset:20480
	ds_read_b128 v[206:209], v191 offset:21504
	ds_read_b128 v[210:213], v191 offset:22528
	ds_read_b128 v[214:217], v191 offset:23552
	global_load_lds_dwordx4 v[184:185], off
	s_add_i32 m0, s44, 0x2000
	s_add_u32 s44, s48, 0x40000
	v_lshl_add_u64 v[218:219], s[48:49], 0, v[134:135]
	s_addc_u32 s45, s49, 0
	s_add_i32 s70, s64, s50
	global_load_lds_dwordx4 v[218:219], off
	v_lshl_add_u64 v[220:221], s[44:45], 0, v[130:131]
	s_mov_b32 m0, s70
	v_lshl_add_u64 v[222:223], s[74:75], 0, v[132:133]
	global_load_lds_dwordx4 v[220:221], off
	v_lshl_add_u64 v[220:221], s[44:45], 0, v[134:135]
	s_add_i32 m0, s70, 0x2000
	v_lshl_add_u64 v[224:225], v[222:223], 0, s[12:13]
	global_load_lds_dwordx4 v[220:221], off
	s_mov_b32 m0, s51
	v_lshl_add_u64 v[220:221], s[74:75], 0, v[128:129]
	global_load_lds_dwordx4 v[220:221], off
	s_mov_b32 m0, s52
	s_nop 0
	global_load_lds_dwordx4 v[224:225], off
	s_waitcnt vmcnt(8) lgkmcnt(0)
	s_barrier
	v_mfma_f32_16x16x32_bf16 v[60:63], v[144:147], v[176:179], v[60:63]
	v_mfma_f32_16x16x32_bf16 v[56:59], v[152:155], v[176:179], v[56:59]
	v_mfma_f32_16x16x32_bf16 v[44:47], v[144:147], v[194:197], v[44:47]
	v_mfma_f32_16x16x32_bf16 v[40:43], v[152:155], v[194:197], v[40:43]
	v_mfma_f32_16x16x32_bf16 v[28:31], v[144:147], v[202:205], v[28:31]
	v_mfma_f32_16x16x32_bf16 v[24:27], v[152:155], v[202:205], v[24:27]
	v_mfma_f32_16x16x32_bf16 v[12:15], v[144:147], v[210:213], v[12:15]
	v_mfma_f32_16x16x32_bf16 v[8:11], v[152:155], v[210:213], v[8:11]
	v_mfma_f32_16x16x32_bf16 v[60:63], v[148:151], v[180:183], v[60:63]
	v_mfma_f32_16x16x32_bf16 v[56:59], v[156:159], v[180:183], v[56:59]
	v_mfma_f32_16x16x32_bf16 v[44:47], v[148:151], v[198:201], v[44:47]
	v_mfma_f32_16x16x32_bf16 v[40:43], v[156:159], v[198:201], v[40:43]
	v_mfma_f32_16x16x32_bf16 v[28:31], v[148:151], v[206:209], v[28:31]
	v_mfma_f32_16x16x32_bf16 v[24:27], v[156:159], v[206:209], v[24:27]
	v_mfma_f32_16x16x32_bf16 v[12:15], v[148:151], v[214:217], v[12:15]
	v_mfma_f32_16x16x32_bf16 v[8:11], v[156:159], v[214:217], v[8:11]
	v_mfma_f32_16x16x32_bf16 v[52:55], v[160:163], v[176:179], v[52:55]
	v_mfma_f32_16x16x32_bf16 v[48:51], v[168:171], v[176:179], v[48:51]
	v_mfma_f32_16x16x32_bf16 v[36:39], v[160:163], v[194:197], v[36:39]
	v_mfma_f32_16x16x32_bf16 v[32:35], v[168:171], v[194:197], v[32:35]
	v_mfma_f32_16x16x32_bf16 v[20:23], v[160:163], v[202:205], v[20:23]
	v_mfma_f32_16x16x32_bf16 v[16:19], v[168:171], v[202:205], v[16:19]
	v_mfma_f32_16x16x32_bf16 v[4:7], v[160:163], v[210:213], v[4:7]
	v_mfma_f32_16x16x32_bf16 v[0:3], v[168:171], v[210:213], v[0:3]
	v_mfma_f32_16x16x32_bf16 v[52:55], v[164:167], v[180:183], v[52:55]
	v_mfma_f32_16x16x32_bf16 v[48:51], v[172:175], v[180:183], v[48:51]
	v_mfma_f32_16x16x32_bf16 v[36:39], v[164:167], v[198:201], v[36:39]
	v_mfma_f32_16x16x32_bf16 v[32:35], v[172:175], v[198:201], v[32:35]
	v_mfma_f32_16x16x32_bf16 v[20:23], v[164:167], v[206:209], v[20:23]
	v_mfma_f32_16x16x32_bf16 v[16:19], v[172:175], v[206:209], v[16:19]
	v_mfma_f32_16x16x32_bf16 v[4:7], v[164:167], v[214:217], v[4:7]
	v_mfma_f32_16x16x32_bf16 v[0:3], v[172:175], v[214:217], v[0:3]
	s_barrier
	s_add_i32 s44, 0, 0x18000
	s_add_i32 s70, 0, 0x1c000
	v_add_u32_e32 v156, s44, v187
	v_add_u32_e32 v172, s70, v187
	ds_read_b128 v[144:147], v156
	ds_read_b128 v[148:151], v156 offset:1024
	ds_read_b128 v[152:155], v156 offset:2048
	ds_read_b128 v[156:159], v156 offset:3072
	ds_read_b128 v[160:163], v172
	ds_read_b128 v[164:167], v172 offset:1024
	ds_read_b128 v[168:171], v172 offset:2048
	ds_read_b128 v[172:175], v172 offset:3072
	s_mov_b32 m0, s53
	v_lshl_add_u64 v[224:225], v[220:221], 0, s[10:11]
	ds_read_b128 v[176:179], v191 offset:32768
	ds_read_b128 v[180:183], v191 offset:33792
	ds_read_b128 v[194:197], v191 offset:34816
	ds_read_b128 v[198:201], v191 offset:35840
	ds_read_b128 v[202:205], v191 offset:36864
	ds_read_b128 v[206:209], v191 offset:37888
	ds_read_b128 v[210:213], v191 offset:38912
	ds_read_b128 v[214:217], v191 offset:39936
	global_load_lds_dwordx4 v[224:225], off
	s_mov_b32 m0, s54
	v_lshl_add_u64 v[224:225], v[222:223], 0, s[14:15]
	global_load_lds_dwordx4 v[224:225], off
	s_waitcnt vmcnt(8) lgkmcnt(0)
	s_barrier
	v_mfma_f32_16x16x32_bf16 v[124:127], v[144:147], v[176:179], v[124:127]
	v_mfma_f32_16x16x32_bf16 v[120:123], v[152:155], v[176:179], v[120:123]
	v_mfma_f32_16x16x32_bf16 v[108:111], v[144:147], v[194:197], v[108:111]
	v_mfma_f32_16x16x32_bf16 v[104:107], v[152:155], v[194:197], v[104:107]
	v_mfma_f32_16x16x32_bf16 v[92:95], v[144:147], v[202:205], v[92:95]
	v_mfma_f32_16x16x32_bf16 v[88:91], v[152:155], v[202:205], v[88:91]
	v_mfma_f32_16x16x32_bf16 v[76:79], v[144:147], v[210:213], v[76:79]
	v_mfma_f32_16x16x32_bf16 v[72:75], v[152:155], v[210:213], v[72:75]
	v_mfma_f32_16x16x32_bf16 v[124:127], v[148:151], v[180:183], v[124:127]
	v_mfma_f32_16x16x32_bf16 v[120:123], v[156:159], v[180:183], v[120:123]
	v_mfma_f32_16x16x32_bf16 v[108:111], v[148:151], v[198:201], v[108:111]
	v_mfma_f32_16x16x32_bf16 v[104:107], v[156:159], v[198:201], v[104:107]
	v_mfma_f32_16x16x32_bf16 v[92:95], v[148:151], v[206:209], v[92:95]
	v_mfma_f32_16x16x32_bf16 v[88:91], v[156:159], v[206:209], v[88:91]
	v_mfma_f32_16x16x32_bf16 v[76:79], v[148:151], v[214:217], v[76:79]
	v_mfma_f32_16x16x32_bf16 v[72:75], v[156:159], v[214:217], v[72:75]
	v_mfma_f32_16x16x32_bf16 v[116:119], v[160:163], v[176:179], v[116:119]
	v_mfma_f32_16x16x32_bf16 v[112:115], v[168:171], v[176:179], v[112:115]
	v_mfma_f32_16x16x32_bf16 v[100:103], v[160:163], v[194:197], v[100:103]
	v_mfma_f32_16x16x32_bf16 v[96:99], v[168:171], v[194:197], v[96:99]
	v_mfma_f32_16x16x32_bf16 v[84:87], v[160:163], v[202:205], v[84:87]
	v_mfma_f32_16x16x32_bf16 v[80:83], v[168:171], v[202:205], v[80:83]
	v_mfma_f32_16x16x32_bf16 v[68:71], v[160:163], v[210:213], v[68:71]
	v_mfma_f32_16x16x32_bf16 v[64:67], v[168:171], v[210:213], v[64:67]
	v_mfma_f32_16x16x32_bf16 v[116:119], v[164:167], v[180:183], v[116:119]
	v_mfma_f32_16x16x32_bf16 v[112:115], v[172:175], v[180:183], v[112:115]
	v_mfma_f32_16x16x32_bf16 v[100:103], v[164:167], v[198:201], v[100:103]
	v_mfma_f32_16x16x32_bf16 v[96:99], v[172:175], v[198:201], v[96:99]
	v_mfma_f32_16x16x32_bf16 v[84:87], v[164:167], v[206:209], v[84:87]
	v_mfma_f32_16x16x32_bf16 v[80:83], v[172:175], v[206:209], v[80:83]
	v_mfma_f32_16x16x32_bf16 v[68:71], v[164:167], v[214:217], v[68:71]
	v_mfma_f32_16x16x32_bf16 v[64:67], v[172:175], v[214:217], v[64:67]
	s_barrier
	s_add_i32 s44, s44, s50
	v_lshl_add_u64 v[184:185], v[184:185], 0, s[24:25]
	s_mov_b32 m0, s44
	ds_read_b128 v[176:179], v191 offset:49152
	ds_read_b128 v[180:183], v191 offset:50176
	ds_read_b128 v[194:197], v191 offset:51200
	ds_read_b128 v[198:201], v191 offset:52224
	ds_read_b128 v[202:205], v191 offset:53248
	ds_read_b128 v[206:209], v191 offset:54272
	ds_read_b128 v[210:213], v191 offset:55296
	ds_read_b128 v[214:217], v191 offset:56320
	global_load_lds_dwordx4 v[184:185], off
	s_add_i32 m0, s44, 0x2000
	s_add_u32 s44, s48, 0x40080
	v_lshl_add_u64 v[184:185], v[218:219], 0, s[24:25]
	s_addc_u32 s45, s49, 0
	s_add_i32 s48, s70, s50
	global_load_lds_dwordx4 v[184:185], off
	s_mov_b32 m0, s48
	v_lshl_add_u64 v[184:185], s[44:45], 0, v[130:131]
	global_load_lds_dwordx4 v[184:185], off
	s_add_i32 m0, s48, 0x2000
	v_lshl_add_u64 v[184:185], s[44:45], 0, v[134:135]
	global_load_lds_dwordx4 v[184:185], off
	s_mov_b32 m0, s58
	v_lshl_add_u64 v[184:185], v[220:221], 0, s[24:25]
	global_load_lds_dwordx4 v[184:185], off
	s_mov_b32 m0, s59
	v_lshl_add_u64 v[184:185], v[222:223], 0, s[30:31]
	global_load_lds_dwordx4 v[184:185], off
	s_waitcnt vmcnt(8) lgkmcnt(0)
	s_barrier
	v_mfma_f32_16x16x32_bf16 v[60:63], v[144:147], v[176:179], v[60:63]
	v_mfma_f32_16x16x32_bf16 v[56:59], v[152:155], v[176:179], v[56:59]
	v_mfma_f32_16x16x32_bf16 v[44:47], v[144:147], v[194:197], v[44:47]
	v_mfma_f32_16x16x32_bf16 v[40:43], v[152:155], v[194:197], v[40:43]
	v_mfma_f32_16x16x32_bf16 v[28:31], v[144:147], v[202:205], v[28:31]
	v_mfma_f32_16x16x32_bf16 v[24:27], v[152:155], v[202:205], v[24:27]
	v_mfma_f32_16x16x32_bf16 v[12:15], v[144:147], v[210:213], v[12:15]
	v_mfma_f32_16x16x32_bf16 v[8:11], v[152:155], v[210:213], v[8:11]
	v_mfma_f32_16x16x32_bf16 v[60:63], v[148:151], v[180:183], v[60:63]
	v_mfma_f32_16x16x32_bf16 v[56:59], v[156:159], v[180:183], v[56:59]
	v_mfma_f32_16x16x32_bf16 v[44:47], v[148:151], v[198:201], v[44:47]
	v_mfma_f32_16x16x32_bf16 v[40:43], v[156:159], v[198:201], v[40:43]
	v_mfma_f32_16x16x32_bf16 v[28:31], v[148:151], v[206:209], v[28:31]
	v_mfma_f32_16x16x32_bf16 v[24:27], v[156:159], v[206:209], v[24:27]
	v_mfma_f32_16x16x32_bf16 v[12:15], v[148:151], v[214:217], v[12:15]
	v_mfma_f32_16x16x32_bf16 v[8:11], v[156:159], v[214:217], v[8:11]
	v_mfma_f32_16x16x32_bf16 v[52:55], v[160:163], v[176:179], v[52:55]
	v_mfma_f32_16x16x32_bf16 v[48:51], v[168:171], v[176:179], v[48:51]
	v_mfma_f32_16x16x32_bf16 v[36:39], v[160:163], v[194:197], v[36:39]
	v_mfma_f32_16x16x32_bf16 v[32:35], v[168:171], v[194:197], v[32:35]
	v_mfma_f32_16x16x32_bf16 v[20:23], v[160:163], v[202:205], v[20:23]
	v_mfma_f32_16x16x32_bf16 v[16:19], v[168:171], v[202:205], v[16:19]
	v_mfma_f32_16x16x32_bf16 v[4:7], v[160:163], v[210:213], v[4:7]
	v_mfma_f32_16x16x32_bf16 v[0:3], v[168:171], v[210:213], v[0:3]
	v_mfma_f32_16x16x32_bf16 v[52:55], v[164:167], v[180:183], v[52:55]
	v_mfma_f32_16x16x32_bf16 v[48:51], v[172:175], v[180:183], v[48:51]
	v_mfma_f32_16x16x32_bf16 v[36:39], v[164:167], v[198:201], v[36:39]
	v_mfma_f32_16x16x32_bf16 v[32:35], v[172:175], v[198:201], v[32:35]
	v_mfma_f32_16x16x32_bf16 v[20:23], v[164:167], v[206:209], v[20:23]
	v_mfma_f32_16x16x32_bf16 v[16:19], v[172:175], v[206:209], v[16:19]
	v_mfma_f32_16x16x32_bf16 v[4:7], v[164:167], v[214:217], v[4:7]
	v_mfma_f32_16x16x32_bf16 v[0:3], v[172:175], v[214:217], v[0:3]
	s_barrier
	s_add_i32 s72, s72, 2
	s_add_u32 s69, s69, 0x100
	s_addc_u32 s71, s71, 0
	s_cmp_gt_u32 s72, 13
	s_mov_b64 s[44:45], s[46:47]
	s_cbranch_scc0 .LBB0_751
	s_and_b64 vcc, exec, s[34:35]
	s_cbranch_vccz .LBB0_754
	s_barrier
